# snake with preference for sharing the B fragment (SrcA) between chains
# baseline (speedup 1.0000x reference)
; #define PG8_STAGE(bufoff, gbase, voff) do { if constexpr (ABL & 1) break; glds16s<(bufoff)>((voff)[0], (const void*)(gbase), ldsbw); glds16s<(bufoff) + 8192>((voff)[1], (const void*)(gbase), ldsbw); } while (0)
; #define PG8_LDA(dst, b, h) do { if constexpr (ABL & 4) break; _Pragma("unroll") for (int m = 0; m < 4; ++m) _Pragma("unroll") for (int k = 0; k < 2; ++k) dst[m][k] = *(const LAS f16x8*)(lds + PG8_SA(b, h) + aoff + m * 2048 + k * 1024); } while (0)
; #define PG8_LDB(dst, b, h) do { if constexpr (ABL & 4) break; _Pragma("unroll") for (int n = 0; n < 2; ++n) _Pragma("unroll") for (int k = 0; k < 2; ++k) dst[n][k] = *(const LAS f16x8*)(lds + PG8_SB(b, h) + boff + n * 2048 + k * 1024); } while (0)
; #define PG8_MMAF(ai, bj, At, Bt) do { if (t == 0) PG8_MMA0(ai, bj, At, Bt); else PG8_MMA(ai, bj, At, Bt); } while (0)
; #define PG8_WAIT_V(n) asm volatile("s_waitcnt vmcnt(" #n ")" ::: "memory")
; #define PG8_WAIT_L(n) asm volatile("s_waitcnt lgkmcnt(" #n ")" ::: "memory")
; #define PG8_BAR __builtin_amdgcn_s_barrier()
; #define PG8_SCHED __builtin_amdgcn_sched_barrier(0)
;     ...
;             PG8_LDB(B0, 0, 0); PG8_LDB(B1, 0, 1); PG8_SCHED; PG8_LDA(At, 0, 0); PG8_STAGE(PG8_SA(1, 1), a1 + hstep, voffA);
;             PG8_WAIT_V(8); PG8_WAIT_L(0); PG8_BAR; PG8_MMAF(0, 0, At, B0); PG8_MMAF(0, 1, At, B1); PG8_BAR; PG8_SCHED;
;             const bool fin = last && !has_next;
;             PG8_LDA(At, 0, 1); if (!fin) { PG8_STAGE(PG8_SB(0, 0), b2, voffB); PG8_STAGE(PG8_SB(0, 1), b2 + hstep, voffB); PG8_STAGE(PG8_SA(0, 0), a2, voffA); }
;             if (!fin) PG8_WAIT_V(8); else PG8_WAIT_V(2); PG8_WAIT_L(0); PG8_BAR; PG8_MMAF(1, 0, At, B0); PG8_MMAF(1, 1, At, B1); PG8_BAR; PG8_SCHED;
.LBB0_229:
	s_ashr_i32 s53, s52, 31
	s_lshl_b64 s[8:9], s[52:53], 19
	s_add_u32 s54, s74, s8
	s_addc_u32 s55, s75, s9
	s_and_b64 s[8:9], exec, s[4:5]
	ds_read_b128 v[2:5], v236
	ds_read_b128 v[6:9], v236 offset:1024
	ds_read_b128 v[10:13], v236 offset:2048
	ds_read_b128 v[14:17], v236 offset:3072
	ds_read_b128 v[18:21], v237
	ds_read_b128 v[22:25], v237 offset:1024
	ds_read_b128 v[26:29], v237 offset:2048
	ds_read_b128 v[30:33], v237 offset:3072
	s_cselect_b32 s11, s63, s55
	s_cselect_b32 s35, s62, s54
	s_ashr_i32 s1, s0, 31
	s_lshl_b64 s[8:9], s[0:1], 19
	s_add_u32 s56, s90, s8
	s_addc_u32 s57, s91, s9
	s_and_b64 s[8:9], exec, s[4:5]
	s_cselect_b32 s1, s7, s57
	s_cselect_b32 s46, s6, s56
	s_add_u32 s8, s62, 0x100
	s_addc_u32 s9, s63, 0
	s_add_u32 s64, s6, 0x100
	s_addc_u32 s65, s7, 0
	s_add_u32 s24, s62, 0x180
	s_addc_u32 s25, s63, 0
	ds_read_b128 v[34:37], v238
	ds_read_b128 v[38:41], v238 offset:1024
	ds_read_b128 v[42:45], v238 offset:2048
	ds_read_b128 v[46:49], v238 offset:3072
	ds_read_b128 v[50:53], v238 offset:4096
	ds_read_b128 v[54:57], v238 offset:5120
	ds_read_b128 v[58:61], v238 offset:6144
	ds_read_b128 v[62:65], v238 offset:7168
	s_add_u32 s26, s6, 0x180
	s_addc_u32 s27, s7, 0
	s_add_u32 s76, s62, 0x40080
	s_addc_u32 s77, s63, 0
	s_add_u32 m0, s28, 0xc000
	s_nop 0
	global_load_lds_dwordx4 v232, s[76:77]
	s_nop 0
	s_add_u32 m0, s28, 0xe000
	s_nop 0
	global_load_lds_dwordx4 v234, s[76:77]
	s_waitcnt vmcnt(8)
	s_waitcnt lgkmcnt(0)
	s_barrier
	v_mfma_f32_16x16x32_f16 v[86:89], v[10:13], v[50:53], 0
	s_setprio 1
	v_mfma_f32_16x16x32_f16 v[90:93], v[14:17], v[54:57], v[86:89]
	v_mfma_f32_16x16x32_f16 v[86:89], v[2:5], v[58:61], 0
	v_mfma_f32_16x16x32_f16 v[94:97], v[6:9], v[62:65], v[86:89]
	v_mfma_f32_16x16x32_f16 v[66:69], v[2:5], v[34:37], 0
	v_mfma_f32_16x16x32_f16 v[66:69], v[6:9], v[38:41], v[66:69]
	v_mfma_f32_16x16x32_f16 v[70:73], v[10:13], v[34:37], 0
	v_mfma_f32_16x16x32_f16 v[70:73], v[14:17], v[38:41], v[70:73]
	v_mfma_f32_16x16x32_f16 v[74:77], v[2:5], v[42:45], 0
	v_mfma_f32_16x16x32_f16 v[74:77], v[6:9], v[46:49], v[74:77]
	v_mfma_f32_16x16x32_f16 v[78:81], v[10:13], v[42:45], 0
	v_mfma_f32_16x16x32_f16 v[78:81], v[14:17], v[46:49], v[78:81]
	v_mfma_f32_16x16x32_f16 v[82:85], v[2:5], v[50:53], 0
	v_mfma_f32_16x16x32_f16 v[82:85], v[6:9], v[54:57], v[82:85]
	v_mfma_f32_16x16x32_f16 v[86:89], v[10:13], v[58:61], 0
	v_mfma_f32_16x16x32_f16 v[106:109], v[14:17], v[62:65], v[86:89]
	v_mfma_f32_16x16x32_f16 v[86:89], v[18:21], v[34:37], 0
	v_mfma_f32_16x16x32_f16 v[34:37], v[26:29], v[34:37], 0
	v_mfma_f32_16x16x32_f16 v[110:113], v[22:25], v[38:41], v[86:89]
	v_mfma_f32_16x16x32_f16 v[34:37], v[30:33], v[38:41], v[34:37]
	v_mfma_f32_16x16x32_f16 v[38:41], v[18:21], v[42:45], 0
	v_mfma_f32_16x16x32_f16 v[42:45], v[26:29], v[42:45], 0
	v_mfma_f32_16x16x32_f16 v[38:41], v[22:25], v[46:49], v[38:41]
	v_mfma_f32_16x16x32_f16 v[42:45], v[30:33], v[46:49], v[42:45]
	v_mfma_f32_16x16x32_f16 v[46:49], v[18:21], v[50:53], 0
	v_mfma_f32_16x16x32_f16 v[50:53], v[26:29], v[50:53], 0
	v_mfma_f32_16x16x32_f16 v[46:49], v[22:25], v[54:57], v[46:49]
	v_mfma_f32_16x16x32_f16 v[54:57], v[30:33], v[54:57], v[50:53]
	v_mfma_f32_16x16x32_f16 v[50:53], v[18:21], v[58:61], 0
	v_mfma_f32_16x16x32_f16 v[130:133], v[22:25], v[62:65], v[50:53]
	v_mfma_f32_16x16x32_f16 v[50:53], v[26:29], v[58:61], 0
	v_mfma_f32_16x16x32_f16 v[62:65], v[30:33], v[62:65], v[50:53]
	s_barrier
	s_setprio 0
	s_nop 4
	ds_read_b128 v[50:53], v238 offset:16384
	ds_read_b128 v[58:61], v238 offset:17408
	ds_read_b128 v[86:89], v238 offset:18432
	ds_read_b128 v[98:101], v238 offset:19456
	ds_read_b128 v[102:105], v238 offset:20480
	ds_read_b128 v[114:117], v238 offset:21504
	ds_read_b128 v[118:121], v238 offset:22528
	ds_read_b128 v[122:125], v238 offset:23552
	s_add_u32 m0, s28, 0x10000
	s_nop 0
	global_load_lds_dwordx4 v233, s[64:65]
	s_nop 0
	s_add_u32 m0, s28, 0x12000
	s_nop 0
	global_load_lds_dwordx4 v235, s[64:65]
	s_add_u32 s64, s6, 0x40100
	s_addc_u32 s65, s7, 0
	s_add_u32 m0, s28, 0x14000
	s_nop 0
	global_load_lds_dwordx4 v233, s[64:65]
	s_nop 0
	s_add_u32 m0, s28, 0x16000
	s_nop 0
	global_load_lds_dwordx4 v235, s[64:65]
	s_nop 0
	s_add_u32 m0, s28, 0
	s_nop 0
	global_load_lds_dwordx4 v232, s[8:9]
	s_nop 0
	s_add_u32 m0, s28, 0x2000
	s_nop 0
	global_load_lds_dwordx4 v234, s[8:9]
	s_waitcnt vmcnt(8)
	s_waitcnt lgkmcnt(0)
	s_barrier
	v_mfma_f32_16x16x32_f16 v[126:129], v[2:5], v[50:53], 0
	s_setprio 1
	v_mfma_f32_16x16x32_f16 v[134:137], v[6:9], v[58:61], v[126:129]
	v_mfma_f32_16x16x32_f16 v[126:129], v[10:13], v[50:53], 0
	v_mfma_f32_16x16x32_f16 v[138:141], v[14:17], v[58:61], v[126:129]
	v_mfma_f32_16x16x32_f16 v[126:129], v[2:5], v[86:89], 0
	v_mfma_f32_16x16x32_f16 v[142:145], v[6:9], v[98:101], v[126:129]
	v_mfma_f32_16x16x32_f16 v[126:129], v[10:13], v[86:89], 0
	v_mfma_f32_16x16x32_f16 v[146:149], v[14:17], v[98:101], v[126:129]
	v_mfma_f32_16x16x32_f16 v[126:129], v[2:5], v[102:105], 0
	v_mfma_f32_16x16x32_f16 v[150:153], v[6:9], v[114:117], v[126:129]
	v_mfma_f32_16x16x32_f16 v[2:5], v[2:5], v[118:121], 0
	v_mfma_f32_16x16x32_f16 v[2:5], v[6:9], v[122:125], v[2:5]
	v_mfma_f32_16x16x32_f16 v[6:9], v[10:13], v[118:121], 0
	v_mfma_f32_16x16x32_f16 v[126:129], v[10:13], v[102:105], 0
	v_mfma_f32_16x16x32_f16 v[154:157], v[14:17], v[114:117], v[126:129]
	v_mfma_f32_16x16x32_f16 v[10:13], v[14:17], v[122:125], v[6:9]
	v_mfma_f32_16x16x32_f16 v[6:9], v[18:21], v[50:53], 0
	v_mfma_f32_16x16x32_f16 v[158:161], v[22:25], v[58:61], v[6:9]
	v_mfma_f32_16x16x32_f16 v[6:9], v[26:29], v[50:53], 0
	v_mfma_f32_16x16x32_f16 v[162:165], v[30:33], v[58:61], v[6:9]
	v_mfma_f32_16x16x32_f16 v[6:9], v[18:21], v[86:89], 0
	v_mfma_f32_16x16x32_f16 v[166:169], v[22:25], v[98:101], v[6:9]
	v_mfma_f32_16x16x32_f16 v[6:9], v[26:29], v[86:89], 0
	v_mfma_f32_16x16x32_f16 v[170:173], v[30:33], v[98:101], v[6:9]
	v_mfma_f32_16x16x32_f16 v[6:9], v[18:21], v[102:105], 0
	v_mfma_f32_16x16x32_f16 v[174:177], v[22:25], v[114:117], v[6:9]
	v_mfma_f32_16x16x32_f16 v[6:9], v[26:29], v[102:105], 0
	v_mfma_f32_16x16x32_f16 v[178:181], v[30:33], v[114:117], v[6:9]
	v_mfma_f32_16x16x32_f16 v[6:9], v[18:21], v[118:121], 0
	v_mfma_f32_16x16x32_f16 v[22:25], v[22:25], v[122:125], v[6:9]
	v_mfma_f32_16x16x32_f16 v[6:9], v[26:29], v[118:121], 0
	v_mfma_f32_16x16x32_f16 v[182:185], v[30:33], v[122:125], v[6:9]
	s_barrier
; #define PG8_STAGE(bufoff, gbase, voff) do { if constexpr (ABL & 1) break; glds16s<(bufoff)>((voff)[0], (const void*)(gbase), ldsbw); glds16s<(bufoff) + 8192>((voff)[1], (const void*)(gbase), ldsbw); } while (0)
; #define PG8_LDA(dst, b, h) do { if constexpr (ABL & 4) break; _Pragma("unroll") for (int m = 0; m < 4; ++m) _Pragma("unroll") for (int k = 0; k < 2; ++k) dst[m][k] = *(const LAS f16x8*)(lds + PG8_SA(b, h) + aoff + m * 2048 + k * 1024); } while (0)
; #define PG8_LDB(dst, b, h) do { if constexpr (ABL & 4) break; _Pragma("unroll") for (int n = 0; n < 2; ++n) _Pragma("unroll") for (int k = 0; k < 2; ++k) dst[n][k] = *(const LAS f16x8*)(lds + PG8_SB(b, h) + boff + n * 2048 + k * 1024); } while (0)
; #define PG8_MMA(ai, bj, At, Bt) do { if constexpr (ABL & 2) break; __builtin_amdgcn_s_setprio(1); _Pragma("unroll") for (int m = 0; m < 4; ++m) _Pragma("unroll") for (int n = 0; n < 2; ++n) _Pragma("unroll") for (int k = 0; k < 2; ++k) \
;         acc[ai][bj][m][n] = __builtin_amdgcn_mfma_f32_16x16x32_f16(Bt[n][k], At[m][k], acc[ai][bj][m][n], 0, 0, 0); __builtin_amdgcn_s_setprio(0); } while (0)
; #define PG8_WAIT_V(n) asm volatile("s_waitcnt vmcnt(" #n ")" ::: "memory")
; #define PG8_WAIT_L(n) asm volatile("s_waitcnt lgkmcnt(" #n ")" ::: "memory")
; #define PG8_BAR __builtin_amdgcn_s_barrier()
; #define PG8_SCHED __builtin_amdgcn_sched_barrier(0)
;     ...
;             PG8_LDB(B0, 1, 0); PG8_LDB(B1, 1, 1); PG8_SCHED; PG8_LDA(At, 1, 0); if (!fin) PG8_STAGE(PG8_SA(0, 1), a2 + hstep, voffA);
;             if (!fin) PG8_WAIT_V(8); else PG8_WAIT_V(0); PG8_WAIT_L(0); PG8_BAR; PG8_MMA(0, 0, At, B0); PG8_MMA(0, 1, At, B1); PG8_BAR; PG8_SCHED;
;             PG8_LDA(At, 1, 1); if (!fin) { PG8_STAGE(PG8_SB(1, 0), b3, voffB); PG8_STAGE(PG8_SB(1, 1), b3 + hstep, voffB); PG8_STAGE(PG8_SA(1, 0), a3, voffA); }
;             if (!fin) PG8_WAIT_V(8); PG8_WAIT_L(0); PG8_BAR; PG8_MMA(1, 0, At, B0); PG8_MMA(1, 1, At, B1); PG8_BAR; PG8_SCHED;
	s_setprio 0
	s_nop 4
	ds_read_b128 v[6:9], v239
	ds_read_b128 v[26:29], v239 offset:1024
	ds_read_b128 v[186:189], v239 offset:2048
	ds_read_b128 v[190:193], v239 offset:3072
	ds_read_b128 v[206:209], v240
	ds_read_b128 v[210:213], v240 offset:1024
	ds_read_b128 v[214:217], v240 offset:2048
	ds_read_b128 v[218:221], v240 offset:3072
	ds_read_b128 v[14:17], v238 offset:32768
	ds_read_b128 v[18:21], v238 offset:33792
	ds_read_b128 v[30:33], v238 offset:34816
	ds_read_b128 v[222:225], v238 offset:35840
	ds_read_b128 v[226:229], v238 offset:36864
	ds_read_b128 v[242:245], v238 offset:37888
	ds_read_b128 v[246:249], v238 offset:38912
	ds_read_b128 v[250:253], v238 offset:39936
	s_add_u32 s62, s62, 0x40100
	s_addc_u32 s63, s63, 0
	s_add_u32 m0, s28, 0x4000
	s_nop 0
	global_load_lds_dwordx4 v232, s[62:63]
	s_nop 0
	s_add_u32 m0, s28, 0x6000
	s_nop 0
	global_load_lds_dwordx4 v234, s[62:63]
	s_waitcnt vmcnt(8)
	s_waitcnt lgkmcnt(0)
	s_barrier
	v_mfma_f32_16x16x32_f16 v[50:53], v[6:9], v[14:17], v[66:69]
	s_setprio 1
	v_mfma_f32_16x16x32_f16 v[118:121], v[26:29], v[18:21], v[50:53]
	v_mfma_f32_16x16x32_f16 v[50:53], v[186:189], v[14:17], v[70:73]
	v_mfma_f32_16x16x32_f16 v[114:117], v[190:193], v[18:21], v[50:53]
	v_mfma_f32_16x16x32_f16 v[50:53], v[6:9], v[30:33], v[74:77]
	v_mfma_f32_16x16x32_f16 v[102:105], v[26:29], v[222:225], v[50:53]
	v_mfma_f32_16x16x32_f16 v[50:53], v[186:189], v[30:33], v[78:81]
	v_mfma_f32_16x16x32_f16 v[98:101], v[190:193], v[222:225], v[50:53]
	v_mfma_f32_16x16x32_f16 v[50:53], v[6:9], v[226:229], v[82:85]
	v_mfma_f32_16x16x32_f16 v[86:89], v[26:29], v[242:245], v[50:53]
	v_mfma_f32_16x16x32_f16 v[50:53], v[186:189], v[226:229], v[90:93]
	v_mfma_f32_16x16x32_f16 v[78:81], v[190:193], v[242:245], v[50:53]
	v_mfma_f32_16x16x32_f16 v[50:53], v[6:9], v[246:249], v[94:97]
	v_mfma_f32_16x16x32_f16 v[58:61], v[26:29], v[250:253], v[50:53]
	v_mfma_f32_16x16x32_f16 v[50:53], v[186:189], v[246:249], v[106:109]
	v_mfma_f32_16x16x32_f16 v[50:53], v[190:193], v[250:253], v[50:53]
	v_mfma_f32_16x16x32_f16 v[66:69], v[206:209], v[14:17], v[110:113]
	v_mfma_f32_16x16x32_f16 v[126:129], v[210:213], v[18:21], v[66:69]
	v_mfma_f32_16x16x32_f16 v[14:17], v[214:217], v[14:17], v[34:37]
	v_mfma_f32_16x16x32_f16 v[122:125], v[218:221], v[18:21], v[14:17]
	v_mfma_f32_16x16x32_f16 v[14:17], v[206:209], v[30:33], v[38:41]
	v_mfma_f32_16x16x32_f16 v[110:113], v[210:213], v[222:225], v[14:17]
	v_mfma_f32_16x16x32_f16 v[14:17], v[214:217], v[30:33], v[42:45]
	v_mfma_f32_16x16x32_f16 v[106:109], v[218:221], v[222:225], v[14:17]
	v_mfma_f32_16x16x32_f16 v[14:17], v[206:209], v[226:229], v[46:49]
	v_mfma_f32_16x16x32_f16 v[94:97], v[210:213], v[242:245], v[14:17]
	v_mfma_f32_16x16x32_f16 v[14:17], v[214:217], v[226:229], v[54:57]
	v_mfma_f32_16x16x32_f16 v[90:93], v[218:221], v[242:245], v[14:17]
	v_mfma_f32_16x16x32_f16 v[14:17], v[206:209], v[246:249], v[130:133]
	v_mfma_f32_16x16x32_f16 v[74:77], v[210:213], v[250:253], v[14:17]
	v_mfma_f32_16x16x32_f16 v[14:17], v[214:217], v[246:249], v[62:65]
	v_mfma_f32_16x16x32_f16 v[66:69], v[218:221], v[250:253], v[14:17]
	s_barrier
	s_setprio 0
	ds_read_b128 v[38:41], v238 offset:49152
	ds_read_b128 v[42:45], v238 offset:50176
	ds_read_b128 v[130:133], v238 offset:51200
	ds_read_b128 v[222:225], v238 offset:52224
	ds_read_b128 v[226:229], v238 offset:53248
	ds_read_b128 v[242:245], v238 offset:54272
	ds_read_b128 v[246:249], v238 offset:55296
	ds_read_b128 v[250:253], v238 offset:56320
	s_add_u32 m0, s28, 0x18000
	s_nop 0
	global_load_lds_dwordx4 v233, s[26:27]
	s_nop 0
	s_add_u32 m0, s28, 0x1a000
	s_nop 0
	global_load_lds_dwordx4 v235, s[26:27]
	s_add_u32 s26, s6, 0x40180
	s_addc_u32 s27, s7, 0
	s_add_u32 m0, s28, 0x1c000
	s_nop 0
	global_load_lds_dwordx4 v233, s[26:27]
	s_nop 0
	s_add_u32 m0, s28, 0x1e000
	s_nop 0
	global_load_lds_dwordx4 v235, s[26:27]
	s_nop 0
	s_add_u32 m0, s28, 0x8000
	s_nop 0
	global_load_lds_dwordx4 v232, s[24:25]
	s_nop 0
	s_add_u32 m0, s28, 0xa000
	s_nop 0
	global_load_lds_dwordx4 v234, s[24:25]
	s_waitcnt vmcnt(8)
	s_waitcnt lgkmcnt(0)
	s_barrier
	v_mfma_f32_16x16x32_f16 v[14:17], v[6:9], v[38:41], v[134:137]
	s_setprio 1
	v_mfma_f32_16x16x32_f16 v[54:57], v[26:29], v[42:45], v[14:17]
	v_mfma_f32_16x16x32_f16 v[14:17], v[190:193], v[42:45], v[138:141]
	v_mfma_f32_16x16x32_f16 v[46:49], v[186:189], v[38:41], v[14:17]
	v_mfma_f32_16x16x32_f16 v[14:17], v[6:9], v[130:133], v[142:145]
	v_mfma_f32_16x16x32_f16 v[34:37], v[26:29], v[222:225], v[14:17]
	v_mfma_f32_16x16x32_f16 v[14:17], v[190:193], v[222:225], v[146:149]
	v_mfma_f32_16x16x32_f16 v[30:33], v[186:189], v[130:133], v[14:17]
	v_mfma_f32_16x16x32_f16 v[14:17], v[6:9], v[226:229], v[150:153]
	v_mfma_f32_16x16x32_f16 v[18:21], v[26:29], v[242:245], v[14:17]
	v_mfma_f32_16x16x32_f16 v[14:17], v[190:193], v[242:245], v[154:157]
	v_mfma_f32_16x16x32_f16 v[14:17], v[186:189], v[226:229], v[14:17]
	v_mfma_f32_16x16x32_f16 v[2:5], v[6:9], v[246:249], v[2:5]
	v_mfma_f32_16x16x32_f16 v[6:9], v[26:29], v[250:253], v[2:5]
	v_mfma_f32_16x16x32_f16 v[2:5], v[190:193], v[250:253], v[10:13]
	v_mfma_f32_16x16x32_f16 v[2:5], v[186:189], v[246:249], v[2:5]
	v_mfma_f32_16x16x32_f16 v[10:13], v[206:209], v[38:41], v[158:161]
	v_mfma_f32_16x16x32_f16 v[82:85], v[210:213], v[42:45], v[10:13]
	v_mfma_f32_16x16x32_f16 v[10:13], v[218:221], v[42:45], v[162:165]
	v_mfma_f32_16x16x32_f16 v[70:73], v[214:217], v[38:41], v[10:13]
	v_mfma_f32_16x16x32_f16 v[10:13], v[206:209], v[130:133], v[166:169]
	v_mfma_f32_16x16x32_f16 v[62:65], v[210:213], v[222:225], v[10:13]
	v_mfma_f32_16x16x32_f16 v[10:13], v[218:221], v[222:225], v[170:173]
	v_mfma_f32_16x16x32_f16 v[42:45], v[214:217], v[130:133], v[10:13]
	v_mfma_f32_16x16x32_f16 v[10:13], v[206:209], v[226:229], v[174:177]
	v_mfma_f32_16x16x32_f16 v[38:41], v[210:213], v[242:245], v[10:13]
	v_mfma_f32_16x16x32_f16 v[10:13], v[218:221], v[242:245], v[178:181]
	v_mfma_f32_16x16x32_f16 v[26:29], v[214:217], v[226:229], v[10:13]
	v_mfma_f32_16x16x32_f16 v[10:13], v[206:209], v[246:249], v[22:25]
	v_mfma_f32_16x16x32_f16 v[22:25], v[210:213], v[250:253], v[10:13]
	v_mfma_f32_16x16x32_f16 v[10:13], v[218:221], v[250:253], v[182:185]
	v_mfma_f32_16x16x32_f16 v[10:13], v[214:217], v[246:249], v[10:13]
	s_barrier
	s_setprio 0
	s_add_u32 s53, s6, 0x200
	s_addc_u32 s61, s7, 0
	s_mov_b32 s64, 0
	s_branch .LBB0_231
; #define PG8_STAGE(bufoff, gbase, voff) do { if constexpr (ABL & 1) break; glds16s<(bufoff)>((voff)[0], (const void*)(gbase), ldsbw); glds16s<(bufoff) + 8192>((voff)[1], (const void*)(gbase), ldsbw); } while (0)
; #define PG8_LDA(dst, b, h) do { if constexpr (ABL & 4) break; _Pragma("unroll") for (int m = 0; m < 4; ++m) _Pragma("unroll") for (int k = 0; k < 2; ++k) dst[m][k] = *(const LAS f16x8*)(lds + PG8_SA(b, h) + aoff + m * 2048 + k * 1024); } while (0)
; #define PG8_LDB(dst, b, h) do { if constexpr (ABL & 4) break; _Pragma("unroll") for (int n = 0; n < 2; ++n) _Pragma("unroll") for (int k = 0; k < 2; ++k) dst[n][k] = *(const LAS f16x8*)(lds + PG8_SB(b, h) + boff + n * 2048 + k * 1024); } while (0)
; #define PG8_MMAF(ai, bj, At, Bt) do { if (t == 0) PG8_MMA0(ai, bj, At, Bt); else PG8_MMA(ai, bj, At, Bt); } while (0)
;     ...
;             const char* a1 = cA + (size_t)(t + 1) * kstep;
;             const char* a2 = last ? nA : cA + (size_t)(t + 2) * kstep; const char* b2 = last ? nB : cB + (size_t)(t + 2) * kstep;
;             const char* a3 = a2 + kstep; const char* b3 = b2 + kstep;
;             if (last && has_next) S.a_ready(nxt);
;             if constexpr (SP2) {
;             PG8_LDB(B0, 0, 0); PG8_LDB(B1, 0, 1); PG8_SCHED; PG8_LDA(At, 0, 0); PG8_STAGE(PG8_SA(1, 1), a1 + hstep, voffA);
;             PG8_WAIT_V(8); PG8_WAIT_L(0); PG8_BAR; PG8_MMAF(0, 0, At, B0); PG8_MMAF(0, 1, At, B1); PG8_BAR; PG8_SCHED;
;             const bool fin = last && !has_next;
;             PG8_LDA(At, 0, 1); if (!fin) { PG8_STAGE(PG8_SB(0, 0), b2, voffB); PG8_STAGE(PG8_SB(0, 1), b2 + hstep, voffB); PG8_STAGE(PG8_SA(0, 0), a2, voffA); }
;             if (!fin) PG8_WAIT_V(8); else PG8_WAIT_V(2); PG8_WAIT_L(0); PG8_BAR; PG8_MMAF(1, 0, At, B0); PG8_MMAF(1, 1, At, B1); PG8_BAR; PG8_SCHED;
;             PG8_LDB(B0, 1, 0); PG8_LDB(B1, 1, 1); PG8_SCHED; PG8_LDA(At, 1, 0); if (!fin) PG8_STAGE(PG8_SA(0, 1), a2 + hstep, voffA);
;             if (!fin) PG8_WAIT_V(8); else PG8_WAIT_V(0); PG8_WAIT_L(0); PG8_BAR; PG8_MMA(0, 0, At, B0); PG8_MMA(0, 1, At, B1); PG8_BAR; PG8_SCHED;
;             PG8_LDA(At, 1, 1); if (!fin) { PG8_STAGE(PG8_SB(1, 0), b3, voffB); PG8_STAGE(PG8_SB(1, 1), b3 + hstep, voffB); PG8_STAGE(PG8_SA(1, 0), a3, voffA); }
;             if (!fin) PG8_WAIT_V(8); PG8_WAIT_L(0); PG8_BAR; PG8_MMA(1, 0, At, B0); PG8_MMA(1, 1, At, B1); PG8_BAR; PG8_SCHED;
.LBB0_230:
	s_waitcnt lgkmcnt(0)
	s_barrier
	v_mfma_f32_16x16x32_f16 v[54:57], v[154:157], v[186:189], v[54:57]
	s_setprio 1
	v_mfma_f32_16x16x32_f16 v[54:57], v[158:161], v[190:193], v[54:57]
	v_mfma_f32_16x16x32_f16 v[34:37], v[158:161], v[182:185], v[34:37]
	v_mfma_f32_16x16x32_f16 v[34:37], v[154:157], v[178:181], v[34:37]
	v_mfma_f32_16x16x32_f16 v[18:21], v[154:157], v[170:173], v[18:21]
	v_mfma_f32_16x16x32_f16 v[18:21], v[158:161], v[174:177], v[18:21]
	v_mfma_f32_16x16x32_f16 v[6:9], v[158:161], v[166:169], v[6:9]
	v_mfma_f32_16x16x32_f16 v[6:9], v[154:157], v[162:165], v[6:9]
	v_mfma_f32_16x16x32_f16 v[2:5], v[146:149], v[162:165], v[2:5]
	v_mfma_f32_16x16x32_f16 v[2:5], v[150:153], v[166:169], v[2:5]
	v_mfma_f32_16x16x32_f16 v[46:49], v[150:153], v[190:193], v[46:49]
	v_mfma_f32_16x16x32_f16 v[46:49], v[146:149], v[186:189], v[46:49]
	v_mfma_f32_16x16x32_f16 v[30:33], v[146:149], v[178:181], v[30:33]
	v_mfma_f32_16x16x32_f16 v[30:33], v[150:153], v[182:185], v[30:33]
	v_mfma_f32_16x16x32_f16 v[14:17], v[150:153], v[174:177], v[14:17]
	v_mfma_f32_16x16x32_f16 v[14:17], v[146:149], v[170:173], v[14:17]
	v_mfma_f32_16x16x32_f16 v[38:41], v[138:141], v[170:173], v[38:41]
	v_mfma_f32_16x16x32_f16 v[38:41], v[142:145], v[174:177], v[38:41]
	v_mfma_f32_16x16x32_f16 v[82:85], v[142:145], v[190:193], v[82:85]
	v_mfma_f32_16x16x32_f16 v[82:85], v[138:141], v[186:189], v[82:85]
	v_mfma_f32_16x16x32_f16 v[62:65], v[138:141], v[178:181], v[62:65]
	v_mfma_f32_16x16x32_f16 v[62:65], v[142:145], v[182:185], v[62:65]
	v_mfma_f32_16x16x32_f16 v[22:25], v[142:145], v[166:169], v[22:25]
	v_mfma_f32_16x16x32_f16 v[22:25], v[138:141], v[162:165], v[22:25]
	v_mfma_f32_16x16x32_f16 v[10:13], v[130:133], v[162:165], v[10:13]
	v_mfma_f32_16x16x32_f16 v[10:13], v[134:137], v[166:169], v[10:13]
	v_mfma_f32_16x16x32_f16 v[70:73], v[134:137], v[190:193], v[70:73]
	v_mfma_f32_16x16x32_f16 v[70:73], v[130:133], v[186:189], v[70:73]
	v_mfma_f32_16x16x32_f16 v[42:45], v[130:133], v[178:181], v[42:45]
	v_mfma_f32_16x16x32_f16 v[42:45], v[134:137], v[182:185], v[42:45]
	v_mfma_f32_16x16x32_f16 v[26:29], v[134:137], v[174:177], v[26:29]
	v_mfma_f32_16x16x32_f16 v[26:29], v[130:133], v[170:173], v[26:29]
	s_barrier
	s_setprio 0
	s_add_i32 s64, s64, 2
	s_add_u32 s53, s53, 0x100
	s_addc_u32 s61, s61, 0
	s_cmp_gt_u32 s64, 13
	s_cbranch_scc1 .LBB0_241
.LBB0_231:
	ds_read_b128 v[146:149], v236
	ds_read_b128 v[150:153], v236 offset:1024
	ds_read_b128 v[154:157], v236 offset:2048
	ds_read_b128 v[158:161], v236 offset:3072
	ds_read_b128 v[130:133], v237
	ds_read_b128 v[134:137], v237 offset:1024
	ds_read_b128 v[138:141], v237 offset:2048
	ds_read_b128 v[142:145], v237 offset:3072
	s_mov_b64 s[6:7], s[8:9]
	s_add_u32 s8, s6, 0x100
	s_addc_u32 s9, s7, 0
	s_cmp_eq_u32 s64, 12
	s_cselect_b64 s[62:63], -1, 0
	s_and_b64 s[24:25], s[62:63], exec
	s_cselect_b32 s27, s11, s9
	s_cselect_b32 s26, s35, s8
	s_cselect_b32 s25, s1, s61
	s_cselect_b32 s24, s46, s53
	ds_read_b128 v[162:165], v238
	ds_read_b128 v[166:169], v238 offset:1024
	ds_read_b128 v[170:173], v238 offset:2048
	ds_read_b128 v[174:177], v238 offset:3072
	ds_read_b128 v[178:181], v238 offset:4096
	ds_read_b128 v[182:185], v238 offset:5120
	ds_read_b128 v[186:189], v238 offset:6144
	ds_read_b128 v[190:193], v238 offset:7168
	s_add_u32 s6, s6, 0x40080
	s_addc_u32 s7, s7, 0
	s_add_u32 m0, s28, 0xc000
	s_nop 0
	global_load_lds_dwordx4 v232, s[6:7]
	s_nop 0
	s_add_u32 m0, s28, 0xe000
	s_nop 0
	global_load_lds_dwordx4 v234, s[6:7]
	s_waitcnt vmcnt(8)
	s_waitcnt lgkmcnt(0)
	s_barrier
	v_mfma_f32_16x16x32_f16 v[118:121], v[146:149], v[162:165], v[118:121]
	s_setprio 1
	v_mfma_f32_16x16x32_f16 v[118:121], v[150:153], v[166:169], v[118:121]
	v_mfma_f32_16x16x32_f16 v[102:105], v[150:153], v[174:177], v[102:105]
	v_mfma_f32_16x16x32_f16 v[102:105], v[146:149], v[170:173], v[102:105]
	v_mfma_f32_16x16x32_f16 v[86:89], v[146:149], v[178:181], v[86:89]
	v_mfma_f32_16x16x32_f16 v[86:89], v[150:153], v[182:185], v[86:89]
	v_mfma_f32_16x16x32_f16 v[58:61], v[150:153], v[190:193], v[58:61]
	v_mfma_f32_16x16x32_f16 v[58:61], v[146:149], v[186:189], v[58:61]
	v_mfma_f32_16x16x32_f16 v[50:53], v[154:157], v[186:189], v[50:53]
	v_mfma_f32_16x16x32_f16 v[50:53], v[158:161], v[190:193], v[50:53]
	v_mfma_f32_16x16x32_f16 v[114:117], v[158:161], v[166:169], v[114:117]
	v_mfma_f32_16x16x32_f16 v[114:117], v[154:157], v[162:165], v[114:117]
	v_mfma_f32_16x16x32_f16 v[98:101], v[154:157], v[170:173], v[98:101]
	v_mfma_f32_16x16x32_f16 v[98:101], v[158:161], v[174:177], v[98:101]
	v_mfma_f32_16x16x32_f16 v[78:81], v[158:161], v[182:185], v[78:81]
	v_mfma_f32_16x16x32_f16 v[78:81], v[154:157], v[178:181], v[78:81]
	v_mfma_f32_16x16x32_f16 v[94:97], v[130:133], v[178:181], v[94:97]
	v_mfma_f32_16x16x32_f16 v[94:97], v[134:137], v[182:185], v[94:97]
	v_mfma_f32_16x16x32_f16 v[126:129], v[134:137], v[166:169], v[126:129]
	v_mfma_f32_16x16x32_f16 v[126:129], v[130:133], v[162:165], v[126:129]
	v_mfma_f32_16x16x32_f16 v[110:113], v[130:133], v[170:173], v[110:113]
	v_mfma_f32_16x16x32_f16 v[110:113], v[134:137], v[174:177], v[110:113]
	v_mfma_f32_16x16x32_f16 v[74:77], v[134:137], v[190:193], v[74:77]
	v_mfma_f32_16x16x32_f16 v[74:77], v[130:133], v[186:189], v[74:77]
	v_mfma_f32_16x16x32_f16 v[66:69], v[138:141], v[186:189], v[66:69]
	v_mfma_f32_16x16x32_f16 v[66:69], v[142:145], v[190:193], v[66:69]
	v_mfma_f32_16x16x32_f16 v[122:125], v[142:145], v[166:169], v[122:125]
	v_mfma_f32_16x16x32_f16 v[122:125], v[138:141], v[162:165], v[122:125]
	v_mfma_f32_16x16x32_f16 v[106:109], v[138:141], v[170:173], v[106:109]
	v_mfma_f32_16x16x32_f16 v[106:109], v[142:145], v[174:177], v[106:109]
	v_mfma_f32_16x16x32_f16 v[90:93], v[142:145], v[182:185], v[90:93]
	v_mfma_f32_16x16x32_f16 v[90:93], v[138:141], v[178:181], v[90:93]
	s_barrier
	s_setprio 0
	ds_read_b128 v[186:189], v238 offset:16384
	ds_read_b128 v[190:193], v238 offset:17408
	ds_read_b128 v[178:181], v238 offset:18432
	ds_read_b128 v[182:185], v238 offset:19456
	ds_read_b128 v[170:173], v238 offset:20480
	ds_read_b128 v[174:177], v238 offset:21504
	ds_read_b128 v[162:165], v238 offset:22528
	ds_read_b128 v[166:169], v238 offset:23552
	s_and_b64 s[6:7], s[4:5], s[62:63]
	s_mov_b64 s[62:63], -1
	s_and_b64 vcc, exec, s[6:7]
	s_cbranch_vccnz .LBB0_233
	s_add_u32 m0, s28, 0x10000
	s_nop 0
	global_load_lds_dwordx4 v233, s[24:25]
	s_nop 0
	s_add_u32 m0, s28, 0x12000
	s_nop 0
	global_load_lds_dwordx4 v235, s[24:25]
	s_add_u32 s62, s24, 0x40000
	s_addc_u32 s63, s25, 0
	s_add_u32 m0, s28, 0x14000
	s_nop 0
	global_load_lds_dwordx4 v233, s[62:63]
	s_nop 0
	s_add_u32 m0, s28, 0x16000
	s_nop 0
	global_load_lds_dwordx4 v235, s[62:63]
	s_mov_b64 s[62:63], 0
	s_add_u32 m0, s28, 0
	s_nop 0
	global_load_lds_dwordx4 v232, s[26:27]
	s_nop 0
	s_add_u32 m0, s28, 0x2000
	s_nop 0
	global_load_lds_dwordx4 v234, s[26:27]
	s_waitcnt vmcnt(8)

; #define PG8_STAGE(bufoff, gbase, voff) do { if constexpr (ABL & 1) break; glds16s<(bufoff)>((voff)[0], (const void*)(gbase), ldsbw); glds16s<(bufoff) + 8192>((voff)[1], (const void*)(gbase), ldsbw); } while (0)
; #define PG8_LDA(dst, b, h) do { if constexpr (ABL & 4) break; _Pragma("unroll") for (int m = 0; m < 4; ++m) _Pragma("unroll") for (int k = 0; k < 2; ++k) dst[m][k] = *(const LAS f16x8*)(lds + PG8_SA(b, h) + aoff + m * 2048 + k * 1024); } while (0)
; #define PG8_LDB(dst, b, h) do { if constexpr (ABL & 4) break; _Pragma("unroll") for (int n = 0; n < 2; ++n) _Pragma("unroll") for (int k = 0; k < 2; ++k) dst[n][k] = *(const LAS f16x8*)(lds + PG8_SB(b, h) + boff + n * 2048 + k * 1024); } while (0)
; #define PG8_MMA(ai, bj, At, Bt) do { if constexpr (ABL & 2) break; __builtin_amdgcn_s_setprio(1); _Pragma("unroll") for (int m = 0; m < 4; ++m) _Pragma("unroll") for (int n = 0; n < 2; ++n) _Pragma("unroll") for (int k = 0; k < 2; ++k) \
;         acc[ai][bj][m][n] = __builtin_amdgcn_mfma_f32_16x16x32_f16(Bt[n][k], At[m][k], acc[ai][bj][m][n], 0, 0, 0); __builtin_amdgcn_s_setprio(0); } while (0)
; #define PG8_MMAF(ai, bj, At, Bt) do { if (t == 0) PG8_MMA0(ai, bj, At, Bt); else PG8_MMA(ai, bj, At, Bt); } while (0)
; #define PG8_WAIT_V(n) asm volatile("s_waitcnt vmcnt(" #n ")" ::: "memory")
; #define PG8_WAIT_L(n) asm volatile("s_waitcnt lgkmcnt(" #n ")" ::: "memory")
; #define PG8_BAR __builtin_amdgcn_s_barrier()
; #define PG8_SCHED __builtin_amdgcn_sched_barrier(0)
;     ...
;             const bool fin = last && !has_next;
;             PG8_LDA(At, 0, 1); if (!fin) { PG8_STAGE(PG8_SB(0, 0), b2, voffB); PG8_STAGE(PG8_SB(0, 1), b2 + hstep, voffB); PG8_STAGE(PG8_SA(0, 0), a2, voffA); }
;             if (!fin) PG8_WAIT_V(8); else PG8_WAIT_V(2); PG8_WAIT_L(0); PG8_BAR; PG8_MMAF(1, 0, At, B0); PG8_MMAF(1, 1, At, B1); PG8_BAR; PG8_SCHED;
;             PG8_LDB(B0, 1, 0); PG8_LDB(B1, 1, 1); PG8_SCHED; PG8_LDA(At, 1, 0); if (!fin) PG8_STAGE(PG8_SA(0, 1), a2 + hstep, voffA);
;             if (!fin) PG8_WAIT_V(8); else PG8_WAIT_V(0); PG8_WAIT_L(0); PG8_BAR; PG8_MMA(0, 0, At, B0); PG8_MMA(0, 1, At, B1); PG8_BAR; PG8_SCHED;
.LBB0_235:
	s_waitcnt lgkmcnt(0)
	s_xor_b64 s[62:63], s[6:7], -1
	s_barrier
	v_mfma_f32_16x16x32_f16 v[54:57], v[146:149], v[186:189], v[54:57]
	s_setprio 1
	v_mfma_f32_16x16x32_f16 v[54:57], v[150:153], v[190:193], v[54:57]
	v_mfma_f32_16x16x32_f16 v[34:37], v[150:153], v[182:185], v[34:37]
	v_mfma_f32_16x16x32_f16 v[34:37], v[146:149], v[178:181], v[34:37]
	v_mfma_f32_16x16x32_f16 v[18:21], v[146:149], v[170:173], v[18:21]
	v_mfma_f32_16x16x32_f16 v[18:21], v[150:153], v[174:177], v[18:21]
	v_mfma_f32_16x16x32_f16 v[6:9], v[150:153], v[166:169], v[6:9]
	v_mfma_f32_16x16x32_f16 v[6:9], v[146:149], v[162:165], v[6:9]
	v_mfma_f32_16x16x32_f16 v[2:5], v[154:157], v[162:165], v[2:5]
	v_mfma_f32_16x16x32_f16 v[2:5], v[158:161], v[166:169], v[2:5]
	v_mfma_f32_16x16x32_f16 v[46:49], v[158:161], v[190:193], v[46:49]
	v_mfma_f32_16x16x32_f16 v[46:49], v[154:157], v[186:189], v[46:49]
	v_mfma_f32_16x16x32_f16 v[30:33], v[154:157], v[178:181], v[30:33]
	v_mfma_f32_16x16x32_f16 v[30:33], v[158:161], v[182:185], v[30:33]
	v_mfma_f32_16x16x32_f16 v[14:17], v[158:161], v[174:177], v[14:17]
	v_mfma_f32_16x16x32_f16 v[14:17], v[154:157], v[170:173], v[14:17]
	v_mfma_f32_16x16x32_f16 v[38:41], v[130:133], v[170:173], v[38:41]
	v_mfma_f32_16x16x32_f16 v[38:41], v[134:137], v[174:177], v[38:41]
	v_mfma_f32_16x16x32_f16 v[82:85], v[134:137], v[190:193], v[82:85]
	v_mfma_f32_16x16x32_f16 v[82:85], v[130:133], v[186:189], v[82:85]
	v_mfma_f32_16x16x32_f16 v[62:65], v[130:133], v[178:181], v[62:65]
	v_mfma_f32_16x16x32_f16 v[62:65], v[134:137], v[182:185], v[62:65]
	v_mfma_f32_16x16x32_f16 v[22:25], v[134:137], v[166:169], v[22:25]
	v_mfma_f32_16x16x32_f16 v[22:25], v[130:133], v[162:165], v[22:25]
	v_mfma_f32_16x16x32_f16 v[10:13], v[138:141], v[162:165], v[10:13]
	v_mfma_f32_16x16x32_f16 v[10:13], v[142:145], v[166:169], v[10:13]
	v_mfma_f32_16x16x32_f16 v[70:73], v[142:145], v[190:193], v[70:73]
	v_mfma_f32_16x16x32_f16 v[70:73], v[138:141], v[186:189], v[70:73]
	v_mfma_f32_16x16x32_f16 v[42:45], v[138:141], v[178:181], v[42:45]
	v_mfma_f32_16x16x32_f16 v[42:45], v[142:145], v[182:185], v[42:45]
	v_mfma_f32_16x16x32_f16 v[26:29], v[142:145], v[174:177], v[26:29]
	v_mfma_f32_16x16x32_f16 v[26:29], v[138:141], v[170:173], v[26:29]
	s_barrier
	s_setprio 0
	ds_read_b128 v[154:157], v239
	ds_read_b128 v[158:161], v239 offset:1024
	ds_read_b128 v[146:149], v239 offset:2048
	ds_read_b128 v[150:153], v239 offset:3072
	ds_read_b128 v[138:141], v240
	ds_read_b128 v[142:145], v240 offset:1024
	ds_read_b128 v[130:133], v240 offset:2048
	ds_read_b128 v[134:137], v240 offset:3072
	ds_read_b128 v[186:189], v238 offset:32768
	ds_read_b128 v[190:193], v238 offset:33792
	ds_read_b128 v[178:181], v238 offset:34816
	ds_read_b128 v[182:185], v238 offset:35840
	ds_read_b128 v[170:173], v238 offset:36864
	ds_read_b128 v[174:177], v238 offset:37888
	ds_read_b128 v[162:165], v238 offset:38912
	ds_read_b128 v[166:169], v238 offset:39936
	v_cndmask_b32_e64 v198, 0, 1, s[62:63]
	v_cmp_ne_u32_e64 s[6:7], 1, v198
	s_andn2_b64 vcc, exec, s[62:63]
	s_mov_b64 s[62:63], -1
	s_cbranch_vccnz .LBB0_237
	s_add_u32 s62, s26, 0x40000
	s_addc_u32 s63, s27, 0
	s_add_u32 m0, s28, 0x4000
	s_nop 0
	global_load_lds_dwordx4 v232, s[62:63]
	s_nop 0
	s_add_u32 m0, s28, 0x6000
	s_nop 0
	global_load_lds_dwordx4 v234, s[62:63]
	s_waitcnt vmcnt(8)
	s_mov_b64 s[62:63], 0

; #define PG8_STAGE(bufoff, gbase, voff) do { if constexpr (ABL & 1) break; glds16s<(bufoff)>((voff)[0], (const void*)(gbase), ldsbw); glds16s<(bufoff) + 8192>((voff)[1], (const void*)(gbase), ldsbw); } while (0)
; #define PG8_LDA(dst, b, h) do { if constexpr (ABL & 4) break; _Pragma("unroll") for (int m = 0; m < 4; ++m) _Pragma("unroll") for (int k = 0; k < 2; ++k) dst[m][k] = *(const LAS f16x8*)(lds + PG8_SA(b, h) + aoff + m * 2048 + k * 1024); } while (0)
; #define PG8_LDB(dst, b, h) do { if constexpr (ABL & 4) break; _Pragma("unroll") for (int n = 0; n < 2; ++n) _Pragma("unroll") for (int k = 0; k < 2; ++k) dst[n][k] = *(const LAS f16x8*)(lds + PG8_SB(b, h) + boff + n * 2048 + k * 1024); } while (0)
; #define PG8_MMA(ai, bj, At, Bt) do { if constexpr (ABL & 2) break; __builtin_amdgcn_s_setprio(1); _Pragma("unroll") for (int m = 0; m < 4; ++m) _Pragma("unroll") for (int n = 0; n < 2; ++n) _Pragma("unroll") for (int k = 0; k < 2; ++k) \
;         acc[ai][bj][m][n] = __builtin_amdgcn_mfma_f32_16x16x32_f16(Bt[n][k], At[m][k], acc[ai][bj][m][n], 0, 0, 0); __builtin_amdgcn_s_setprio(0); } while (0)
; #define PG8_WAIT_V(n) asm volatile("s_waitcnt vmcnt(" #n ")" ::: "memory")
; #define PG8_WAIT_L(n) asm volatile("s_waitcnt lgkmcnt(" #n ")" ::: "memory")
; #define PG8_BAR __builtin_amdgcn_s_barrier()
; #define PG8_SCHED __builtin_amdgcn_sched_barrier(0)
;     ...
;             PG8_LDB(B0, 1, 0); PG8_LDB(B1, 1, 1); PG8_SCHED; PG8_LDA(At, 1, 0); if (!fin) PG8_STAGE(PG8_SA(0, 1), a2 + hstep, voffA);
;             if (!fin) PG8_WAIT_V(8); else PG8_WAIT_V(0); PG8_WAIT_L(0); PG8_BAR; PG8_MMA(0, 0, At, B0); PG8_MMA(0, 1, At, B1); PG8_BAR; PG8_SCHED;
;             PG8_LDA(At, 1, 1); if (!fin) { PG8_STAGE(PG8_SB(1, 0), b3, voffB); PG8_STAGE(PG8_SB(1, 1), b3 + hstep, voffB); PG8_STAGE(PG8_SA(1, 0), a3, voffA); }
;             if (!fin) PG8_WAIT_V(8); PG8_WAIT_L(0); PG8_BAR; PG8_MMA(1, 0, At, B0); PG8_MMA(1, 1, At, B1); PG8_BAR; PG8_SCHED;
.LBB0_239:
	s_waitcnt lgkmcnt(0)
	s_barrier
	v_mfma_f32_16x16x32_f16 v[118:121], v[154:157], v[186:189], v[118:121]
	s_setprio 1
	v_mfma_f32_16x16x32_f16 v[118:121], v[158:161], v[190:193], v[118:121]
	v_mfma_f32_16x16x32_f16 v[102:105], v[158:161], v[182:185], v[102:105]
	v_mfma_f32_16x16x32_f16 v[102:105], v[154:157], v[178:181], v[102:105]
	v_mfma_f32_16x16x32_f16 v[86:89], v[154:157], v[170:173], v[86:89]
	v_mfma_f32_16x16x32_f16 v[86:89], v[158:161], v[174:177], v[86:89]
	v_mfma_f32_16x16x32_f16 v[58:61], v[158:161], v[166:169], v[58:61]
	v_mfma_f32_16x16x32_f16 v[58:61], v[154:157], v[162:165], v[58:61]
	v_mfma_f32_16x16x32_f16 v[50:53], v[146:149], v[162:165], v[50:53]
	v_mfma_f32_16x16x32_f16 v[50:53], v[150:153], v[166:169], v[50:53]
	v_mfma_f32_16x16x32_f16 v[114:117], v[150:153], v[190:193], v[114:117]
	v_mfma_f32_16x16x32_f16 v[114:117], v[146:149], v[186:189], v[114:117]
	v_mfma_f32_16x16x32_f16 v[98:101], v[146:149], v[178:181], v[98:101]
	v_mfma_f32_16x16x32_f16 v[98:101], v[150:153], v[182:185], v[98:101]
	v_mfma_f32_16x16x32_f16 v[78:81], v[150:153], v[174:177], v[78:81]
	v_mfma_f32_16x16x32_f16 v[78:81], v[146:149], v[170:173], v[78:81]
	v_mfma_f32_16x16x32_f16 v[94:97], v[138:141], v[170:173], v[94:97]
	v_mfma_f32_16x16x32_f16 v[94:97], v[142:145], v[174:177], v[94:97]
	v_mfma_f32_16x16x32_f16 v[126:129], v[142:145], v[190:193], v[126:129]
	v_mfma_f32_16x16x32_f16 v[126:129], v[138:141], v[186:189], v[126:129]
	v_mfma_f32_16x16x32_f16 v[110:113], v[138:141], v[178:181], v[110:113]
	v_mfma_f32_16x16x32_f16 v[110:113], v[142:145], v[182:185], v[110:113]
	v_mfma_f32_16x16x32_f16 v[74:77], v[142:145], v[166:169], v[74:77]
	v_mfma_f32_16x16x32_f16 v[74:77], v[138:141], v[162:165], v[74:77]
	v_mfma_f32_16x16x32_f16 v[66:69], v[130:133], v[162:165], v[66:69]
	v_mfma_f32_16x16x32_f16 v[66:69], v[134:137], v[166:169], v[66:69]
	v_mfma_f32_16x16x32_f16 v[122:125], v[134:137], v[190:193], v[122:125]
	v_mfma_f32_16x16x32_f16 v[122:125], v[130:133], v[186:189], v[122:125]
	v_mfma_f32_16x16x32_f16 v[106:109], v[130:133], v[178:181], v[106:109]
	v_mfma_f32_16x16x32_f16 v[106:109], v[134:137], v[182:185], v[106:109]
	v_mfma_f32_16x16x32_f16 v[90:93], v[134:137], v[174:177], v[90:93]
	v_mfma_f32_16x16x32_f16 v[90:93], v[130:133], v[170:173], v[90:93]
	s_barrier
	s_setprio 0
	ds_read_b128 v[186:189], v238 offset:49152
	ds_read_b128 v[190:193], v238 offset:50176
	ds_read_b128 v[178:181], v238 offset:51200
	ds_read_b128 v[182:185], v238 offset:52224
	ds_read_b128 v[170:173], v238 offset:53248
	ds_read_b128 v[174:177], v238 offset:54272
	ds_read_b128 v[162:165], v238 offset:55296
	ds_read_b128 v[166:169], v238 offset:56320
	s_and_b64 vcc, exec, s[6:7]
	s_cbranch_vccnz .LBB0_230
	s_add_u32 s6, s26, 0x80
	s_addc_u32 s7, s27, 0
	s_add_u32 s26, s24, 0x80
	s_addc_u32 s27, s25, 0
	s_add_u32 m0, s28, 0x18000
	s_nop 0
	global_load_lds_dwordx4 v233, s[26:27]
	s_nop 0
	s_add_u32 m0, s28, 0x1a000
	s_nop 0
	global_load_lds_dwordx4 v235, s[26:27]
	s_add_u32 s24, s24, 0x40080
	s_addc_u32 s25, s25, 0
	s_add_u32 m0, s28, 0x1c000
	s_nop 0
	global_load_lds_dwordx4 v233, s[24:25]
	s_nop 0
	s_add_u32 m0, s28, 0x1e000
	s_nop 0
	global_load_lds_dwordx4 v235, s[24:25]
	s_nop 0
	s_add_u32 m0, s28, 0x8000
	s_nop 0
	global_load_lds_dwordx4 v232, s[6:7]
	s_nop 0
	s_add_u32 m0, s28, 0xa000
	s_nop 0
	global_load_lds_dwordx4 v234, s[6:7]
	s_waitcnt vmcnt(8)
	s_branch .LBB0_230

; #define PG8_STAGE(bufoff, gbase, voff) do { if constexpr (ABL & 1) break; glds16s<(bufoff)>((voff)[0], (const void*)(gbase), ldsbw); glds16s<(bufoff) + 8192>((voff)[1], (const void*)(gbase), ldsbw); } while (0)
; #define PG8_LDA(dst, b, h) do { if constexpr (ABL & 4) break; _Pragma("unroll") for (int m = 0; m < 4; ++m) _Pragma("unroll") for (int k = 0; k < 2; ++k) dst[m][k] = *(const LAS f16x8*)(lds + PG8_SA(b, h) + aoff + m * 2048 + k * 1024); } while (0)
; #define PG8_LDB(dst, b, h) do { if constexpr (ABL & 4) break; _Pragma("unroll") for (int n = 0; n < 2; ++n) _Pragma("unroll") for (int k = 0; k < 2; ++k) dst[n][k] = *(const LAS f16x8*)(lds + PG8_SB(b, h) + boff + n * 2048 + k * 1024); } while (0)
; #define PG8_MMAF(ai, bj, At, Bt) do { if (t == 0) PG8_MMA0(ai, bj, At, Bt); else PG8_MMA(ai, bj, At, Bt); } while (0)
; #define PG8_WAIT_V(n) asm volatile("s_waitcnt vmcnt(" #n ")" ::: "memory")
; #define PG8_WAIT_L(n) asm volatile("s_waitcnt lgkmcnt(" #n ")" ::: "memory")
; #define PG8_BAR __builtin_amdgcn_s_barrier()
; #define PG8_SCHED __builtin_amdgcn_sched_barrier(0)
;     ...
;             PG8_LDB(B0, 0, 0); PG8_LDB(B1, 0, 1); PG8_SCHED; PG8_LDA(At, 0, 0); PG8_STAGE(PG8_SA(1, 1), a1 + hstep, voffA);
;             PG8_WAIT_V(8); PG8_WAIT_L(0); PG8_BAR; PG8_MMAF(0, 0, At, B0); PG8_MMAF(0, 1, At, B1); PG8_BAR; PG8_SCHED;
;             const bool fin = last && !has_next;
;             PG8_LDA(At, 0, 1); if (!fin) { PG8_STAGE(PG8_SB(0, 0), b2, voffB); PG8_STAGE(PG8_SB(0, 1), b2 + hstep, voffB); PG8_STAGE(PG8_SA(0, 0), a2, voffA); }
;             if (!fin) PG8_WAIT_V(8); else PG8_WAIT_V(2); PG8_WAIT_L(0); PG8_BAR; PG8_MMAF(1, 0, At, B0); PG8_MMAF(1, 1, At, B1); PG8_BAR; PG8_SCHED;
.LBB0_748:
	s_ashr_i32 s47, s46, 31
	s_lshl_b64 s[8:9], s[46:47], 19
	s_add_u32 s48, s12, s8
	s_addc_u32 s49, s13, s9
	s_and_b64 s[8:9], exec, s[4:5]
	s_waitcnt lgkmcnt(0)
	ds_read_b128 v[2:5], v222
	ds_read_b128 v[6:9], v222 offset:1024
	ds_read_b128 v[10:13], v222 offset:2048
	ds_read_b128 v[14:17], v222 offset:3072
	ds_read_b128 v[18:21], v223
	ds_read_b128 v[22:25], v223 offset:1024
	ds_read_b128 v[26:29], v223 offset:2048
	ds_read_b128 v[30:33], v223 offset:3072
	s_cselect_b32 s47, s31, s49
	s_cselect_b32 s55, s30, s48
	s_ashr_i32 s45, s44, 31
	s_lshl_b64 s[8:9], s[44:45], 19
	s_add_u32 s50, s90, s8
	s_addc_u32 s51, s91, s9
	s_and_b64 s[8:9], exec, s[4:5]
	s_cselect_b32 s45, s7, s51
	s_cselect_b32 s58, s6, s50
	s_add_u32 s56, s30, 0x100
	s_addc_u32 s57, s31, 0
	s_add_u32 s26, s6, 0x100
	s_addc_u32 s27, s7, 0
	s_add_u32 s8, s30, 0x180
	s_addc_u32 s9, s31, 0
	ds_read_b128 v[34:37], v224
	ds_read_b128 v[38:41], v224 offset:1024
	ds_read_b128 v[42:45], v224 offset:2048
	ds_read_b128 v[46:49], v224 offset:3072
	ds_read_b128 v[50:53], v224 offset:4096
	ds_read_b128 v[54:57], v224 offset:5120
	ds_read_b128 v[58:61], v224 offset:6144
	ds_read_b128 v[62:65], v224 offset:7168
	s_add_u32 s24, s6, 0x180
	s_addc_u32 s25, s7, 0
	s_add_u32 s60, s30, 0x40080
	s_addc_u32 s61, s31, 0
	s_add_u32 m0, s14, 0xc000
	s_nop 0
	global_load_lds_dwordx4 v1, s[60:61]
	s_nop 0
	s_add_u32 m0, s14, 0xe000
	s_nop 0
	global_load_lds_dwordx4 v213, s[60:61]
	s_waitcnt vmcnt(8)
	s_waitcnt lgkmcnt(0)
	s_barrier
	v_mfma_f32_16x16x32_f16 v[66:69], v[2:5], v[34:37], 0
	s_setprio 1
	v_mfma_f32_16x16x32_f16 v[66:69], v[6:9], v[38:41], v[66:69]
	v_mfma_f32_16x16x32_f16 v[70:73], v[10:13], v[34:37], 0
	v_mfma_f32_16x16x32_f16 v[70:73], v[14:17], v[38:41], v[70:73]
	v_mfma_f32_16x16x32_f16 v[78:81], v[10:13], v[42:45], 0
	v_mfma_f32_16x16x32_f16 v[78:81], v[14:17], v[46:49], v[78:81]
	v_mfma_f32_16x16x32_f16 v[82:85], v[2:5], v[50:53], 0
	v_mfma_f32_16x16x32_f16 v[82:85], v[6:9], v[54:57], v[82:85]
	v_mfma_f32_16x16x32_f16 v[90:93], v[2:5], v[58:61], 0
	v_mfma_f32_16x16x32_f16 v[90:93], v[6:9], v[62:65], v[90:93]
	v_mfma_f32_16x16x32_f16 v[94:97], v[10:13], v[58:61], 0
	v_mfma_f32_16x16x32_f16 v[94:97], v[14:17], v[62:65], v[94:97]
	v_mfma_f32_16x16x32_f16 v[74:77], v[2:5], v[42:45], 0
	v_mfma_f32_16x16x32_f16 v[74:77], v[6:9], v[46:49], v[74:77]
	v_mfma_f32_16x16x32_f16 v[86:89], v[10:13], v[50:53], 0
	v_mfma_f32_16x16x32_f16 v[86:89], v[14:17], v[54:57], v[86:89]
	v_mfma_f32_16x16x32_f16 v[98:101], v[18:21], v[34:37], 0
	v_mfma_f32_16x16x32_f16 v[98:101], v[22:25], v[38:41], v[98:101]
	v_mfma_f32_16x16x32_f16 v[34:37], v[26:29], v[34:37], 0
	v_mfma_f32_16x16x32_f16 v[34:37], v[30:33], v[38:41], v[34:37]
	v_mfma_f32_16x16x32_f16 v[38:41], v[18:21], v[42:45], 0
	v_mfma_f32_16x16x32_f16 v[38:41], v[22:25], v[46:49], v[38:41]
	v_mfma_f32_16x16x32_f16 v[42:45], v[26:29], v[42:45], 0
	v_mfma_f32_16x16x32_f16 v[42:45], v[30:33], v[46:49], v[42:45]
	v_mfma_f32_16x16x32_f16 v[46:49], v[18:21], v[50:53], 0
	v_mfma_f32_16x16x32_f16 v[46:49], v[22:25], v[54:57], v[46:49]
	v_mfma_f32_16x16x32_f16 v[50:53], v[26:29], v[50:53], 0
	v_mfma_f32_16x16x32_f16 v[50:53], v[30:33], v[54:57], v[50:53]
	v_mfma_f32_16x16x32_f16 v[54:57], v[18:21], v[58:61], 0
	v_mfma_f32_16x16x32_f16 v[54:57], v[22:25], v[62:65], v[54:57]
	v_mfma_f32_16x16x32_f16 v[58:61], v[26:29], v[58:61], 0
	v_mfma_f32_16x16x32_f16 v[58:61], v[30:33], v[62:65], v[58:61]
	s_barrier
	s_setprio 0
	ds_read_b128 v[62:65], v224 offset:16384
	ds_read_b128 v[102:105], v224 offset:17408
	ds_read_b128 v[106:109], v224 offset:18432
	ds_read_b128 v[110:113], v224 offset:19456
	ds_read_b128 v[114:117], v224 offset:20480
	ds_read_b128 v[118:121], v224 offset:21504
	ds_read_b128 v[122:125], v224 offset:22528
	ds_read_b128 v[126:129], v224 offset:23552
	s_add_u32 m0, s14, 0x10000
	s_nop 0
	global_load_lds_dwordx4 v209, s[26:27]
	s_nop 0
	s_add_u32 m0, s14, 0x12000
	s_nop 0
	global_load_lds_dwordx4 v219, s[26:27]
	s_add_u32 s26, s6, 0x40100
	s_addc_u32 s27, s7, 0
	s_add_u32 m0, s14, 0x14000
	s_nop 0
	global_load_lds_dwordx4 v209, s[26:27]
	s_nop 0
	s_add_u32 m0, s14, 0x16000
	s_nop 0
	global_load_lds_dwordx4 v219, s[26:27]
	s_nop 0
	s_add_u32 m0, s14, 0
	s_nop 0
	global_load_lds_dwordx4 v1, s[56:57]
	s_nop 0
	s_add_u32 m0, s14, 0x2000
	s_nop 0
	global_load_lds_dwordx4 v213, s[56:57]
	s_waitcnt vmcnt(8)
	s_waitcnt lgkmcnt(0)
	s_barrier
	v_mfma_f32_16x16x32_f16 v[130:133], v[2:5], v[62:65], 0
	s_setprio 1
	v_mfma_f32_16x16x32_f16 v[134:137], v[6:9], v[102:105], v[130:133]
	v_mfma_f32_16x16x32_f16 v[130:133], v[10:13], v[62:65], 0
	v_mfma_f32_16x16x32_f16 v[146:149], v[14:17], v[102:105], v[130:133]
	v_mfma_f32_16x16x32_f16 v[130:133], v[2:5], v[106:109], 0
	v_mfma_f32_16x16x32_f16 v[158:161], v[6:9], v[110:113], v[130:133]
	v_mfma_f32_16x16x32_f16 v[130:133], v[10:13], v[106:109], 0
	v_mfma_f32_16x16x32_f16 v[162:165], v[14:17], v[110:113], v[130:133]
	v_mfma_f32_16x16x32_f16 v[130:133], v[2:5], v[114:117], 0
	v_mfma_f32_16x16x32_f16 v[166:169], v[6:9], v[118:121], v[130:133]
	v_mfma_f32_16x16x32_f16 v[2:5], v[2:5], v[122:125], 0
	v_mfma_f32_16x16x32_f16 v[2:5], v[6:9], v[126:129], v[2:5]
	v_mfma_f32_16x16x32_f16 v[6:9], v[10:13], v[122:125], 0
	v_mfma_f32_16x16x32_f16 v[6:9], v[14:17], v[126:129], v[6:9]
	v_mfma_f32_16x16x32_f16 v[130:133], v[10:13], v[114:117], 0
	v_mfma_f32_16x16x32_f16 v[170:173], v[14:17], v[118:121], v[130:133]
	v_mfma_f32_16x16x32_f16 v[10:13], v[18:21], v[62:65], 0
	v_mfma_f32_16x16x32_f16 v[174:177], v[22:25], v[102:105], v[10:13]
	v_mfma_f32_16x16x32_f16 v[10:13], v[26:29], v[62:65], 0
	v_mfma_f32_16x16x32_f16 v[178:181], v[30:33], v[102:105], v[10:13]
	v_mfma_f32_16x16x32_f16 v[10:13], v[18:21], v[106:109], 0
	v_mfma_f32_16x16x32_f16 v[182:185], v[22:25], v[110:113], v[10:13]
	v_mfma_f32_16x16x32_f16 v[10:13], v[26:29], v[106:109], 0
	v_mfma_f32_16x16x32_f16 v[110:113], v[30:33], v[110:113], v[10:13]
	v_mfma_f32_16x16x32_f16 v[10:13], v[18:21], v[114:117], 0
	v_mfma_f32_16x16x32_f16 v[186:189], v[22:25], v[118:121], v[10:13]
	v_mfma_f32_16x16x32_f16 v[10:13], v[26:29], v[114:117], 0
	v_mfma_f32_16x16x32_f16 v[190:193], v[30:33], v[118:121], v[10:13]
	v_mfma_f32_16x16x32_f16 v[10:13], v[18:21], v[122:125], 0
	v_mfma_f32_16x16x32_f16 v[194:197], v[22:25], v[126:129], v[10:13]
	v_mfma_f32_16x16x32_f16 v[10:13], v[26:29], v[122:125], 0
	v_mfma_f32_16x16x32_f16 v[122:125], v[30:33], v[126:129], v[10:13]
	s_barrier
; #define PG8_STAGE(bufoff, gbase, voff) do { if constexpr (ABL & 1) break; glds16s<(bufoff)>((voff)[0], (const void*)(gbase), ldsbw); glds16s<(bufoff) + 8192>((voff)[1], (const void*)(gbase), ldsbw); } while (0)
; #define PG8_LDA(dst, b, h) do { if constexpr (ABL & 4) break; _Pragma("unroll") for (int m = 0; m < 4; ++m) _Pragma("unroll") for (int k = 0; k < 2; ++k) dst[m][k] = *(const LAS f16x8*)(lds + PG8_SA(b, h) + aoff + m * 2048 + k * 1024); } while (0)
; #define PG8_LDB(dst, b, h) do { if constexpr (ABL & 4) break; _Pragma("unroll") for (int n = 0; n < 2; ++n) _Pragma("unroll") for (int k = 0; k < 2; ++k) dst[n][k] = *(const LAS f16x8*)(lds + PG8_SB(b, h) + boff + n * 2048 + k * 1024); } while (0)
; #define PG8_MMA(ai, bj, At, Bt) do { if constexpr (ABL & 2) break; __builtin_amdgcn_s_setprio(1); _Pragma("unroll") for (int m = 0; m < 4; ++m) _Pragma("unroll") for (int n = 0; n < 2; ++n) _Pragma("unroll") for (int k = 0; k < 2; ++k) \
;         acc[ai][bj][m][n] = __builtin_amdgcn_mfma_f32_16x16x32_f16(Bt[n][k], At[m][k], acc[ai][bj][m][n], 0, 0, 0); __builtin_amdgcn_s_setprio(0); } while (0)
; #define PG8_WAIT_V(n) asm volatile("s_waitcnt vmcnt(" #n ")" ::: "memory")
; #define PG8_WAIT_L(n) asm volatile("s_waitcnt lgkmcnt(" #n ")" ::: "memory")
; #define PG8_BAR __builtin_amdgcn_s_barrier()
; #define PG8_SCHED __builtin_amdgcn_sched_barrier(0)
;     ...
;             PG8_LDB(B0, 1, 0); PG8_LDB(B1, 1, 1); PG8_SCHED; PG8_LDA(At, 1, 0); if (!fin) PG8_STAGE(PG8_SA(0, 1), a2 + hstep, voffA);
;             if (!fin) PG8_WAIT_V(8); else PG8_WAIT_V(0); PG8_WAIT_L(0); PG8_BAR; PG8_MMA(0, 0, At, B0); PG8_MMA(0, 1, At, B1); PG8_BAR; PG8_SCHED;
;             PG8_LDA(At, 1, 1); if (!fin) { PG8_STAGE(PG8_SB(1, 0), b3, voffB); PG8_STAGE(PG8_SB(1, 1), b3 + hstep, voffB); PG8_STAGE(PG8_SA(1, 0), a3, voffA); }
;             if (!fin) PG8_WAIT_V(8); PG8_WAIT_L(0); PG8_BAR; PG8_MMA(1, 0, At, B0); PG8_MMA(1, 1, At, B1); PG8_BAR; PG8_SCHED;
	s_setprio 0
	s_nop 4
	ds_read_b128 v[10:13], v225
	ds_read_b128 v[14:17], v225 offset:1024
	ds_read_b128 v[18:21], v225 offset:2048
	ds_read_b128 v[22:25], v225 offset:3072
	ds_read_b128 v[198:201], v226
	ds_read_b128 v[214:217], v226 offset:1024
	ds_read_b128 v[228:231], v226 offset:2048
	ds_read_b128 v[232:235], v226 offset:3072
	ds_read_b128 v[26:29], v224 offset:32768
	ds_read_b128 v[30:33], v224 offset:33792
	ds_read_b128 v[62:65], v224 offset:34816
	ds_read_b128 v[114:117], v224 offset:35840
	ds_read_b128 v[236:239], v224 offset:36864
	ds_read_b128 v[240:243], v224 offset:37888
	ds_read_b128 v[244:247], v224 offset:38912
	ds_read_b128 v[248:251], v224 offset:39936
	s_add_u32 s26, s30, 0x40100
	s_addc_u32 s27, s31, 0
	s_add_u32 m0, s14, 0x4000
	s_nop 0
	global_load_lds_dwordx4 v1, s[26:27]
	s_nop 0
	s_add_u32 m0, s14, 0x6000
	s_nop 0
	global_load_lds_dwordx4 v213, s[26:27]
	s_waitcnt vmcnt(8)
	s_waitcnt lgkmcnt(0)
	s_barrier
	v_mfma_f32_16x16x32_f16 v[66:69], v[10:13], v[26:29], v[66:69]
	s_setprio 1
	v_mfma_f32_16x16x32_f16 v[154:157], v[14:17], v[30:33], v[66:69]
	v_mfma_f32_16x16x32_f16 v[66:69], v[18:21], v[26:29], v[70:73]
	v_mfma_f32_16x16x32_f16 v[150:153], v[22:25], v[30:33], v[66:69]
	v_mfma_f32_16x16x32_f16 v[66:69], v[10:13], v[62:65], v[74:77]
	v_mfma_f32_16x16x32_f16 v[130:133], v[14:17], v[114:117], v[66:69]
	v_mfma_f32_16x16x32_f16 v[66:69], v[18:21], v[62:65], v[78:81]
	v_mfma_f32_16x16x32_f16 v[126:129], v[22:25], v[114:117], v[66:69]
	v_mfma_f32_16x16x32_f16 v[66:69], v[10:13], v[236:239], v[82:85]
	v_mfma_f32_16x16x32_f16 v[106:109], v[14:17], v[240:243], v[66:69]
	v_mfma_f32_16x16x32_f16 v[66:69], v[18:21], v[236:239], v[86:89]
	v_mfma_f32_16x16x32_f16 v[102:105], v[22:25], v[240:243], v[66:69]
	v_mfma_f32_16x16x32_f16 v[66:69], v[10:13], v[244:247], v[90:93]
	v_mfma_f32_16x16x32_f16 v[82:85], v[14:17], v[248:251], v[66:69]
	v_mfma_f32_16x16x32_f16 v[66:69], v[18:21], v[244:247], v[94:97]
	v_mfma_f32_16x16x32_f16 v[78:81], v[22:25], v[248:251], v[66:69]
	v_mfma_f32_16x16x32_f16 v[66:69], v[198:201], v[26:29], v[98:101]
	v_mfma_f32_16x16x32_f16 v[142:145], v[214:217], v[30:33], v[66:69]
	v_mfma_f32_16x16x32_f16 v[26:29], v[228:231], v[26:29], v[34:37]
	v_mfma_f32_16x16x32_f16 v[138:141], v[232:235], v[30:33], v[26:29]
	v_mfma_f32_16x16x32_f16 v[26:29], v[198:201], v[62:65], v[38:41]
	v_mfma_f32_16x16x32_f16 v[118:121], v[214:217], v[114:117], v[26:29]
	v_mfma_f32_16x16x32_f16 v[26:29], v[228:231], v[62:65], v[42:45]
	v_mfma_f32_16x16x32_f16 v[114:117], v[232:235], v[114:117], v[26:29]
	v_mfma_f32_16x16x32_f16 v[26:29], v[198:201], v[236:239], v[46:49]
	v_mfma_f32_16x16x32_f16 v[94:97], v[214:217], v[240:243], v[26:29]
	v_mfma_f32_16x16x32_f16 v[26:29], v[228:231], v[236:239], v[50:53]
	v_mfma_f32_16x16x32_f16 v[90:93], v[232:235], v[240:243], v[26:29]
	v_mfma_f32_16x16x32_f16 v[26:29], v[198:201], v[244:247], v[54:57]
	v_mfma_f32_16x16x32_f16 v[70:73], v[214:217], v[248:251], v[26:29]
	v_mfma_f32_16x16x32_f16 v[26:29], v[228:231], v[244:247], v[58:61]
	v_mfma_f32_16x16x32_f16 v[66:69], v[232:235], v[248:251], v[26:29]
	s_barrier
	s_setprio 0
	ds_read_b128 v[34:37], v224 offset:49152
	ds_read_b128 v[38:41], v224 offset:50176
	ds_read_b128 v[74:77], v224 offset:51200
	ds_read_b128 v[86:89], v224 offset:52224
	ds_read_b128 v[98:101], v224 offset:53248
	ds_read_b128 v[236:239], v224 offset:54272
	ds_read_b128 v[240:243], v224 offset:55296
	ds_read_b128 v[244:247], v224 offset:56320
	s_add_u32 m0, s14, 0x18000
	s_nop 0
	global_load_lds_dwordx4 v209, s[24:25]
	s_nop 0
	s_add_u32 m0, s14, 0x1a000
	s_nop 0
	global_load_lds_dwordx4 v219, s[24:25]
	s_add_u32 s24, s6, 0x40180
	s_addc_u32 s25, s7, 0
	s_add_u32 m0, s14, 0x1c000
	s_nop 0
	global_load_lds_dwordx4 v209, s[24:25]
	s_nop 0
	s_add_u32 m0, s14, 0x1e000
	s_nop 0
	global_load_lds_dwordx4 v219, s[24:25]
	s_nop 0
	s_add_u32 m0, s14, 0x8000
	s_nop 0
	global_load_lds_dwordx4 v1, s[8:9]
	s_nop 0
	s_add_u32 m0, s14, 0xa000
	s_nop 0
	global_load_lds_dwordx4 v213, s[8:9]
	s_waitcnt vmcnt(8)
	s_waitcnt lgkmcnt(0)
	s_barrier
	v_mfma_f32_16x16x32_f16 v[26:29], v[10:13], v[34:37], v[134:137]
	s_setprio 1
	v_mfma_f32_16x16x32_f16 v[62:65], v[14:17], v[38:41], v[26:29]
	v_mfma_f32_16x16x32_f16 v[26:29], v[22:25], v[38:41], v[146:149]
	v_mfma_f32_16x16x32_f16 v[58:61], v[18:21], v[34:37], v[26:29]
	v_mfma_f32_16x16x32_f16 v[26:29], v[10:13], v[74:77], v[158:161]
	v_mfma_f32_16x16x32_f16 v[46:49], v[14:17], v[86:89], v[26:29]
	v_mfma_f32_16x16x32_f16 v[26:29], v[22:25], v[86:89], v[162:165]
	v_mfma_f32_16x16x32_f16 v[42:45], v[18:21], v[74:77], v[26:29]
	v_mfma_f32_16x16x32_f16 v[26:29], v[10:13], v[98:101], v[166:169]
	v_mfma_f32_16x16x32_f16 v[30:33], v[14:17], v[236:239], v[26:29]
	v_mfma_f32_16x16x32_f16 v[26:29], v[22:25], v[236:239], v[170:173]
	v_mfma_f32_16x16x32_f16 v[26:29], v[18:21], v[98:101], v[26:29]
	v_mfma_f32_16x16x32_f16 v[2:5], v[10:13], v[240:243], v[2:5]
	v_mfma_f32_16x16x32_f16 v[14:17], v[14:17], v[244:247], v[2:5]
	v_mfma_f32_16x16x32_f16 v[2:5], v[22:25], v[244:247], v[6:9]
	v_mfma_f32_16x16x32_f16 v[10:13], v[18:21], v[240:243], v[2:5]
	v_mfma_f32_16x16x32_f16 v[2:5], v[198:201], v[34:37], v[174:177]
	v_mfma_f32_16x16x32_f16 v[54:57], v[214:217], v[38:41], v[2:5]
	v_mfma_f32_16x16x32_f16 v[2:5], v[232:235], v[38:41], v[178:181]
	v_mfma_f32_16x16x32_f16 v[50:53], v[228:231], v[34:37], v[2:5]
	v_mfma_f32_16x16x32_f16 v[2:5], v[198:201], v[74:77], v[182:185]
	v_mfma_f32_16x16x32_f16 v[38:41], v[214:217], v[86:89], v[2:5]
	v_mfma_f32_16x16x32_f16 v[2:5], v[232:235], v[86:89], v[110:113]
	v_mfma_f32_16x16x32_f16 v[34:37], v[228:231], v[74:77], v[2:5]
	v_mfma_f32_16x16x32_f16 v[2:5], v[198:201], v[98:101], v[186:189]
	v_mfma_f32_16x16x32_f16 v[22:25], v[214:217], v[236:239], v[2:5]
	v_mfma_f32_16x16x32_f16 v[2:5], v[232:235], v[236:239], v[190:193]
	v_mfma_f32_16x16x32_f16 v[18:21], v[228:231], v[98:101], v[2:5]
	v_mfma_f32_16x16x32_f16 v[2:5], v[198:201], v[240:243], v[194:197]
	v_mfma_f32_16x16x32_f16 v[6:9], v[214:217], v[244:247], v[2:5]
	v_mfma_f32_16x16x32_f16 v[2:5], v[232:235], v[244:247], v[122:125]
	v_mfma_f32_16x16x32_f16 v[2:5], v[228:231], v[240:243], v[2:5]
	s_barrier
	s_setprio 0
	s_add_u32 s30, s6, 0x200
	s_addc_u32 s31, s7, 0
	s_mov_b32 s59, 0
	s_branch .LBB0_750
; #define PG8_STAGE(bufoff, gbase, voff) do { if constexpr (ABL & 1) break; glds16s<(bufoff)>((voff)[0], (const void*)(gbase), ldsbw); glds16s<(bufoff) + 8192>((voff)[1], (const void*)(gbase), ldsbw); } while (0)
; #define PG8_LDA(dst, b, h) do { if constexpr (ABL & 4) break; _Pragma("unroll") for (int m = 0; m < 4; ++m) _Pragma("unroll") for (int k = 0; k < 2; ++k) dst[m][k] = *(const LAS f16x8*)(lds + PG8_SA(b, h) + aoff + m * 2048 + k * 1024); } while (0)
; #define PG8_LDB(dst, b, h) do { if constexpr (ABL & 4) break; _Pragma("unroll") for (int n = 0; n < 2; ++n) _Pragma("unroll") for (int k = 0; k < 2; ++k) dst[n][k] = *(const LAS f16x8*)(lds + PG8_SB(b, h) + boff + n * 2048 + k * 1024); } while (0)
; #define PG8_MMAF(ai, bj, At, Bt) do { if (t == 0) PG8_MMA0(ai, bj, At, Bt); else PG8_MMA(ai, bj, At, Bt); } while (0)
;     ...
;             const char* a1 = cA + (size_t)(t + 1) * kstep;
;             const char* a2 = last ? nA : cA + (size_t)(t + 2) * kstep; const char* b2 = last ? nB : cB + (size_t)(t + 2) * kstep;
;             const char* a3 = a2 + kstep; const char* b3 = b2 + kstep;
;             if (last && has_next) S.a_ready(nxt);
;             if constexpr (SP2) {
;             PG8_LDB(B0, 0, 0); PG8_LDB(B1, 0, 1); PG8_SCHED; PG8_LDA(At, 0, 0); PG8_STAGE(PG8_SA(1, 1), a1 + hstep, voffA);
;             PG8_WAIT_V(8); PG8_WAIT_L(0); PG8_BAR; PG8_MMAF(0, 0, At, B0); PG8_MMAF(0, 1, At, B1); PG8_BAR; PG8_SCHED;
;             const bool fin = last && !has_next;
;             PG8_LDA(At, 0, 1); if (!fin) { PG8_STAGE(PG8_SB(0, 0), b2, voffB); PG8_STAGE(PG8_SB(0, 1), b2 + hstep, voffB); PG8_STAGE(PG8_SA(0, 0), a2, voffA); }
;             if (!fin) PG8_WAIT_V(8); else PG8_WAIT_V(2); PG8_WAIT_L(0); PG8_BAR; PG8_MMAF(1, 0, At, B0); PG8_MMAF(1, 1, At, B1); PG8_BAR; PG8_SCHED;
;             PG8_LDB(B0, 1, 0); PG8_LDB(B1, 1, 1); PG8_SCHED; PG8_LDA(At, 1, 0); if (!fin) PG8_STAGE(PG8_SA(0, 1), a2 + hstep, voffA);
;             if (!fin) PG8_WAIT_V(8); else PG8_WAIT_V(0); PG8_WAIT_L(0); PG8_BAR; PG8_MMA(0, 0, At, B0); PG8_MMA(0, 1, At, B1); PG8_BAR; PG8_SCHED;
;             PG8_LDA(At, 1, 1); if (!fin) { PG8_STAGE(PG8_SB(1, 0), b3, voffB); PG8_STAGE(PG8_SB(1, 1), b3 + hstep, voffB); PG8_STAGE(PG8_SA(1, 0), a3, voffA); }
;             if (!fin) PG8_WAIT_V(8); PG8_WAIT_L(0); PG8_BAR; PG8_MMA(1, 0, At, B0); PG8_MMA(1, 1, At, B1); PG8_BAR; PG8_SCHED;
.LBB0_749:
	s_waitcnt lgkmcnt(0)
	s_barrier
	v_mfma_f32_16x16x32_f16 v[62:65], v[162:165], v[186:189], v[62:65]
	s_setprio 1
	v_mfma_f32_16x16x32_f16 v[62:65], v[166:169], v[190:193], v[62:65]
	v_mfma_f32_16x16x32_f16 v[46:49], v[166:169], v[182:185], v[46:49]
	v_mfma_f32_16x16x32_f16 v[46:49], v[162:165], v[178:181], v[46:49]
	v_mfma_f32_16x16x32_f16 v[30:33], v[162:165], v[170:173], v[30:33]
	v_mfma_f32_16x16x32_f16 v[30:33], v[166:169], v[174:177], v[30:33]
	v_mfma_f32_16x16x32_f16 v[14:17], v[166:169], v[134:137], v[14:17]
	v_mfma_f32_16x16x32_f16 v[14:17], v[162:165], v[122:125], v[14:17]
	v_mfma_f32_16x16x32_f16 v[10:13], v[146:149], v[122:125], v[10:13]
	v_mfma_f32_16x16x32_f16 v[10:13], v[158:161], v[134:137], v[10:13]
	v_mfma_f32_16x16x32_f16 v[58:61], v[158:161], v[190:193], v[58:61]
	v_mfma_f32_16x16x32_f16 v[58:61], v[146:149], v[186:189], v[58:61]
	v_mfma_f32_16x16x32_f16 v[42:45], v[146:149], v[178:181], v[42:45]
	v_mfma_f32_16x16x32_f16 v[42:45], v[158:161], v[182:185], v[42:45]
	v_mfma_f32_16x16x32_f16 v[26:29], v[158:161], v[174:177], v[26:29]
	v_mfma_f32_16x16x32_f16 v[26:29], v[146:149], v[170:173], v[26:29]
	v_mfma_f32_16x16x32_f16 v[22:25], v[98:101], v[170:173], v[22:25]
	v_mfma_f32_16x16x32_f16 v[22:25], v[110:113], v[174:177], v[22:25]
	v_mfma_f32_16x16x32_f16 v[54:57], v[110:113], v[190:193], v[54:57]
	v_mfma_f32_16x16x32_f16 v[54:57], v[98:101], v[186:189], v[54:57]
	v_mfma_f32_16x16x32_f16 v[38:41], v[98:101], v[178:181], v[38:41]
	v_mfma_f32_16x16x32_f16 v[38:41], v[110:113], v[182:185], v[38:41]
	v_mfma_f32_16x16x32_f16 v[6:9], v[110:113], v[134:137], v[6:9]
	v_mfma_f32_16x16x32_f16 v[6:9], v[98:101], v[122:125], v[6:9]
	v_mfma_f32_16x16x32_f16 v[2:5], v[74:77], v[122:125], v[2:5]
	v_mfma_f32_16x16x32_f16 v[2:5], v[86:89], v[134:137], v[2:5]
	v_mfma_f32_16x16x32_f16 v[50:53], v[86:89], v[190:193], v[50:53]
	v_mfma_f32_16x16x32_f16 v[50:53], v[74:77], v[186:189], v[50:53]
	v_mfma_f32_16x16x32_f16 v[34:37], v[74:77], v[178:181], v[34:37]
	v_mfma_f32_16x16x32_f16 v[34:37], v[86:89], v[182:185], v[34:37]
	v_mfma_f32_16x16x32_f16 v[18:21], v[86:89], v[174:177], v[18:21]
	v_mfma_f32_16x16x32_f16 v[18:21], v[74:77], v[170:173], v[18:21]
	s_barrier
	s_setprio 0
	s_add_i32 s59, s59, 2
	s_add_u32 s30, s30, 0x100
	s_addc_u32 s31, s31, 0
	s_cmp_gt_u32 s59, 13
	s_cbranch_scc1 .LBB0_760
.LBB0_750:
	ds_read_b128 v[146:149], v222
	ds_read_b128 v[158:161], v222 offset:1024
	ds_read_b128 v[162:165], v222 offset:2048
	ds_read_b128 v[166:169], v222 offset:3072
	ds_read_b128 v[74:77], v223
	ds_read_b128 v[86:89], v223 offset:1024
	ds_read_b128 v[98:101], v223 offset:2048
	ds_read_b128 v[110:113], v223 offset:3072
	s_mov_b64 s[6:7], s[56:57]
	s_add_u32 s56, s6, 0x100
	s_addc_u32 s57, s7, 0
	s_cmp_eq_u32 s59, 12
	s_cselect_b64 s[26:27], -1, 0
	s_and_b64 s[8:9], s[26:27], exec
	s_cselect_b32 s25, s47, s57
	s_cselect_b32 s24, s55, s56
	s_cselect_b32 s9, s45, s31
	s_cselect_b32 s8, s58, s30
	ds_read_b128 v[170:173], v224
	ds_read_b128 v[174:177], v224 offset:1024
	ds_read_b128 v[178:181], v224 offset:2048
	ds_read_b128 v[182:185], v224 offset:3072
	ds_read_b128 v[186:189], v224 offset:4096
	ds_read_b128 v[190:193], v224 offset:5120
	ds_read_b128 v[194:197], v224 offset:6144
	ds_read_b128 v[198:201], v224 offset:7168
	s_add_u32 s6, s6, 0x40080
	s_addc_u32 s7, s7, 0
	s_add_u32 m0, s14, 0xc000
	s_nop 0
	global_load_lds_dwordx4 v1, s[6:7]
	s_nop 0
	s_add_u32 m0, s14, 0xe000
	s_nop 0
	global_load_lds_dwordx4 v213, s[6:7]
	s_waitcnt vmcnt(8)
	s_waitcnt lgkmcnt(0)
	s_barrier
	v_mfma_f32_16x16x32_f16 v[122:125], v[146:149], v[170:173], v[154:157]
	s_setprio 1
	v_mfma_f32_16x16x32_f16 v[122:125], v[158:161], v[174:177], v[122:125]
	v_mfma_f32_16x16x32_f16 v[130:133], v[158:161], v[182:185], v[130:133]
	v_mfma_f32_16x16x32_f16 v[130:133], v[146:149], v[178:181], v[130:133]
	v_mfma_f32_16x16x32_f16 v[106:109], v[146:149], v[186:189], v[106:109]
	v_mfma_f32_16x16x32_f16 v[106:109], v[158:161], v[190:193], v[106:109]
	v_mfma_f32_16x16x32_f16 v[82:85], v[158:161], v[198:201], v[82:85]
	v_mfma_f32_16x16x32_f16 v[82:85], v[146:149], v[194:197], v[82:85]
	v_mfma_f32_16x16x32_f16 v[78:81], v[162:165], v[194:197], v[78:81]
	v_mfma_f32_16x16x32_f16 v[78:81], v[166:169], v[198:201], v[78:81]
	v_mfma_f32_16x16x32_f16 v[134:137], v[166:169], v[174:177], v[150:153]
	v_mfma_f32_16x16x32_f16 v[134:137], v[162:165], v[170:173], v[134:137]
	v_mfma_f32_16x16x32_f16 v[126:129], v[162:165], v[178:181], v[126:129]
	v_mfma_f32_16x16x32_f16 v[126:129], v[166:169], v[182:185], v[126:129]
	v_mfma_f32_16x16x32_f16 v[102:105], v[166:169], v[190:193], v[102:105]
	v_mfma_f32_16x16x32_f16 v[102:105], v[162:165], v[186:189], v[102:105]
	v_mfma_f32_16x16x32_f16 v[94:97], v[74:77], v[186:189], v[94:97]
	v_mfma_f32_16x16x32_f16 v[94:97], v[86:89], v[190:193], v[94:97]
	v_mfma_f32_16x16x32_f16 v[142:145], v[86:89], v[174:177], v[142:145]
	v_mfma_f32_16x16x32_f16 v[142:145], v[74:77], v[170:173], v[142:145]
	v_mfma_f32_16x16x32_f16 v[118:121], v[74:77], v[178:181], v[118:121]
	v_mfma_f32_16x16x32_f16 v[118:121], v[86:89], v[182:185], v[118:121]
	v_mfma_f32_16x16x32_f16 v[70:73], v[86:89], v[198:201], v[70:73]
	v_mfma_f32_16x16x32_f16 v[70:73], v[74:77], v[194:197], v[70:73]
	v_mfma_f32_16x16x32_f16 v[66:69], v[98:101], v[194:197], v[66:69]
	v_mfma_f32_16x16x32_f16 v[66:69], v[110:113], v[198:201], v[66:69]
	v_mfma_f32_16x16x32_f16 v[138:141], v[110:113], v[174:177], v[138:141]
	v_mfma_f32_16x16x32_f16 v[138:141], v[98:101], v[170:173], v[138:141]
	v_mfma_f32_16x16x32_f16 v[114:117], v[98:101], v[178:181], v[114:117]
	v_mfma_f32_16x16x32_f16 v[114:117], v[110:113], v[182:185], v[114:117]
	v_mfma_f32_16x16x32_f16 v[90:93], v[110:113], v[190:193], v[90:93]
	v_mfma_f32_16x16x32_f16 v[90:93], v[98:101], v[186:189], v[90:93]
	s_barrier
	s_setprio 0
	ds_read_b128 v[186:189], v224 offset:16384
	ds_read_b128 v[190:193], v224 offset:17408
	ds_read_b128 v[178:181], v224 offset:18432
	ds_read_b128 v[182:185], v224 offset:19456
	ds_read_b128 v[170:173], v224 offset:20480
	ds_read_b128 v[174:177], v224 offset:21504
	ds_read_b128 v[150:153], v224 offset:22528
	ds_read_b128 v[154:157], v224 offset:23552
	s_and_b64 s[6:7], s[4:5], s[26:27]
	s_mov_b64 s[26:27], -1
	s_and_b64 vcc, exec, s[6:7]
	s_cbranch_vccnz .LBB0_752
	s_add_u32 m0, s14, 0x10000
	s_nop 0
	global_load_lds_dwordx4 v209, s[8:9]
	s_nop 0
	s_add_u32 m0, s14, 0x12000
	s_nop 0
	global_load_lds_dwordx4 v219, s[8:9]
	s_add_u32 s26, s8, 0x40000
	s_addc_u32 s27, s9, 0
	s_add_u32 m0, s14, 0x14000
	s_nop 0
	global_load_lds_dwordx4 v209, s[26:27]
	s_nop 0
	s_add_u32 m0, s14, 0x16000
	s_nop 0
	global_load_lds_dwordx4 v219, s[26:27]
	s_mov_b64 s[26:27], 0
	s_add_u32 m0, s14, 0
	s_nop 0
	global_load_lds_dwordx4 v1, s[24:25]
	s_nop 0
	s_add_u32 m0, s14, 0x2000
	s_nop 0
	global_load_lds_dwordx4 v213, s[24:25]
	s_waitcnt vmcnt(8)

; #define PG8_STAGE(bufoff, gbase, voff) do { if constexpr (ABL & 1) break; glds16s<(bufoff)>((voff)[0], (const void*)(gbase), ldsbw); glds16s<(bufoff) + 8192>((voff)[1], (const void*)(gbase), ldsbw); } while (0)
; #define PG8_LDA(dst, b, h) do { if constexpr (ABL & 4) break; _Pragma("unroll") for (int m = 0; m < 4; ++m) _Pragma("unroll") for (int k = 0; k < 2; ++k) dst[m][k] = *(const LAS f16x8*)(lds + PG8_SA(b, h) + aoff + m * 2048 + k * 1024); } while (0)
; #define PG8_LDB(dst, b, h) do { if constexpr (ABL & 4) break; _Pragma("unroll") for (int n = 0; n < 2; ++n) _Pragma("unroll") for (int k = 0; k < 2; ++k) dst[n][k] = *(const LAS f16x8*)(lds + PG8_SB(b, h) + boff + n * 2048 + k * 1024); } while (0)
; #define PG8_MMA(ai, bj, At, Bt) do { if constexpr (ABL & 2) break; __builtin_amdgcn_s_setprio(1); _Pragma("unroll") for (int m = 0; m < 4; ++m) _Pragma("unroll") for (int n = 0; n < 2; ++n) _Pragma("unroll") for (int k = 0; k < 2; ++k) \
;         acc[ai][bj][m][n] = __builtin_amdgcn_mfma_f32_16x16x32_f16(Bt[n][k], At[m][k], acc[ai][bj][m][n], 0, 0, 0); __builtin_amdgcn_s_setprio(0); } while (0)
; #define PG8_MMAF(ai, bj, At, Bt) do { if (t == 0) PG8_MMA0(ai, bj, At, Bt); else PG8_MMA(ai, bj, At, Bt); } while (0)
; #define PG8_WAIT_V(n) asm volatile("s_waitcnt vmcnt(" #n ")" ::: "memory")
; #define PG8_WAIT_L(n) asm volatile("s_waitcnt lgkmcnt(" #n ")" ::: "memory")
; #define PG8_BAR __builtin_amdgcn_s_barrier()
; #define PG8_SCHED __builtin_amdgcn_sched_barrier(0)
;     ...
;             const bool fin = last && !has_next;
;             PG8_LDA(At, 0, 1); if (!fin) { PG8_STAGE(PG8_SB(0, 0), b2, voffB); PG8_STAGE(PG8_SB(0, 1), b2 + hstep, voffB); PG8_STAGE(PG8_SA(0, 0), a2, voffA); }
;             if (!fin) PG8_WAIT_V(8); else PG8_WAIT_V(2); PG8_WAIT_L(0); PG8_BAR; PG8_MMAF(1, 0, At, B0); PG8_MMAF(1, 1, At, B1); PG8_BAR; PG8_SCHED;
;             PG8_LDB(B0, 1, 0); PG8_LDB(B1, 1, 1); PG8_SCHED; PG8_LDA(At, 1, 0); if (!fin) PG8_STAGE(PG8_SA(0, 1), a2 + hstep, voffA);
;             if (!fin) PG8_WAIT_V(8); else PG8_WAIT_V(0); PG8_WAIT_L(0); PG8_BAR; PG8_MMA(0, 0, At, B0); PG8_MMA(0, 1, At, B1); PG8_BAR; PG8_SCHED;
.LBB0_754:
	s_waitcnt lgkmcnt(0)
	s_xor_b64 s[26:27], s[6:7], -1
	s_barrier
	v_mfma_f32_16x16x32_f16 v[62:65], v[146:149], v[186:189], v[62:65]
	s_setprio 1
	v_mfma_f32_16x16x32_f16 v[62:65], v[158:161], v[190:193], v[62:65]
	v_mfma_f32_16x16x32_f16 v[46:49], v[158:161], v[182:185], v[46:49]
	v_mfma_f32_16x16x32_f16 v[46:49], v[146:149], v[178:181], v[46:49]
	v_mfma_f32_16x16x32_f16 v[30:33], v[146:149], v[170:173], v[30:33]
	v_mfma_f32_16x16x32_f16 v[30:33], v[158:161], v[174:177], v[30:33]
	v_mfma_f32_16x16x32_f16 v[14:17], v[158:161], v[154:157], v[14:17]
	v_mfma_f32_16x16x32_f16 v[14:17], v[146:149], v[150:153], v[14:17]
	v_mfma_f32_16x16x32_f16 v[10:13], v[162:165], v[150:153], v[10:13]
	v_mfma_f32_16x16x32_f16 v[10:13], v[166:169], v[154:157], v[10:13]
	v_mfma_f32_16x16x32_f16 v[58:61], v[166:169], v[190:193], v[58:61]
	v_mfma_f32_16x16x32_f16 v[58:61], v[162:165], v[186:189], v[58:61]
	v_mfma_f32_16x16x32_f16 v[42:45], v[162:165], v[178:181], v[42:45]
	v_mfma_f32_16x16x32_f16 v[42:45], v[166:169], v[182:185], v[42:45]
	v_mfma_f32_16x16x32_f16 v[26:29], v[166:169], v[174:177], v[26:29]
	v_mfma_f32_16x16x32_f16 v[26:29], v[162:165], v[170:173], v[26:29]
	v_mfma_f32_16x16x32_f16 v[22:25], v[74:77], v[170:173], v[22:25]
	v_mfma_f32_16x16x32_f16 v[22:25], v[86:89], v[174:177], v[22:25]
	v_mfma_f32_16x16x32_f16 v[54:57], v[86:89], v[190:193], v[54:57]
	v_mfma_f32_16x16x32_f16 v[54:57], v[74:77], v[186:189], v[54:57]
	v_mfma_f32_16x16x32_f16 v[38:41], v[74:77], v[178:181], v[38:41]
	v_mfma_f32_16x16x32_f16 v[38:41], v[86:89], v[182:185], v[38:41]
	v_mfma_f32_16x16x32_f16 v[6:9], v[86:89], v[154:157], v[6:9]
	v_mfma_f32_16x16x32_f16 v[6:9], v[74:77], v[150:153], v[6:9]
	v_mfma_f32_16x16x32_f16 v[2:5], v[98:101], v[150:153], v[2:5]
	v_mfma_f32_16x16x32_f16 v[2:5], v[110:113], v[154:157], v[2:5]
	v_mfma_f32_16x16x32_f16 v[50:53], v[110:113], v[190:193], v[50:53]
	v_mfma_f32_16x16x32_f16 v[50:53], v[98:101], v[186:189], v[50:53]
	v_mfma_f32_16x16x32_f16 v[34:37], v[98:101], v[178:181], v[34:37]
	v_mfma_f32_16x16x32_f16 v[34:37], v[110:113], v[182:185], v[34:37]
	v_mfma_f32_16x16x32_f16 v[18:21], v[110:113], v[174:177], v[18:21]
	v_mfma_f32_16x16x32_f16 v[18:21], v[98:101], v[170:173], v[18:21]
	s_barrier
	s_setprio 0
	ds_read_b128 v[162:165], v225
	ds_read_b128 v[166:169], v225 offset:1024
	ds_read_b128 v[146:149], v225 offset:2048
	ds_read_b128 v[158:161], v225 offset:3072
	ds_read_b128 v[98:101], v226
	ds_read_b128 v[110:113], v226 offset:1024
	ds_read_b128 v[74:77], v226 offset:2048
	ds_read_b128 v[86:89], v226 offset:3072
	ds_read_b128 v[194:197], v224 offset:32768
	ds_read_b128 v[198:201], v224 offset:33792
	ds_read_b128 v[186:189], v224 offset:34816
	ds_read_b128 v[190:193], v224 offset:35840
	ds_read_b128 v[178:181], v224 offset:36864
	ds_read_b128 v[182:185], v224 offset:37888
	ds_read_b128 v[170:173], v224 offset:38912
	ds_read_b128 v[174:177], v224 offset:39936
	v_cndmask_b32_e64 v150, 0, 1, s[26:27]
	v_cmp_ne_u32_e64 s[6:7], 1, v150
	s_andn2_b64 vcc, exec, s[26:27]
	s_mov_b64 s[26:27], -1
	s_cbranch_vccnz .LBB0_756
	s_add_u32 s26, s24, 0x40000
	s_addc_u32 s27, s25, 0
	s_add_u32 m0, s14, 0x4000
	s_nop 0
	global_load_lds_dwordx4 v1, s[26:27]
	s_nop 0
	s_add_u32 m0, s14, 0x6000
	s_nop 0
	global_load_lds_dwordx4 v213, s[26:27]
	s_waitcnt vmcnt(8)
	s_mov_b64 s[26:27], 0

; #define PG8_STAGE(bufoff, gbase, voff) do { if constexpr (ABL & 1) break; glds16s<(bufoff)>((voff)[0], (const void*)(gbase), ldsbw); glds16s<(bufoff) + 8192>((voff)[1], (const void*)(gbase), ldsbw); } while (0)
; #define PG8_LDA(dst, b, h) do { if constexpr (ABL & 4) break; _Pragma("unroll") for (int m = 0; m < 4; ++m) _Pragma("unroll") for (int k = 0; k < 2; ++k) dst[m][k] = *(const LAS f16x8*)(lds + PG8_SA(b, h) + aoff + m * 2048 + k * 1024); } while (0)
; #define PG8_LDB(dst, b, h) do { if constexpr (ABL & 4) break; _Pragma("unroll") for (int n = 0; n < 2; ++n) _Pragma("unroll") for (int k = 0; k < 2; ++k) dst[n][k] = *(const LAS f16x8*)(lds + PG8_SB(b, h) + boff + n * 2048 + k * 1024); } while (0)
; #define PG8_MMAF(ai, bj, At, Bt) do { if (t == 0) PG8_MMA0(ai, bj, At, Bt); else PG8_MMA(ai, bj, At, Bt); } while (0)
; #define PG8_WAIT_V(n) asm volatile("s_waitcnt vmcnt(" #n ")" ::: "memory")
; #define PG8_WAIT_L(n) asm volatile("s_waitcnt lgkmcnt(" #n ")" ::: "memory")
; #define PG8_BAR __builtin_amdgcn_s_barrier()
; #define PG8_SCHED __builtin_amdgcn_sched_barrier(0)
;     ...
;             PG8_LDB(B0, 0, 0); PG8_LDB(B1, 0, 1); PG8_SCHED; PG8_LDA(At, 0, 0); PG8_STAGE(PG8_SA(1, 1), a1 + hstep, voffA);
;             PG8_WAIT_V(8); PG8_WAIT_L(0); PG8_BAR; PG8_MMAF(0, 0, At, B0); PG8_MMAF(0, 1, At, B1); PG8_BAR; PG8_SCHED;
;             const bool fin = last && !has_next;
;             PG8_LDA(At, 0, 1); if (!fin) { PG8_STAGE(PG8_SB(0, 0), b2, voffB); PG8_STAGE(PG8_SB(0, 1), b2 + hstep, voffB); PG8_STAGE(PG8_SA(0, 0), a2, voffA); }
;             if (!fin) PG8_WAIT_V(8); else PG8_WAIT_V(2); PG8_WAIT_L(0); PG8_BAR; PG8_MMAF(1, 0, At, B0); PG8_MMAF(1, 1, At, B1); PG8_BAR; PG8_SCHED;
.LBB0_841:
	s_ashr_i32 s41, s40, 31
	s_lshl_b64 s[24:25], s[40:41], 19
	s_add_u32 s42, s74, s24
	s_addc_u32 s43, s75, s25
	s_and_b64 s[24:25], exec, s[4:5]
	ds_read_b128 v[2:5], v210
	ds_read_b128 v[6:9], v210 offset:1024
	ds_read_b128 v[10:13], v210 offset:2048
	ds_read_b128 v[14:17], v210 offset:3072
	ds_read_b128 v[18:21], v211
	ds_read_b128 v[22:25], v211 offset:1024
	ds_read_b128 v[26:29], v211 offset:2048
	ds_read_b128 v[30:33], v211 offset:3072
	s_cselect_b32 s41, s9, s43
	s_cselect_b32 s51, s8, s42
	s_ashr_i32 s39, s38, 31
	s_lshl_b64 s[24:25], s[38:39], 19
	s_add_u32 s44, s58, s24
	s_addc_u32 s45, s59, s25
	s_and_b64 s[24:25], exec, s[4:5]
	s_cselect_b32 s39, s7, s45
	s_cselect_b32 s52, s6, s44
	s_add_u32 s48, s8, 0x100
	s_addc_u32 s49, s9, 0
	s_add_u32 s54, s6, 0x100
	s_addc_u32 s55, s7, 0
	s_add_u32 s24, s8, 0x180
	s_addc_u32 s25, s9, 0
	ds_read_b128 v[34:37], v212
	ds_read_b128 v[38:41], v212 offset:1024
	ds_read_b128 v[42:45], v212 offset:2048
	ds_read_b128 v[46:49], v212 offset:3072
	ds_read_b128 v[50:53], v212 offset:4096
	ds_read_b128 v[54:57], v212 offset:5120
	ds_read_b128 v[58:61], v212 offset:6144
	ds_read_b128 v[62:65], v212 offset:7168
	s_add_u32 s26, s6, 0x180
	s_addc_u32 s27, s7, 0
	s_add_u32 s56, s8, 0x40080
	s_addc_u32 s57, s9, 0
	s_add_u32 m0, s14, 0xc000
	s_nop 0
	global_load_lds_dwordx4 v206, s[56:57]
	s_nop 0
	s_add_u32 m0, s14, 0xe000
	s_nop 0
	global_load_lds_dwordx4 v208, s[56:57]
	s_waitcnt vmcnt(8)
	s_waitcnt lgkmcnt(0)
	s_barrier
	v_mfma_f32_16x16x32_f16 v[90:93], v[2:5], v[58:61], 0
	s_setprio 1
	v_mfma_f32_16x16x32_f16 v[94:97], v[6:9], v[62:65], v[90:93]
	v_mfma_f32_16x16x32_f16 v[66:69], v[2:5], v[34:37], 0
	v_mfma_f32_16x16x32_f16 v[66:69], v[6:9], v[38:41], v[66:69]
	v_mfma_f32_16x16x32_f16 v[70:73], v[10:13], v[34:37], 0
	v_mfma_f32_16x16x32_f16 v[70:73], v[14:17], v[38:41], v[70:73]
	v_mfma_f32_16x16x32_f16 v[74:77], v[2:5], v[42:45], 0
	v_mfma_f32_16x16x32_f16 v[74:77], v[6:9], v[46:49], v[74:77]
	v_mfma_f32_16x16x32_f16 v[78:81], v[10:13], v[42:45], 0
	v_mfma_f32_16x16x32_f16 v[78:81], v[14:17], v[46:49], v[78:81]
	v_mfma_f32_16x16x32_f16 v[82:85], v[2:5], v[50:53], 0
	v_mfma_f32_16x16x32_f16 v[82:85], v[6:9], v[54:57], v[82:85]
	v_mfma_f32_16x16x32_f16 v[86:89], v[10:13], v[50:53], 0
	v_mfma_f32_16x16x32_f16 v[86:89], v[14:17], v[54:57], v[86:89]
	v_mfma_f32_16x16x32_f16 v[90:93], v[10:13], v[58:61], 0
	v_mfma_f32_16x16x32_f16 v[102:105], v[14:17], v[62:65], v[90:93]
	v_mfma_f32_16x16x32_f16 v[90:93], v[18:21], v[34:37], 0
	v_mfma_f32_16x16x32_f16 v[118:121], v[22:25], v[38:41], v[90:93]
	v_mfma_f32_16x16x32_f16 v[34:37], v[26:29], v[34:37], 0
	v_mfma_f32_16x16x32_f16 v[34:37], v[30:33], v[38:41], v[34:37]
	v_mfma_f32_16x16x32_f16 v[38:41], v[18:21], v[42:45], 0
	v_mfma_f32_16x16x32_f16 v[38:41], v[22:25], v[46:49], v[38:41]
	v_mfma_f32_16x16x32_f16 v[42:45], v[26:29], v[42:45], 0
	v_mfma_f32_16x16x32_f16 v[42:45], v[30:33], v[46:49], v[42:45]
	v_mfma_f32_16x16x32_f16 v[46:49], v[18:21], v[50:53], 0
	v_mfma_f32_16x16x32_f16 v[46:49], v[22:25], v[54:57], v[46:49]
	v_mfma_f32_16x16x32_f16 v[50:53], v[26:29], v[50:53], 0
	v_mfma_f32_16x16x32_f16 v[50:53], v[30:33], v[54:57], v[50:53]
	v_mfma_f32_16x16x32_f16 v[54:57], v[18:21], v[58:61], 0
	v_mfma_f32_16x16x32_f16 v[54:57], v[22:25], v[62:65], v[54:57]
	v_mfma_f32_16x16x32_f16 v[58:61], v[26:29], v[58:61], 0
	v_mfma_f32_16x16x32_f16 v[58:61], v[30:33], v[62:65], v[58:61]
	s_barrier
	s_setprio 0
	ds_read_b128 v[62:65], v212 offset:16384
	ds_read_b128 v[90:93], v212 offset:17408
	ds_read_b128 v[98:101], v212 offset:18432
	ds_read_b128 v[106:109], v212 offset:19456
	ds_read_b128 v[110:113], v212 offset:20480
	ds_read_b128 v[114:117], v212 offset:21504
	ds_read_b128 v[122:125], v212 offset:22528
	ds_read_b128 v[126:129], v212 offset:23552
	s_add_u32 m0, s14, 0x10000
	s_nop 0
	global_load_lds_dwordx4 v207, s[54:55]
	s_nop 0
	s_add_u32 m0, s14, 0x12000
	s_nop 0
	global_load_lds_dwordx4 v209, s[54:55]
	s_add_u32 s54, s6, 0x40100
	s_addc_u32 s55, s7, 0
	s_add_u32 m0, s14, 0x14000
	s_nop 0
	global_load_lds_dwordx4 v207, s[54:55]
	s_nop 0
	s_add_u32 m0, s14, 0x16000
	s_nop 0
	global_load_lds_dwordx4 v209, s[54:55]
	s_nop 0
	s_add_u32 m0, s14, 0
	s_nop 0
	global_load_lds_dwordx4 v206, s[48:49]
	s_nop 0
	s_add_u32 m0, s14, 0x2000
	s_nop 0
	global_load_lds_dwordx4 v208, s[48:49]
	s_waitcnt vmcnt(8)
	s_waitcnt lgkmcnt(0)
	s_barrier
	v_mfma_f32_16x16x32_f16 v[130:133], v[2:5], v[62:65], 0
	s_setprio 1
	v_mfma_f32_16x16x32_f16 v[130:133], v[6:9], v[90:93], v[130:133]
	v_mfma_f32_16x16x32_f16 v[138:141], v[2:5], v[98:101], 0
	v_mfma_f32_16x16x32_f16 v[138:141], v[6:9], v[106:109], v[138:141]
	v_mfma_f32_16x16x32_f16 v[146:149], v[2:5], v[110:113], 0
	v_mfma_f32_16x16x32_f16 v[146:149], v[6:9], v[114:117], v[146:149]
	v_mfma_f32_16x16x32_f16 v[2:5], v[2:5], v[122:125], 0
	v_mfma_f32_16x16x32_f16 v[2:5], v[6:9], v[126:129], v[2:5]
	v_mfma_f32_16x16x32_f16 v[6:9], v[10:13], v[122:125], 0
	v_mfma_f32_16x16x32_f16 v[6:9], v[14:17], v[126:129], v[6:9]
	v_mfma_f32_16x16x32_f16 v[134:137], v[10:13], v[62:65], 0
	v_mfma_f32_16x16x32_f16 v[134:137], v[14:17], v[90:93], v[134:137]
	v_mfma_f32_16x16x32_f16 v[142:145], v[10:13], v[98:101], 0
	v_mfma_f32_16x16x32_f16 v[142:145], v[14:17], v[106:109], v[142:145]
	v_mfma_f32_16x16x32_f16 v[150:153], v[10:13], v[110:113], 0
	v_mfma_f32_16x16x32_f16 v[150:153], v[14:17], v[114:117], v[150:153]
	v_mfma_f32_16x16x32_f16 v[10:13], v[18:21], v[62:65], 0
	v_mfma_f32_16x16x32_f16 v[14:17], v[22:25], v[90:93], v[10:13]
	v_mfma_f32_16x16x32_f16 v[10:13], v[26:29], v[62:65], 0
	v_mfma_f32_16x16x32_f16 v[154:157], v[30:33], v[90:93], v[10:13]
	v_mfma_f32_16x16x32_f16 v[10:13], v[18:21], v[98:101], 0
	v_mfma_f32_16x16x32_f16 v[158:161], v[22:25], v[106:109], v[10:13]
	v_mfma_f32_16x16x32_f16 v[10:13], v[26:29], v[98:101], 0
	v_mfma_f32_16x16x32_f16 v[162:165], v[30:33], v[106:109], v[10:13]
	v_mfma_f32_16x16x32_f16 v[10:13], v[18:21], v[110:113], 0
	v_mfma_f32_16x16x32_f16 v[166:169], v[22:25], v[114:117], v[10:13]
	v_mfma_f32_16x16x32_f16 v[10:13], v[26:29], v[110:113], 0
	v_mfma_f32_16x16x32_f16 v[170:173], v[30:33], v[114:117], v[10:13]
	v_mfma_f32_16x16x32_f16 v[10:13], v[18:21], v[122:125], 0
	v_mfma_f32_16x16x32_f16 v[174:177], v[22:25], v[126:129], v[10:13]
	v_mfma_f32_16x16x32_f16 v[10:13], v[26:29], v[122:125], 0
	v_mfma_f32_16x16x32_f16 v[178:181], v[30:33], v[126:129], v[10:13]
	s_barrier
; #define PG8_STAGE(bufoff, gbase, voff) do { if constexpr (ABL & 1) break; glds16s<(bufoff)>((voff)[0], (const void*)(gbase), ldsbw); glds16s<(bufoff) + 8192>((voff)[1], (const void*)(gbase), ldsbw); } while (0)
; #define PG8_LDA(dst, b, h) do { if constexpr (ABL & 4) break; _Pragma("unroll") for (int m = 0; m < 4; ++m) _Pragma("unroll") for (int k = 0; k < 2; ++k) dst[m][k] = *(const LAS f16x8*)(lds + PG8_SA(b, h) + aoff + m * 2048 + k * 1024); } while (0)
; #define PG8_LDB(dst, b, h) do { if constexpr (ABL & 4) break; _Pragma("unroll") for (int n = 0; n < 2; ++n) _Pragma("unroll") for (int k = 0; k < 2; ++k) dst[n][k] = *(const LAS f16x8*)(lds + PG8_SB(b, h) + boff + n * 2048 + k * 1024); } while (0)
; #define PG8_MMA(ai, bj, At, Bt) do { if constexpr (ABL & 2) break; __builtin_amdgcn_s_setprio(1); _Pragma("unroll") for (int m = 0; m < 4; ++m) _Pragma("unroll") for (int n = 0; n < 2; ++n) _Pragma("unroll") for (int k = 0; k < 2; ++k) \
;         acc[ai][bj][m][n] = __builtin_amdgcn_mfma_f32_16x16x32_f16(Bt[n][k], At[m][k], acc[ai][bj][m][n], 0, 0, 0); __builtin_amdgcn_s_setprio(0); } while (0)
; #define PG8_WAIT_V(n) asm volatile("s_waitcnt vmcnt(" #n ")" ::: "memory")
; #define PG8_WAIT_L(n) asm volatile("s_waitcnt lgkmcnt(" #n ")" ::: "memory")
; #define PG8_BAR __builtin_amdgcn_s_barrier()
; #define PG8_SCHED __builtin_amdgcn_sched_barrier(0)
;     ...
;             PG8_LDB(B0, 1, 0); PG8_LDB(B1, 1, 1); PG8_SCHED; PG8_LDA(At, 1, 0); if (!fin) PG8_STAGE(PG8_SA(0, 1), a2 + hstep, voffA);
;             if (!fin) PG8_WAIT_V(8); else PG8_WAIT_V(0); PG8_WAIT_L(0); PG8_BAR; PG8_MMA(0, 0, At, B0); PG8_MMA(0, 1, At, B1); PG8_BAR; PG8_SCHED;
;             PG8_LDA(At, 1, 1); if (!fin) { PG8_STAGE(PG8_SB(1, 0), b3, voffB); PG8_STAGE(PG8_SB(1, 1), b3 + hstep, voffB); PG8_STAGE(PG8_SA(1, 0), a3, voffA); }
;             if (!fin) PG8_WAIT_V(8); PG8_WAIT_L(0); PG8_BAR; PG8_MMA(1, 0, At, B0); PG8_MMA(1, 1, At, B1); PG8_BAR; PG8_SCHED;
	s_setprio 0
	s_nop 4
	ds_read_b128 v[10:13], v213
	ds_read_b128 v[22:25], v213 offset:1024
	ds_read_b128 v[30:33], v213 offset:2048
	ds_read_b128 v[182:185], v213 offset:3072
	ds_read_b128 v[186:189], v214
	ds_read_b128 v[190:193], v214 offset:1024
	ds_read_b128 v[216:219], v214 offset:2048
	ds_read_b128 v[220:223], v214 offset:3072
	ds_read_b128 v[18:21], v212 offset:32768
	ds_read_b128 v[26:29], v212 offset:33792
	ds_read_b128 v[224:227], v212 offset:34816
	ds_read_b128 v[228:231], v212 offset:35840
	ds_read_b128 v[232:235], v212 offset:36864
	ds_read_b128 v[236:239], v212 offset:37888
	ds_read_b128 v[240:243], v212 offset:38912
	ds_read_b128 v[244:247], v212 offset:39936
	s_add_u32 s8, s8, 0x40100
	s_addc_u32 s9, s9, 0
	s_add_u32 m0, s14, 0x4000
	s_nop 0
	global_load_lds_dwordx4 v206, s[8:9]
	s_nop 0
	s_add_u32 m0, s14, 0x6000
	s_nop 0
	global_load_lds_dwordx4 v208, s[8:9]
	s_waitcnt vmcnt(8)
	s_waitcnt lgkmcnt(0)
	s_barrier
	v_mfma_f32_16x16x32_f16 v[62:65], v[10:13], v[18:21], v[66:69]
	s_setprio 1
	v_mfma_f32_16x16x32_f16 v[114:117], v[22:25], v[26:29], v[62:65]
	v_mfma_f32_16x16x32_f16 v[62:65], v[30:33], v[18:21], v[70:73]
	v_mfma_f32_16x16x32_f16 v[110:113], v[182:185], v[26:29], v[62:65]
	v_mfma_f32_16x16x32_f16 v[62:65], v[10:13], v[224:227], v[74:77]
	v_mfma_f32_16x16x32_f16 v[106:109], v[22:25], v[228:231], v[62:65]
	v_mfma_f32_16x16x32_f16 v[62:65], v[30:33], v[224:227], v[78:81]
	v_mfma_f32_16x16x32_f16 v[98:101], v[182:185], v[228:231], v[62:65]
	v_mfma_f32_16x16x32_f16 v[62:65], v[10:13], v[232:235], v[82:85]
	v_mfma_f32_16x16x32_f16 v[90:93], v[22:25], v[236:239], v[62:65]
	v_mfma_f32_16x16x32_f16 v[62:65], v[30:33], v[232:235], v[86:89]
	v_mfma_f32_16x16x32_f16 v[82:85], v[182:185], v[236:239], v[62:65]
	v_mfma_f32_16x16x32_f16 v[62:65], v[10:13], v[240:243], v[94:97]
	v_mfma_f32_16x16x32_f16 v[74:77], v[22:25], v[244:247], v[62:65]
	v_mfma_f32_16x16x32_f16 v[62:65], v[30:33], v[240:243], v[102:105]
	v_mfma_f32_16x16x32_f16 v[62:65], v[182:185], v[244:247], v[62:65]
	v_mfma_f32_16x16x32_f16 v[66:69], v[186:189], v[18:21], v[118:121]
	v_mfma_f32_16x16x32_f16 v[126:129], v[190:193], v[26:29], v[66:69]
	v_mfma_f32_16x16x32_f16 v[18:21], v[216:219], v[18:21], v[34:37]
	v_mfma_f32_16x16x32_f16 v[122:125], v[220:223], v[26:29], v[18:21]
	v_mfma_f32_16x16x32_f16 v[18:21], v[186:189], v[224:227], v[38:41]
	v_mfma_f32_16x16x32_f16 v[118:121], v[190:193], v[228:231], v[18:21]
	v_mfma_f32_16x16x32_f16 v[18:21], v[216:219], v[224:227], v[42:45]
	v_mfma_f32_16x16x32_f16 v[102:105], v[220:223], v[228:231], v[18:21]
	v_mfma_f32_16x16x32_f16 v[18:21], v[186:189], v[232:235], v[46:49]
	v_mfma_f32_16x16x32_f16 v[94:97], v[190:193], v[236:239], v[18:21]
	v_mfma_f32_16x16x32_f16 v[18:21], v[216:219], v[232:235], v[50:53]
	v_mfma_f32_16x16x32_f16 v[86:89], v[220:223], v[236:239], v[18:21]
	v_mfma_f32_16x16x32_f16 v[18:21], v[186:189], v[240:243], v[54:57]
	v_mfma_f32_16x16x32_f16 v[78:81], v[190:193], v[244:247], v[18:21]
	v_mfma_f32_16x16x32_f16 v[18:21], v[216:219], v[240:243], v[58:61]
	v_mfma_f32_16x16x32_f16 v[70:73], v[220:223], v[244:247], v[18:21]
	s_barrier
	s_setprio 0
	ds_read_b128 v[38:41], v212 offset:49152
	ds_read_b128 v[46:49], v212 offset:50176
	ds_read_b128 v[224:227], v212 offset:51200
	ds_read_b128 v[228:231], v212 offset:52224
	ds_read_b128 v[232:235], v212 offset:53248
	ds_read_b128 v[236:239], v212 offset:54272
	ds_read_b128 v[240:243], v212 offset:55296
	ds_read_b128 v[244:247], v212 offset:56320
	s_add_u32 m0, s14, 0x18000
	s_nop 0
	global_load_lds_dwordx4 v207, s[26:27]
	s_nop 0
	s_add_u32 m0, s14, 0x1a000
	s_nop 0
	global_load_lds_dwordx4 v209, s[26:27]
	s_add_u32 s8, s6, 0x40180
	s_addc_u32 s9, s7, 0
	s_add_u32 m0, s14, 0x1c000
	s_nop 0
	global_load_lds_dwordx4 v207, s[8:9]
	s_nop 0
	s_add_u32 m0, s14, 0x1e000
	s_nop 0
	global_load_lds_dwordx4 v209, s[8:9]
	s_nop 0
	s_add_u32 m0, s14, 0x8000
	s_nop 0
	global_load_lds_dwordx4 v206, s[24:25]
	s_nop 0
	s_add_u32 m0, s14, 0xa000
	s_nop 0
	global_load_lds_dwordx4 v208, s[24:25]
	s_waitcnt vmcnt(8)
	s_waitcnt lgkmcnt(0)
	s_barrier
	v_mfma_f32_16x16x32_f16 v[18:21], v[10:13], v[38:41], v[130:133]
	s_setprio 1
	v_mfma_f32_16x16x32_f16 v[58:61], v[22:25], v[46:49], v[18:21]
	v_mfma_f32_16x16x32_f16 v[18:21], v[182:185], v[46:49], v[134:137]
	v_mfma_f32_16x16x32_f16 v[50:53], v[30:33], v[38:41], v[18:21]
	v_mfma_f32_16x16x32_f16 v[18:21], v[10:13], v[224:227], v[138:141]
	v_mfma_f32_16x16x32_f16 v[42:45], v[22:25], v[228:231], v[18:21]
	v_mfma_f32_16x16x32_f16 v[18:21], v[182:185], v[228:231], v[142:145]
	v_mfma_f32_16x16x32_f16 v[34:37], v[30:33], v[224:227], v[18:21]
	v_mfma_f32_16x16x32_f16 v[18:21], v[10:13], v[232:235], v[146:149]
	v_mfma_f32_16x16x32_f16 v[26:29], v[22:25], v[236:239], v[18:21]
	v_mfma_f32_16x16x32_f16 v[18:21], v[182:185], v[236:239], v[150:153]
	v_mfma_f32_16x16x32_f16 v[18:21], v[30:33], v[232:235], v[18:21]
	v_mfma_f32_16x16x32_f16 v[2:5], v[10:13], v[240:243], v[2:5]
	v_mfma_f32_16x16x32_f16 v[10:13], v[22:25], v[244:247], v[2:5]
	v_mfma_f32_16x16x32_f16 v[2:5], v[182:185], v[244:247], v[6:9]
	v_mfma_f32_16x16x32_f16 v[2:5], v[30:33], v[240:243], v[2:5]
	v_mfma_f32_16x16x32_f16 v[6:9], v[186:189], v[38:41], v[14:17]
	v_mfma_f32_16x16x32_f16 v[66:69], v[190:193], v[46:49], v[6:9]
	v_mfma_f32_16x16x32_f16 v[6:9], v[220:223], v[46:49], v[154:157]
	v_mfma_f32_16x16x32_f16 v[54:57], v[216:219], v[38:41], v[6:9]
	v_mfma_f32_16x16x32_f16 v[6:9], v[186:189], v[224:227], v[158:161]
	v_mfma_f32_16x16x32_f16 v[46:49], v[190:193], v[228:231], v[6:9]
	v_mfma_f32_16x16x32_f16 v[6:9], v[220:223], v[228:231], v[162:165]
	v_mfma_f32_16x16x32_f16 v[38:41], v[216:219], v[224:227], v[6:9]
	v_mfma_f32_16x16x32_f16 v[6:9], v[186:189], v[232:235], v[166:169]
	v_mfma_f32_16x16x32_f16 v[30:33], v[190:193], v[236:239], v[6:9]
	v_mfma_f32_16x16x32_f16 v[6:9], v[220:223], v[236:239], v[170:173]
	v_mfma_f32_16x16x32_f16 v[22:25], v[216:219], v[232:235], v[6:9]
	v_mfma_f32_16x16x32_f16 v[6:9], v[186:189], v[240:243], v[174:177]
	v_mfma_f32_16x16x32_f16 v[14:17], v[190:193], v[244:247], v[6:9]
	v_mfma_f32_16x16x32_f16 v[6:9], v[220:223], v[244:247], v[178:181]
	v_mfma_f32_16x16x32_f16 v[6:9], v[216:219], v[240:243], v[6:9]
	s_barrier
	s_setprio 0
	s_add_u32 s53, s6, 0x200
	s_addc_u32 s54, s7, 0
	s_mov_b32 s55, 0
	s_branch .LBB0_843
; #define PG8_STAGE(bufoff, gbase, voff) do { if constexpr (ABL & 1) break; glds16s<(bufoff)>((voff)[0], (const void*)(gbase), ldsbw); glds16s<(bufoff) + 8192>((voff)[1], (const void*)(gbase), ldsbw); } while (0)
; #define PG8_LDA(dst, b, h) do { if constexpr (ABL & 4) break; _Pragma("unroll") for (int m = 0; m < 4; ++m) _Pragma("unroll") for (int k = 0; k < 2; ++k) dst[m][k] = *(const LAS f16x8*)(lds + PG8_SA(b, h) + aoff + m * 2048 + k * 1024); } while (0)
; #define PG8_LDB(dst, b, h) do { if constexpr (ABL & 4) break; _Pragma("unroll") for (int n = 0; n < 2; ++n) _Pragma("unroll") for (int k = 0; k < 2; ++k) dst[n][k] = *(const LAS f16x8*)(lds + PG8_SB(b, h) + boff + n * 2048 + k * 1024); } while (0)
; #define PG8_BAR __builtin_amdgcn_s_barrier()
;     ...
;         for (int t = 0; t < nt; t += 2) {
;             const bool last = (t == nt - 2);
;             const char* a1 = cA + (size_t)(t + 1) * kstep;
;             const char* a2 = last ? nA : cA + (size_t)(t + 2) * kstep; const char* b2 = last ? nB : cB + (size_t)(t + 2) * kstep;
;             const char* a3 = a2 + kstep; const char* b3 = b2 + kstep;
;             if (last && has_next) S.a_ready(nxt);
;             if constexpr (SP2) {
;             PG8_LDB(B0, 0, 0); PG8_LDB(B1, 0, 1); PG8_SCHED; PG8_LDA(At, 0, 0); PG8_STAGE(PG8_SA(1, 1), a1 + hstep, voffA);
;             PG8_WAIT_V(8); PG8_WAIT_L(0); PG8_BAR; PG8_MMAF(0, 0, At, B0); PG8_MMAF(0, 1, At, B1); PG8_BAR; PG8_SCHED;
;             const bool fin = last && !has_next;
;             PG8_LDA(At, 0, 1); if (!fin) { PG8_STAGE(PG8_SB(0, 0), b2, voffB); PG8_STAGE(PG8_SB(0, 1), b2 + hstep, voffB); PG8_STAGE(PG8_SA(0, 0), a2, voffA); }
;             if (!fin) PG8_WAIT_V(8); else PG8_WAIT_V(2); PG8_WAIT_L(0); PG8_BAR; PG8_MMAF(1, 0, At, B0); PG8_MMAF(1, 1, At, B1); PG8_BAR; PG8_SCHED;
;             PG8_LDB(B0, 1, 0); PG8_LDB(B1, 1, 1); PG8_SCHED; PG8_LDA(At, 1, 0); if (!fin) PG8_STAGE(PG8_SA(0, 1), a2 + hstep, voffA);
;             if (!fin) PG8_WAIT_V(8); else PG8_WAIT_V(0); PG8_WAIT_L(0); PG8_BAR; PG8_MMA(0, 0, At, B0); PG8_MMA(0, 1, At, B1); PG8_BAR; PG8_SCHED;
;             PG8_LDA(At, 1, 1); if (!fin) { PG8_STAGE(PG8_SB(1, 0), b3, voffB); PG8_STAGE(PG8_SB(1, 1), b3 + hstep, voffB); PG8_STAGE(PG8_SA(1, 0), a3, voffA); }
;             if (!fin) PG8_WAIT_V(8); PG8_WAIT_L(0); PG8_BAR; PG8_MMA(1, 0, At, B0); PG8_MMA(1, 1, At, B1); PG8_BAR; PG8_SCHED;
.LBB0_842:
	s_waitcnt lgkmcnt(0)
	s_barrier
	v_mfma_f32_16x16x32_f16 v[58:61], v[146:149], v[186:189], v[58:61]
	s_setprio 1
	v_mfma_f32_16x16x32_f16 v[58:61], v[150:153], v[190:193], v[58:61]
	v_mfma_f32_16x16x32_f16 v[42:45], v[150:153], v[182:185], v[42:45]
	v_mfma_f32_16x16x32_f16 v[42:45], v[146:149], v[178:181], v[42:45]
	v_mfma_f32_16x16x32_f16 v[26:29], v[146:149], v[170:173], v[26:29]
	v_mfma_f32_16x16x32_f16 v[26:29], v[150:153], v[174:177], v[26:29]
	v_mfma_f32_16x16x32_f16 v[10:13], v[150:153], v[166:169], v[10:13]
	v_mfma_f32_16x16x32_f16 v[10:13], v[146:149], v[162:165], v[10:13]
	v_mfma_f32_16x16x32_f16 v[2:5], v[154:157], v[162:165], v[2:5]
	v_mfma_f32_16x16x32_f16 v[2:5], v[158:161], v[166:169], v[2:5]
	v_mfma_f32_16x16x32_f16 v[50:53], v[158:161], v[190:193], v[50:53]
	v_mfma_f32_16x16x32_f16 v[50:53], v[154:157], v[186:189], v[50:53]
	v_mfma_f32_16x16x32_f16 v[34:37], v[154:157], v[178:181], v[34:37]
	v_mfma_f32_16x16x32_f16 v[34:37], v[158:161], v[182:185], v[34:37]
	v_mfma_f32_16x16x32_f16 v[18:21], v[158:161], v[174:177], v[18:21]
	v_mfma_f32_16x16x32_f16 v[18:21], v[154:157], v[170:173], v[18:21]
	v_mfma_f32_16x16x32_f16 v[30:33], v[130:133], v[170:173], v[30:33]
	v_mfma_f32_16x16x32_f16 v[30:33], v[134:137], v[174:177], v[30:33]
	v_mfma_f32_16x16x32_f16 v[66:69], v[134:137], v[190:193], v[66:69]
	v_mfma_f32_16x16x32_f16 v[66:69], v[130:133], v[186:189], v[66:69]
	v_mfma_f32_16x16x32_f16 v[46:49], v[130:133], v[178:181], v[46:49]
	v_mfma_f32_16x16x32_f16 v[46:49], v[134:137], v[182:185], v[46:49]
	v_mfma_f32_16x16x32_f16 v[14:17], v[134:137], v[166:169], v[14:17]
	v_mfma_f32_16x16x32_f16 v[14:17], v[130:133], v[162:165], v[14:17]
	v_mfma_f32_16x16x32_f16 v[6:9], v[138:141], v[162:165], v[6:9]
	v_mfma_f32_16x16x32_f16 v[6:9], v[142:145], v[166:169], v[6:9]
	v_mfma_f32_16x16x32_f16 v[54:57], v[142:145], v[190:193], v[54:57]
	v_mfma_f32_16x16x32_f16 v[54:57], v[138:141], v[186:189], v[54:57]
	v_mfma_f32_16x16x32_f16 v[38:41], v[138:141], v[178:181], v[38:41]
	v_mfma_f32_16x16x32_f16 v[38:41], v[142:145], v[182:185], v[38:41]
	v_mfma_f32_16x16x32_f16 v[22:25], v[142:145], v[174:177], v[22:25]
	v_mfma_f32_16x16x32_f16 v[22:25], v[138:141], v[170:173], v[22:25]
	s_barrier
	s_setprio 0
	s_add_i32 s55, s55, 2
	s_add_u32 s53, s53, 0x100
	s_addc_u32 s54, s54, 0
	s_cmp_gt_u32 s55, 13
	s_cbranch_scc1 .LBB0_853
.LBB0_843:
	ds_read_b128 v[146:149], v210
	ds_read_b128 v[150:153], v210 offset:1024
	ds_read_b128 v[154:157], v210 offset:2048
	ds_read_b128 v[158:161], v210 offset:3072
	ds_read_b128 v[130:133], v211
	ds_read_b128 v[134:137], v211 offset:1024
	ds_read_b128 v[138:141], v211 offset:2048
	ds_read_b128 v[142:145], v211 offset:3072
	s_mov_b64 s[6:7], s[48:49]
	s_add_u32 s48, s6, 0x100
	s_addc_u32 s49, s7, 0
	s_cmp_eq_u32 s55, 12
	s_cselect_b64 s[26:27], -1, 0
	s_and_b64 s[8:9], s[26:27], exec
	s_cselect_b32 s25, s41, s49
	s_cselect_b32 s24, s51, s48
	s_cselect_b32 s9, s39, s54
	s_cselect_b32 s8, s52, s53
	ds_read_b128 v[162:165], v212
	ds_read_b128 v[166:169], v212 offset:1024
	ds_read_b128 v[170:173], v212 offset:2048
	ds_read_b128 v[174:177], v212 offset:3072
	ds_read_b128 v[178:181], v212 offset:4096
	ds_read_b128 v[182:185], v212 offset:5120
	ds_read_b128 v[186:189], v212 offset:6144
	ds_read_b128 v[190:193], v212 offset:7168
	s_add_u32 s6, s6, 0x40080
	s_addc_u32 s7, s7, 0
	s_add_u32 m0, s14, 0xc000
	s_nop 0
	global_load_lds_dwordx4 v206, s[6:7]
	s_nop 0
	s_add_u32 m0, s14, 0xe000
	s_nop 0
	global_load_lds_dwordx4 v208, s[6:7]
	s_waitcnt vmcnt(8)
	s_waitcnt lgkmcnt(0)
	s_barrier
	v_mfma_f32_16x16x32_f16 v[114:117], v[146:149], v[162:165], v[114:117]
	s_setprio 1
	v_mfma_f32_16x16x32_f16 v[114:117], v[150:153], v[166:169], v[114:117]
	v_mfma_f32_16x16x32_f16 v[106:109], v[150:153], v[174:177], v[106:109]
	v_mfma_f32_16x16x32_f16 v[106:109], v[146:149], v[170:173], v[106:109]
	v_mfma_f32_16x16x32_f16 v[90:93], v[146:149], v[178:181], v[90:93]
	v_mfma_f32_16x16x32_f16 v[90:93], v[150:153], v[182:185], v[90:93]
	v_mfma_f32_16x16x32_f16 v[74:77], v[150:153], v[190:193], v[74:77]
	v_mfma_f32_16x16x32_f16 v[74:77], v[146:149], v[186:189], v[74:77]
	v_mfma_f32_16x16x32_f16 v[62:65], v[154:157], v[186:189], v[62:65]
	v_mfma_f32_16x16x32_f16 v[62:65], v[158:161], v[190:193], v[62:65]
	v_mfma_f32_16x16x32_f16 v[110:113], v[158:161], v[166:169], v[110:113]
	v_mfma_f32_16x16x32_f16 v[110:113], v[154:157], v[162:165], v[110:113]
	v_mfma_f32_16x16x32_f16 v[98:101], v[154:157], v[170:173], v[98:101]
	v_mfma_f32_16x16x32_f16 v[98:101], v[158:161], v[174:177], v[98:101]
	v_mfma_f32_16x16x32_f16 v[82:85], v[158:161], v[182:185], v[82:85]
	v_mfma_f32_16x16x32_f16 v[82:85], v[154:157], v[178:181], v[82:85]
	v_mfma_f32_16x16x32_f16 v[94:97], v[130:133], v[178:181], v[94:97]
	v_mfma_f32_16x16x32_f16 v[94:97], v[134:137], v[182:185], v[94:97]
	v_mfma_f32_16x16x32_f16 v[126:129], v[134:137], v[166:169], v[126:129]
	v_mfma_f32_16x16x32_f16 v[126:129], v[130:133], v[162:165], v[126:129]
	v_mfma_f32_16x16x32_f16 v[118:121], v[130:133], v[170:173], v[118:121]
	v_mfma_f32_16x16x32_f16 v[118:121], v[134:137], v[174:177], v[118:121]
	v_mfma_f32_16x16x32_f16 v[78:81], v[134:137], v[190:193], v[78:81]
	v_mfma_f32_16x16x32_f16 v[78:81], v[130:133], v[186:189], v[78:81]
	v_mfma_f32_16x16x32_f16 v[70:73], v[138:141], v[186:189], v[70:73]
	v_mfma_f32_16x16x32_f16 v[70:73], v[142:145], v[190:193], v[70:73]
	v_mfma_f32_16x16x32_f16 v[122:125], v[142:145], v[166:169], v[122:125]
	v_mfma_f32_16x16x32_f16 v[122:125], v[138:141], v[162:165], v[122:125]
	v_mfma_f32_16x16x32_f16 v[102:105], v[138:141], v[170:173], v[102:105]
	v_mfma_f32_16x16x32_f16 v[102:105], v[142:145], v[174:177], v[102:105]
	v_mfma_f32_16x16x32_f16 v[86:89], v[142:145], v[182:185], v[86:89]
	v_mfma_f32_16x16x32_f16 v[86:89], v[138:141], v[178:181], v[86:89]
	s_barrier
	s_setprio 0
	ds_read_b128 v[186:189], v212 offset:16384
	ds_read_b128 v[190:193], v212 offset:17408
	ds_read_b128 v[178:181], v212 offset:18432
	ds_read_b128 v[182:185], v212 offset:19456
	ds_read_b128 v[170:173], v212 offset:20480
	ds_read_b128 v[174:177], v212 offset:21504
	ds_read_b128 v[162:165], v212 offset:22528
	ds_read_b128 v[166:169], v212 offset:23552
	s_and_b64 s[6:7], s[4:5], s[26:27]
	s_mov_b64 s[26:27], -1
	s_and_b64 vcc, exec, s[6:7]
	s_cbranch_vccnz .LBB0_845
	s_add_u32 m0, s14, 0x10000
	s_nop 0
	global_load_lds_dwordx4 v207, s[8:9]
	s_nop 0
	s_add_u32 m0, s14, 0x12000
	s_nop 0
	global_load_lds_dwordx4 v209, s[8:9]
	s_add_u32 s26, s8, 0x40000
	s_addc_u32 s27, s9, 0
	s_add_u32 m0, s14, 0x14000
	s_nop 0
	global_load_lds_dwordx4 v207, s[26:27]
	s_nop 0
	s_add_u32 m0, s14, 0x16000
	s_nop 0
	global_load_lds_dwordx4 v209, s[26:27]
	s_mov_b64 s[26:27], 0
	s_add_u32 m0, s14, 0
	s_nop 0
	global_load_lds_dwordx4 v206, s[24:25]
	s_nop 0
	s_add_u32 m0, s14, 0x2000
	s_nop 0
	global_load_lds_dwordx4 v208, s[24:25]
	s_waitcnt vmcnt(8)

; #define PG8_STAGE(bufoff, gbase, voff) do { if constexpr (ABL & 1) break; glds16s<(bufoff)>((voff)[0], (const void*)(gbase), ldsbw); glds16s<(bufoff) + 8192>((voff)[1], (const void*)(gbase), ldsbw); } while (0)
; #define PG8_LDA(dst, b, h) do { if constexpr (ABL & 4) break; _Pragma("unroll") for (int m = 0; m < 4; ++m) _Pragma("unroll") for (int k = 0; k < 2; ++k) dst[m][k] = *(const LAS f16x8*)(lds + PG8_SA(b, h) + aoff + m * 2048 + k * 1024); } while (0)
; #define PG8_LDB(dst, b, h) do { if constexpr (ABL & 4) break; _Pragma("unroll") for (int n = 0; n < 2; ++n) _Pragma("unroll") for (int k = 0; k < 2; ++k) dst[n][k] = *(const LAS f16x8*)(lds + PG8_SB(b, h) + boff + n * 2048 + k * 1024); } while (0)
; #define PG8_MMA(ai, bj, At, Bt) do { if constexpr (ABL & 2) break; __builtin_amdgcn_s_setprio(1); _Pragma("unroll") for (int m = 0; m < 4; ++m) _Pragma("unroll") for (int n = 0; n < 2; ++n) _Pragma("unroll") for (int k = 0; k < 2; ++k) \
;         acc[ai][bj][m][n] = __builtin_amdgcn_mfma_f32_16x16x32_f16(Bt[n][k], At[m][k], acc[ai][bj][m][n], 0, 0, 0); __builtin_amdgcn_s_setprio(0); } while (0)
; #define PG8_MMAF(ai, bj, At, Bt) do { if (t == 0) PG8_MMA0(ai, bj, At, Bt); else PG8_MMA(ai, bj, At, Bt); } while (0)
; #define PG8_WAIT_V(n) asm volatile("s_waitcnt vmcnt(" #n ")" ::: "memory")
; #define PG8_WAIT_L(n) asm volatile("s_waitcnt lgkmcnt(" #n ")" ::: "memory")
; #define PG8_BAR __builtin_amdgcn_s_barrier()
; #define PG8_SCHED __builtin_amdgcn_sched_barrier(0)
;     ...
;             if (!fin) PG8_WAIT_V(8); else PG8_WAIT_V(2); PG8_WAIT_L(0); PG8_BAR; PG8_MMAF(1, 0, At, B0); PG8_MMAF(1, 1, At, B1); PG8_BAR; PG8_SCHED;
;             PG8_LDB(B0, 1, 0); PG8_LDB(B1, 1, 1); PG8_SCHED; PG8_LDA(At, 1, 0); if (!fin) PG8_STAGE(PG8_SA(0, 1), a2 + hstep, voffA);
;             if (!fin) PG8_WAIT_V(8); else PG8_WAIT_V(0); PG8_WAIT_L(0); PG8_BAR; PG8_MMA(0, 0, At, B0); PG8_MMA(0, 1, At, B1); PG8_BAR; PG8_SCHED;
.LBB0_847:
	s_waitcnt lgkmcnt(0)
	s_xor_b64 s[26:27], s[6:7], -1
	s_barrier
	v_mfma_f32_16x16x32_f16 v[58:61], v[146:149], v[186:189], v[58:61]
	s_setprio 1
	v_mfma_f32_16x16x32_f16 v[58:61], v[150:153], v[190:193], v[58:61]
	v_mfma_f32_16x16x32_f16 v[42:45], v[150:153], v[182:185], v[42:45]
	v_mfma_f32_16x16x32_f16 v[42:45], v[146:149], v[178:181], v[42:45]
	v_mfma_f32_16x16x32_f16 v[26:29], v[146:149], v[170:173], v[26:29]
	v_mfma_f32_16x16x32_f16 v[26:29], v[150:153], v[174:177], v[26:29]
	v_mfma_f32_16x16x32_f16 v[10:13], v[150:153], v[166:169], v[10:13]
	v_mfma_f32_16x16x32_f16 v[10:13], v[146:149], v[162:165], v[10:13]
	v_mfma_f32_16x16x32_f16 v[2:5], v[154:157], v[162:165], v[2:5]
	v_mfma_f32_16x16x32_f16 v[2:5], v[158:161], v[166:169], v[2:5]
	v_mfma_f32_16x16x32_f16 v[50:53], v[158:161], v[190:193], v[50:53]
	v_mfma_f32_16x16x32_f16 v[50:53], v[154:157], v[186:189], v[50:53]
	v_mfma_f32_16x16x32_f16 v[34:37], v[154:157], v[178:181], v[34:37]
	v_mfma_f32_16x16x32_f16 v[34:37], v[158:161], v[182:185], v[34:37]
	v_mfma_f32_16x16x32_f16 v[18:21], v[158:161], v[174:177], v[18:21]
	v_mfma_f32_16x16x32_f16 v[18:21], v[154:157], v[170:173], v[18:21]
	v_mfma_f32_16x16x32_f16 v[30:33], v[130:133], v[170:173], v[30:33]
	v_mfma_f32_16x16x32_f16 v[30:33], v[134:137], v[174:177], v[30:33]
	v_mfma_f32_16x16x32_f16 v[66:69], v[134:137], v[190:193], v[66:69]
	v_mfma_f32_16x16x32_f16 v[66:69], v[130:133], v[186:189], v[66:69]
	v_mfma_f32_16x16x32_f16 v[46:49], v[130:133], v[178:181], v[46:49]
	v_mfma_f32_16x16x32_f16 v[46:49], v[134:137], v[182:185], v[46:49]
	v_mfma_f32_16x16x32_f16 v[14:17], v[134:137], v[166:169], v[14:17]
	v_mfma_f32_16x16x32_f16 v[14:17], v[130:133], v[162:165], v[14:17]
	v_mfma_f32_16x16x32_f16 v[6:9], v[138:141], v[162:165], v[6:9]
	v_mfma_f32_16x16x32_f16 v[6:9], v[142:145], v[166:169], v[6:9]
	v_mfma_f32_16x16x32_f16 v[54:57], v[142:145], v[190:193], v[54:57]
	v_mfma_f32_16x16x32_f16 v[54:57], v[138:141], v[186:189], v[54:57]
	v_mfma_f32_16x16x32_f16 v[38:41], v[138:141], v[178:181], v[38:41]
	v_mfma_f32_16x16x32_f16 v[38:41], v[142:145], v[182:185], v[38:41]
	v_mfma_f32_16x16x32_f16 v[22:25], v[142:145], v[174:177], v[22:25]
	v_mfma_f32_16x16x32_f16 v[22:25], v[138:141], v[170:173], v[22:25]
	s_barrier
	s_setprio 0
	ds_read_b128 v[146:149], v213
	ds_read_b128 v[150:153], v213 offset:1024
	ds_read_b128 v[154:157], v213 offset:2048
	ds_read_b128 v[158:161], v213 offset:3072
	ds_read_b128 v[130:133], v214
	ds_read_b128 v[134:137], v214 offset:1024
	ds_read_b128 v[138:141], v214 offset:2048
	ds_read_b128 v[142:145], v214 offset:3072
	ds_read_b128 v[186:189], v212 offset:32768
	ds_read_b128 v[190:193], v212 offset:33792
	ds_read_b128 v[178:181], v212 offset:34816
	ds_read_b128 v[182:185], v212 offset:35840
	ds_read_b128 v[170:173], v212 offset:36864
	ds_read_b128 v[174:177], v212 offset:37888
	ds_read_b128 v[162:165], v212 offset:38912
	ds_read_b128 v[166:169], v212 offset:39936
	v_cndmask_b32_e64 v216, 0, 1, s[26:27]
	v_cmp_ne_u32_e64 s[6:7], 1, v216
	s_andn2_b64 vcc, exec, s[26:27]
	s_mov_b64 s[26:27], -1
	s_cbranch_vccnz .LBB0_849
	s_add_u32 s26, s24, 0x40000
	s_addc_u32 s27, s25, 0
	s_add_u32 m0, s14, 0x4000
	s_nop 0
	global_load_lds_dwordx4 v206, s[26:27]
	s_nop 0
	s_add_u32 m0, s14, 0x6000
	s_nop 0
	global_load_lds_dwordx4 v208, s[26:27]
	s_waitcnt vmcnt(8)
	s_mov_b64 s[26:27], 0

; #define PG8_STAGE(bufoff, gbase, voff) do { if constexpr (ABL & 1) break; glds16s<(bufoff)>((voff)[0], (const void*)(gbase), ldsbw); glds16s<(bufoff) + 8192>((voff)[1], (const void*)(gbase), ldsbw); } while (0)
; #define PG8_LDA(dst, b, h) do { if constexpr (ABL & 4) break; _Pragma("unroll") for (int m = 0; m < 4; ++m) _Pragma("unroll") for (int k = 0; k < 2; ++k) dst[m][k] = *(const LAS f16x8*)(lds + PG8_SA(b, h) + aoff + m * 2048 + k * 1024); } while (0)
; #define PG8_MMA(ai, bj, At, Bt) do { if constexpr (ABL & 2) break; __builtin_amdgcn_s_setprio(1); _Pragma("unroll") for (int m = 0; m < 4; ++m) _Pragma("unroll") for (int n = 0; n < 2; ++n) _Pragma("unroll") for (int k = 0; k < 2; ++k) \
;         acc[ai][bj][m][n] = __builtin_amdgcn_mfma_f32_16x16x32_f16(Bt[n][k], At[m][k], acc[ai][bj][m][n], 0, 0, 0); __builtin_amdgcn_s_setprio(0); } while (0)
; #define PG8_WAIT_V(n) asm volatile("s_waitcnt vmcnt(" #n ")" ::: "memory")
; #define PG8_WAIT_L(n) asm volatile("s_waitcnt lgkmcnt(" #n ")" ::: "memory")
; #define PG8_BAR __builtin_amdgcn_s_barrier()
; #define PG8_SCHED __builtin_amdgcn_sched_barrier(0)
;     ...
;             if (!fin) PG8_WAIT_V(8); else PG8_WAIT_V(0); PG8_WAIT_L(0); PG8_BAR; PG8_MMA(0, 0, At, B0); PG8_MMA(0, 1, At, B1); PG8_BAR; PG8_SCHED;
;             PG8_LDA(At, 1, 1); if (!fin) { PG8_STAGE(PG8_SB(1, 0), b3, voffB); PG8_STAGE(PG8_SB(1, 1), b3 + hstep, voffB); PG8_STAGE(PG8_SA(1, 0), a3, voffA); }
;             if (!fin) PG8_WAIT_V(8); PG8_WAIT_L(0); PG8_BAR; PG8_MMA(1, 0, At, B0); PG8_MMA(1, 1, At, B1); PG8_BAR; PG8_SCHED;
.LBB0_851:
	s_waitcnt lgkmcnt(0)
	s_barrier
	v_mfma_f32_16x16x32_f16 v[114:117], v[146:149], v[186:189], v[114:117]
	s_setprio 1
	v_mfma_f32_16x16x32_f16 v[114:117], v[150:153], v[190:193], v[114:117]
	v_mfma_f32_16x16x32_f16 v[106:109], v[150:153], v[182:185], v[106:109]
	v_mfma_f32_16x16x32_f16 v[106:109], v[146:149], v[178:181], v[106:109]
	v_mfma_f32_16x16x32_f16 v[90:93], v[146:149], v[170:173], v[90:93]
	v_mfma_f32_16x16x32_f16 v[90:93], v[150:153], v[174:177], v[90:93]
	v_mfma_f32_16x16x32_f16 v[74:77], v[150:153], v[166:169], v[74:77]
	v_mfma_f32_16x16x32_f16 v[74:77], v[146:149], v[162:165], v[74:77]
	v_mfma_f32_16x16x32_f16 v[62:65], v[154:157], v[162:165], v[62:65]
	v_mfma_f32_16x16x32_f16 v[62:65], v[158:161], v[166:169], v[62:65]
	v_mfma_f32_16x16x32_f16 v[110:113], v[158:161], v[190:193], v[110:113]
	v_mfma_f32_16x16x32_f16 v[110:113], v[154:157], v[186:189], v[110:113]
	v_mfma_f32_16x16x32_f16 v[98:101], v[154:157], v[178:181], v[98:101]
	v_mfma_f32_16x16x32_f16 v[98:101], v[158:161], v[182:185], v[98:101]
	v_mfma_f32_16x16x32_f16 v[82:85], v[158:161], v[174:177], v[82:85]
	v_mfma_f32_16x16x32_f16 v[82:85], v[154:157], v[170:173], v[82:85]
	v_mfma_f32_16x16x32_f16 v[94:97], v[130:133], v[170:173], v[94:97]
	v_mfma_f32_16x16x32_f16 v[94:97], v[134:137], v[174:177], v[94:97]
	v_mfma_f32_16x16x32_f16 v[126:129], v[134:137], v[190:193], v[126:129]
	v_mfma_f32_16x16x32_f16 v[126:129], v[130:133], v[186:189], v[126:129]
	v_mfma_f32_16x16x32_f16 v[118:121], v[130:133], v[178:181], v[118:121]
	v_mfma_f32_16x16x32_f16 v[118:121], v[134:137], v[182:185], v[118:121]
	v_mfma_f32_16x16x32_f16 v[78:81], v[134:137], v[166:169], v[78:81]
	v_mfma_f32_16x16x32_f16 v[78:81], v[130:133], v[162:165], v[78:81]
	v_mfma_f32_16x16x32_f16 v[70:73], v[138:141], v[162:165], v[70:73]
	v_mfma_f32_16x16x32_f16 v[70:73], v[142:145], v[166:169], v[70:73]
	v_mfma_f32_16x16x32_f16 v[122:125], v[142:145], v[190:193], v[122:125]
	v_mfma_f32_16x16x32_f16 v[122:125], v[138:141], v[186:189], v[122:125]
	v_mfma_f32_16x16x32_f16 v[102:105], v[138:141], v[178:181], v[102:105]
	v_mfma_f32_16x16x32_f16 v[102:105], v[142:145], v[182:185], v[102:105]
	v_mfma_f32_16x16x32_f16 v[86:89], v[142:145], v[174:177], v[86:89]
	v_mfma_f32_16x16x32_f16 v[86:89], v[138:141], v[170:173], v[86:89]
	s_barrier
	s_setprio 0
	ds_read_b128 v[186:189], v212 offset:49152
	ds_read_b128 v[190:193], v212 offset:50176
	ds_read_b128 v[178:181], v212 offset:51200
	ds_read_b128 v[182:185], v212 offset:52224
	ds_read_b128 v[170:173], v212 offset:53248
	ds_read_b128 v[174:177], v212 offset:54272
	ds_read_b128 v[162:165], v212 offset:55296
	ds_read_b128 v[166:169], v212 offset:56320
	s_and_b64 vcc, exec, s[6:7]
	s_cbranch_vccnz .LBB0_842
	s_add_u32 s6, s24, 0x80
	s_addc_u32 s7, s25, 0
	s_add_u32 s24, s8, 0x80
	s_addc_u32 s25, s9, 0
	s_add_u32 m0, s14, 0x18000
	s_nop 0
	global_load_lds_dwordx4 v207, s[24:25]
	s_nop 0
	s_add_u32 m0, s14, 0x1a000
	s_nop 0
	global_load_lds_dwordx4 v209, s[24:25]
	s_add_u32 s8, s8, 0x40080
	s_addc_u32 s9, s9, 0
	s_add_u32 m0, s14, 0x1c000
	s_nop 0
	global_load_lds_dwordx4 v207, s[8:9]
	s_nop 0
	s_add_u32 m0, s14, 0x1e000
	s_nop 0
	global_load_lds_dwordx4 v209, s[8:9]
	s_nop 0
	s_add_u32 m0, s14, 0x8000
	s_nop 0
	global_load_lds_dwordx4 v206, s[6:7]
	s_nop 0
	s_add_u32 m0, s14, 0xa000
	s_nop 0
	global_load_lds_dwordx4 v208, s[6:7]
	s_waitcnt vmcnt(8)
	s_branch .LBB0_842

;     __device__ __forceinline__ bool next(int i, Unit& u) const { if (i >= count) return false; const int L = first + i; u.pm = L / nN; u.pn = L % nN; return true; }
; #define PG8_STAGE(bufoff, gbase, voff) do { if constexpr (ABL & 1) break; glds16s<(bufoff)>((voff)[0], (const void*)(gbase), ldsbw); glds16s<(bufoff) + 8192>((voff)[1], (const void*)(gbase), ldsbw); } while (0)
; #define PG8_LDA(dst, b, h) do { if constexpr (ABL & 4) break; _Pragma("unroll") for (int m = 0; m < 4; ++m) _Pragma("unroll") for (int k = 0; k < 2; ++k) dst[m][k] = *(const LAS f16x8*)(lds + PG8_SA(b, h) + aoff + m * 2048 + k * 1024); } while (0)
; #define PG8_LDB(dst, b, h) do { if constexpr (ABL & 4) break; _Pragma("unroll") for (int n = 0; n < 2; ++n) _Pragma("unroll") for (int k = 0; k < 2; ++k) dst[n][k] = *(const LAS f16x8*)(lds + PG8_SB(b, h) + boff + n * 2048 + k * 1024); } while (0)
; #define PG8_MMAF(ai, bj, At, Bt) do { if (t == 0) PG8_MMA0(ai, bj, At, Bt); else PG8_MMA(ai, bj, At, Bt); } while (0)
; #define PG8_WAIT_V(n) asm volatile("s_waitcnt vmcnt(" #n ")" ::: "memory")
; #define PG8_BAR __builtin_amdgcn_s_barrier()
;     ...
;         const bool has_next = S.next(ui + 1, nxt);
;         const char* nA = has_next ? (const char*)g.A + (size_t)nxt.pm * tstep : cA; const char* nB = has_next ? (const char*)g.Bt + (size_t)nxt.pn * tstep : cB;
;         for (int t = 0; t < nt; t += 2) {
;             const bool last = (t == nt - 2);
;             const char* a1 = cA + (size_t)(t + 1) * kstep;
;             const char* a2 = last ? nA : cA + (size_t)(t + 2) * kstep; const char* b2 = last ? nB : cB + (size_t)(t + 2) * kstep;
;             const char* a3 = a2 + kstep; const char* b3 = b2 + kstep;
;             if (last && has_next) S.a_ready(nxt);
;             if constexpr (SP2) {
;             PG8_LDB(B0, 0, 0); PG8_LDB(B1, 0, 1); PG8_SCHED; PG8_LDA(At, 0, 0); PG8_STAGE(PG8_SA(1, 1), a1 + hstep, voffA);
;             PG8_WAIT_V(8); PG8_WAIT_L(0); PG8_BAR; PG8_MMAF(0, 0, At, B0); PG8_MMAF(0, 1, At, B1); PG8_BAR; PG8_SCHED;
;             const bool fin = last && !has_next;
;             PG8_LDA(At, 0, 1); if (!fin) { PG8_STAGE(PG8_SB(0, 0), b2, voffB); PG8_STAGE(PG8_SB(0, 1), b2 + hstep, voffB); PG8_STAGE(PG8_SA(0, 0), a2, voffA); }
;             if (!fin) PG8_WAIT_V(8); else PG8_WAIT_V(2); PG8_WAIT_L(0); PG8_BAR; PG8_MMAF(1, 0, At, B0); PG8_MMAF(1, 1, At, B1); PG8_BAR; PG8_SCHED;
.LBB0_878:
	s_ashr_i32 s45, s44, 31
	s_lshl_b64 s[8:9], s[44:45], 17
	s_add_u32 s48, s86, s8
	ds_read_b128 v[2:5], v1
	ds_read_b128 v[6:9], v1 offset:1024
	ds_read_b128 v[10:13], v1 offset:2048
	ds_read_b128 v[14:17], v1 offset:3072
	ds_read_b128 v[18:21], v234
	ds_read_b128 v[22:25], v234 offset:1024
	ds_read_b128 v[26:29], v234 offset:2048
	ds_read_b128 v[30:33], v234 offset:3072
	s_addc_u32 s49, s87, s9
	s_ashr_i32 s43, s42, 31
	s_lshl_b64 s[8:9], s[42:43], 17
	s_add_u32 s50, s70, s8
	s_addc_u32 s51, s71, s9
	s_add_u32 s26, s52, 0x100
	s_addc_u32 s27, s53, 0
	s_add_u32 s60, s54, 0x100
	s_addc_u32 s61, s55, 0
	s_add_u32 s8, s52, 0x180
	s_addc_u32 s9, s53, 0
	ds_read_b128 v[34:37], v235
	ds_read_b128 v[38:41], v235 offset:1024
	ds_read_b128 v[42:45], v235 offset:2048
	ds_read_b128 v[46:49], v235 offset:3072
	ds_read_b128 v[50:53], v235 offset:4096
	ds_read_b128 v[54:57], v235 offset:5120
	ds_read_b128 v[58:61], v235 offset:6144
	ds_read_b128 v[62:65], v235 offset:7168
	s_add_u32 s24, s54, 0x180
	s_addc_u32 s25, s55, 0
	s_add_u32 s62, s52, 0x10080
	s_addc_u32 s63, s53, 0
	s_add_u32 m0, s14, 0xc000
	s_nop 0
	global_load_lds_dwordx4 v230, s[62:63]
	s_nop 0
	s_add_u32 m0, s14, 0xe000
	s_nop 0
	global_load_lds_dwordx4 v232, s[62:63]
	s_waitcnt vmcnt(8)
	s_waitcnt lgkmcnt(0)
	s_barrier
	v_mfma_f32_16x16x32_f16 v[66:69], v[2:5], v[34:37], 0
	s_setprio 1
	v_mfma_f32_16x16x32_f16 v[66:69], v[6:9], v[38:41], v[66:69]
	v_mfma_f32_16x16x32_f16 v[70:73], v[10:13], v[34:37], 0
	v_mfma_f32_16x16x32_f16 v[70:73], v[14:17], v[38:41], v[70:73]
	v_mfma_f32_16x16x32_f16 v[82:85], v[2:5], v[50:53], 0
	v_mfma_f32_16x16x32_f16 v[82:85], v[6:9], v[54:57], v[82:85]
	v_mfma_f32_16x16x32_f16 v[86:89], v[10:13], v[50:53], 0
	v_mfma_f32_16x16x32_f16 v[86:89], v[14:17], v[54:57], v[86:89]
	v_mfma_f32_16x16x32_f16 v[90:93], v[2:5], v[58:61], 0
	v_mfma_f32_16x16x32_f16 v[90:93], v[6:9], v[62:65], v[90:93]
	v_mfma_f32_16x16x32_f16 v[94:97], v[10:13], v[58:61], 0
	v_mfma_f32_16x16x32_f16 v[94:97], v[14:17], v[62:65], v[94:97]
	v_mfma_f32_16x16x32_f16 v[74:77], v[2:5], v[42:45], 0
	v_mfma_f32_16x16x32_f16 v[74:77], v[6:9], v[46:49], v[74:77]
	v_mfma_f32_16x16x32_f16 v[78:81], v[10:13], v[42:45], 0
	v_mfma_f32_16x16x32_f16 v[78:81], v[14:17], v[46:49], v[78:81]
	v_mfma_f32_16x16x32_f16 v[98:101], v[18:21], v[34:37], 0
	v_mfma_f32_16x16x32_f16 v[98:101], v[22:25], v[38:41], v[98:101]
	v_mfma_f32_16x16x32_f16 v[34:37], v[26:29], v[34:37], 0
	v_mfma_f32_16x16x32_f16 v[34:37], v[30:33], v[38:41], v[34:37]
	v_mfma_f32_16x16x32_f16 v[38:41], v[18:21], v[42:45], 0
	v_mfma_f32_16x16x32_f16 v[38:41], v[22:25], v[46:49], v[38:41]
	v_mfma_f32_16x16x32_f16 v[42:45], v[26:29], v[42:45], 0
	v_mfma_f32_16x16x32_f16 v[42:45], v[30:33], v[46:49], v[42:45]
	v_mfma_f32_16x16x32_f16 v[46:49], v[18:21], v[50:53], 0
	v_mfma_f32_16x16x32_f16 v[46:49], v[22:25], v[54:57], v[46:49]
	v_mfma_f32_16x16x32_f16 v[50:53], v[26:29], v[50:53], 0
	v_mfma_f32_16x16x32_f16 v[50:53], v[30:33], v[54:57], v[50:53]
	v_mfma_f32_16x16x32_f16 v[54:57], v[18:21], v[58:61], 0
	v_mfma_f32_16x16x32_f16 v[54:57], v[22:25], v[62:65], v[54:57]
	v_mfma_f32_16x16x32_f16 v[58:61], v[26:29], v[58:61], 0
	v_mfma_f32_16x16x32_f16 v[58:61], v[30:33], v[62:65], v[58:61]
	s_barrier
	s_setprio 0
	ds_read_b128 v[62:65], v235 offset:16384
	ds_read_b128 v[102:105], v235 offset:17408
	ds_read_b128 v[106:109], v235 offset:18432
	ds_read_b128 v[110:113], v235 offset:19456
	ds_read_b128 v[114:117], v235 offset:20480
	ds_read_b128 v[118:121], v235 offset:21504
	ds_read_b128 v[122:125], v235 offset:22528
	ds_read_b128 v[126:129], v235 offset:23552
	s_add_u32 m0, s14, 0x10000
	s_nop 0
	global_load_lds_dwordx4 v231, s[60:61]
	s_nop 0
	s_add_u32 m0, s14, 0x12000
	s_nop 0
	global_load_lds_dwordx4 v233, s[60:61]
	s_add_u32 s60, s54, 0x10100
	s_addc_u32 s61, s55, 0
	s_add_u32 m0, s14, 0x14000
	s_nop 0
	global_load_lds_dwordx4 v231, s[60:61]
	s_nop 0
	s_add_u32 m0, s14, 0x16000
	s_nop 0
	global_load_lds_dwordx4 v233, s[60:61]
	s_nop 0
	s_add_u32 m0, s14, 0
	s_nop 0
	global_load_lds_dwordx4 v230, s[26:27]
	s_nop 0
	s_add_u32 m0, s14, 0x2000
	s_nop 0
	global_load_lds_dwordx4 v232, s[26:27]
	s_waitcnt vmcnt(8)
	s_waitcnt lgkmcnt(0)
	s_barrier
	v_mfma_f32_16x16x32_f16 v[130:133], v[2:5], v[62:65], 0
	s_setprio 1
	v_mfma_f32_16x16x32_f16 v[130:133], v[6:9], v[102:105], v[130:133]
	v_mfma_f32_16x16x32_f16 v[138:141], v[2:5], v[106:109], 0
	v_mfma_f32_16x16x32_f16 v[138:141], v[6:9], v[110:113], v[138:141]
	v_mfma_f32_16x16x32_f16 v[146:149], v[2:5], v[114:117], 0
	v_mfma_f32_16x16x32_f16 v[146:149], v[6:9], v[118:121], v[146:149]
	v_mfma_f32_16x16x32_f16 v[2:5], v[2:5], v[122:125], 0
	v_mfma_f32_16x16x32_f16 v[2:5], v[6:9], v[126:129], v[2:5]
	v_mfma_f32_16x16x32_f16 v[134:137], v[10:13], v[62:65], 0
	v_mfma_f32_16x16x32_f16 v[134:137], v[14:17], v[102:105], v[134:137]
	v_mfma_f32_16x16x32_f16 v[142:145], v[10:13], v[106:109], 0
	v_mfma_f32_16x16x32_f16 v[142:145], v[14:17], v[110:113], v[142:145]
	v_mfma_f32_16x16x32_f16 v[150:153], v[10:13], v[114:117], 0
	v_mfma_f32_16x16x32_f16 v[150:153], v[14:17], v[118:121], v[150:153]
	v_mfma_f32_16x16x32_f16 v[6:9], v[10:13], v[122:125], 0
	v_mfma_f32_16x16x32_f16 v[6:9], v[14:17], v[126:129], v[6:9]
	v_mfma_f32_16x16x32_f16 v[10:13], v[18:21], v[62:65], 0
	v_mfma_f32_16x16x32_f16 v[14:17], v[26:29], v[62:65], 0
	v_mfma_f32_16x16x32_f16 v[10:13], v[22:25], v[102:105], v[10:13]
	v_mfma_f32_16x16x32_f16 v[14:17], v[30:33], v[102:105], v[14:17]
	v_mfma_f32_16x16x32_f16 v[102:105], v[26:29], v[106:109], 0
	v_mfma_f32_16x16x32_f16 v[62:65], v[18:21], v[106:109], 0
	v_mfma_f32_16x16x32_f16 v[154:157], v[30:33], v[110:113], v[102:105]
	v_mfma_f32_16x16x32_f16 v[102:105], v[18:21], v[114:117], 0
	v_mfma_f32_16x16x32_f16 v[18:21], v[18:21], v[122:125], 0
	v_mfma_f32_16x16x32_f16 v[62:65], v[22:25], v[110:113], v[62:65]
	v_mfma_f32_16x16x32_f16 v[158:161], v[22:25], v[118:121], v[102:105]
	v_mfma_f32_16x16x32_f16 v[102:105], v[26:29], v[114:117], 0
	v_mfma_f32_16x16x32_f16 v[18:21], v[22:25], v[126:129], v[18:21]
	v_mfma_f32_16x16x32_f16 v[22:25], v[26:29], v[122:125], 0
	v_mfma_f32_16x16x32_f16 v[162:165], v[30:33], v[118:121], v[102:105]
	v_mfma_f32_16x16x32_f16 v[22:25], v[30:33], v[126:129], v[22:25]
	s_barrier
; #define PG8_STAGE(bufoff, gbase, voff) do { if constexpr (ABL & 1) break; glds16s<(bufoff)>((voff)[0], (const void*)(gbase), ldsbw); glds16s<(bufoff) + 8192>((voff)[1], (const void*)(gbase), ldsbw); } while (0)
; #define PG8_LDA(dst, b, h) do { if constexpr (ABL & 4) break; _Pragma("unroll") for (int m = 0; m < 4; ++m) _Pragma("unroll") for (int k = 0; k < 2; ++k) dst[m][k] = *(const LAS f16x8*)(lds + PG8_SA(b, h) + aoff + m * 2048 + k * 1024); } while (0)
; #define PG8_LDB(dst, b, h) do { if constexpr (ABL & 4) break; _Pragma("unroll") for (int n = 0; n < 2; ++n) _Pragma("unroll") for (int k = 0; k < 2; ++k) dst[n][k] = *(const LAS f16x8*)(lds + PG8_SB(b, h) + boff + n * 2048 + k * 1024); } while (0)
; #define PG8_MMA(ai, bj, At, Bt) do { if constexpr (ABL & 2) break; __builtin_amdgcn_s_setprio(1); _Pragma("unroll") for (int m = 0; m < 4; ++m) _Pragma("unroll") for (int n = 0; n < 2; ++n) _Pragma("unroll") for (int k = 0; k < 2; ++k) \
;         acc[ai][bj][m][n] = __builtin_amdgcn_mfma_f32_16x16x32_f16(Bt[n][k], At[m][k], acc[ai][bj][m][n], 0, 0, 0); __builtin_amdgcn_s_setprio(0); } while (0)
; #define PG8_MMAF(ai, bj, At, Bt) do { if (t == 0) PG8_MMA0(ai, bj, At, Bt); else PG8_MMA(ai, bj, At, Bt); } while (0)
; #define PG8_WAIT_V(n) asm volatile("s_waitcnt vmcnt(" #n ")" ::: "memory")
; #define PG8_WAIT_L(n) asm volatile("s_waitcnt lgkmcnt(" #n ")" ::: "memory")
; #define PG8_BAR __builtin_amdgcn_s_barrier()
; #define PG8_SCHED __builtin_amdgcn_sched_barrier(0)
;     ...
;             if (!fin) PG8_WAIT_V(8); else PG8_WAIT_V(2); PG8_WAIT_L(0); PG8_BAR; PG8_MMAF(1, 0, At, B0); PG8_MMAF(1, 1, At, B1); PG8_BAR; PG8_SCHED;
;             PG8_LDB(B0, 1, 0); PG8_LDB(B1, 1, 1); PG8_SCHED; PG8_LDA(At, 1, 0); if (!fin) PG8_STAGE(PG8_SA(0, 1), a2 + hstep, voffA);
;             if (!fin) PG8_WAIT_V(8); else PG8_WAIT_V(0); PG8_WAIT_L(0); PG8_BAR; PG8_MMA(0, 0, At, B0); PG8_MMA(0, 1, At, B1); PG8_BAR; PG8_SCHED;
;             PG8_LDA(At, 1, 1); if (!fin) { PG8_STAGE(PG8_SB(1, 0), b3, voffB); PG8_STAGE(PG8_SB(1, 1), b3 + hstep, voffB); PG8_STAGE(PG8_SA(1, 0), a3, voffA); }
	s_setprio 0
	ds_read_b128 v[26:29], v236
	ds_read_b128 v[30:33], v236 offset:1024
	ds_read_b128 v[102:105], v236 offset:2048
	ds_read_b128 v[106:109], v236 offset:3072
	ds_read_b128 v[166:169], v237
	ds_read_b128 v[170:173], v237 offset:1024
	ds_read_b128 v[174:177], v237 offset:2048
	ds_read_b128 v[178:181], v237 offset:3072
	ds_read_b128 v[110:113], v235 offset:32768
	ds_read_b128 v[114:117], v235 offset:33792
	ds_read_b128 v[118:121], v235 offset:34816
	ds_read_b128 v[122:125], v235 offset:35840
	ds_read_b128 v[126:129], v235 offset:36864
	ds_read_b128 v[182:185], v235 offset:37888
	ds_read_b128 v[186:189], v235 offset:38912
	ds_read_b128 v[190:193], v235 offset:39936
	s_add_u32 s26, s52, 0x10100
	s_addc_u32 s27, s53, 0
	s_add_u32 m0, s14, 0x4000
	s_nop 0
	global_load_lds_dwordx4 v230, s[26:27]
	s_nop 0
	s_add_u32 m0, s14, 0x6000
	s_nop 0
	global_load_lds_dwordx4 v232, s[26:27]
	s_waitcnt vmcnt(8)
	s_waitcnt lgkmcnt(0)
	s_barrier
	v_mfma_f32_16x16x32_f16 v[82:85], v[26:29], v[126:129], v[82:85]
	s_setprio 1
	v_mfma_f32_16x16x32_f16 v[194:197], v[30:33], v[182:185], v[82:85]
	v_mfma_f32_16x16x32_f16 v[82:85], v[102:105], v[126:129], v[86:89]
	v_mfma_f32_16x16x32_f16 v[198:201], v[106:109], v[182:185], v[82:85]
	v_mfma_f32_16x16x32_f16 v[66:69], v[26:29], v[110:113], v[66:69]
	v_mfma_f32_16x16x32_f16 v[66:69], v[30:33], v[114:117], v[66:69]
	v_mfma_f32_16x16x32_f16 v[70:73], v[102:105], v[110:113], v[70:73]
	v_mfma_f32_16x16x32_f16 v[70:73], v[106:109], v[114:117], v[70:73]
	v_mfma_f32_16x16x32_f16 v[82:85], v[26:29], v[186:189], v[90:93]
	v_mfma_f32_16x16x32_f16 v[202:205], v[30:33], v[190:193], v[82:85]
	v_mfma_f32_16x16x32_f16 v[74:77], v[26:29], v[118:121], v[74:77]
	v_mfma_f32_16x16x32_f16 v[74:77], v[30:33], v[122:125], v[74:77]
	v_mfma_f32_16x16x32_f16 v[78:81], v[102:105], v[118:121], v[78:81]
	v_mfma_f32_16x16x32_f16 v[78:81], v[106:109], v[122:125], v[78:81]
	v_mfma_f32_16x16x32_f16 v[82:85], v[102:105], v[186:189], v[94:97]
	v_mfma_f32_16x16x32_f16 v[206:209], v[106:109], v[190:193], v[82:85]
	v_mfma_f32_16x16x32_f16 v[34:37], v[174:177], v[110:113], v[34:37]
	v_mfma_f32_16x16x32_f16 v[214:217], v[178:181], v[114:117], v[34:37]
	v_mfma_f32_16x16x32_f16 v[34:37], v[166:169], v[118:121], v[38:41]
	v_mfma_f32_16x16x32_f16 v[218:221], v[170:173], v[122:125], v[34:37]
	v_mfma_f32_16x16x32_f16 v[34:37], v[174:177], v[118:121], v[42:45]
	v_mfma_f32_16x16x32_f16 v[222:225], v[178:181], v[122:125], v[34:37]
	v_mfma_f32_16x16x32_f16 v[34:37], v[166:169], v[126:129], v[46:49]
	v_mfma_f32_16x16x32_f16 v[238:241], v[170:173], v[182:185], v[34:37]
	v_mfma_f32_16x16x32_f16 v[34:37], v[174:177], v[126:129], v[50:53]
	v_mfma_f32_16x16x32_f16 v[182:185], v[178:181], v[182:185], v[34:37]
	v_mfma_f32_16x16x32_f16 v[34:37], v[166:169], v[186:189], v[54:57]
	v_mfma_f32_16x16x32_f16 v[242:245], v[170:173], v[190:193], v[34:37]
	v_mfma_f32_16x16x32_f16 v[34:37], v[174:177], v[186:189], v[58:61]
	v_mfma_f32_16x16x32_f16 v[186:189], v[178:181], v[190:193], v[34:37]
	v_mfma_f32_16x16x32_f16 v[82:85], v[166:169], v[110:113], v[98:101]
	v_mfma_f32_16x16x32_f16 v[210:213], v[170:173], v[114:117], v[82:85]
	s_barrier
	s_setprio 0
	ds_read_b128 v[42:45], v235 offset:49152
	ds_read_b128 v[46:49], v235 offset:50176
	ds_read_b128 v[50:53], v235 offset:51200
	ds_read_b128 v[54:57], v235 offset:52224
	ds_read_b128 v[58:61], v235 offset:53248
	ds_read_b128 v[126:129], v235 offset:54272
	ds_read_b128 v[190:193], v235 offset:55296
	ds_read_b128 v[246:249], v235 offset:56320
	s_add_u32 m0, s14, 0x18000
	s_nop 0
	global_load_lds_dwordx4 v231, s[24:25]
	s_nop 0
	s_add_u32 m0, s14, 0x1a000
	s_nop 0
	global_load_lds_dwordx4 v233, s[24:25]
	s_add_u32 s24, s54, 0x10180
	s_addc_u32 s25, s55, 0
	s_add_u32 m0, s14, 0x1c000
	s_nop 0
	global_load_lds_dwordx4 v231, s[24:25]
	s_nop 0
	s_add_u32 m0, s14, 0x1e000
	s_nop 0
	global_load_lds_dwordx4 v233, s[24:25]
	s_nop 0
	s_add_u32 m0, s14, 0x8000
	s_nop 0
	global_load_lds_dwordx4 v230, s[8:9]
	s_nop 0
	s_add_u32 m0, s14, 0xa000
	s_nop 0
	global_load_lds_dwordx4 v232, s[8:9]
	s_waitcnt vmcnt(8)
	s_waitcnt lgkmcnt(0)
	s_barrier
; #define PG8_STAGE(bufoff, gbase, voff) do { if constexpr (ABL & 1) break; glds16s<(bufoff)>((voff)[0], (const void*)(gbase), ldsbw); glds16s<(bufoff) + 8192>((voff)[1], (const void*)(gbase), ldsbw); } while (0)
; #define PG8_LDA(dst, b, h) do { if constexpr (ABL & 4) break; _Pragma("unroll") for (int m = 0; m < 4; ++m) _Pragma("unroll") for (int k = 0; k < 2; ++k) dst[m][k] = *(const LAS f16x8*)(lds + PG8_SA(b, h) + aoff + m * 2048 + k * 1024); } while (0)
; #define PG8_LDB(dst, b, h) do { if constexpr (ABL & 4) break; _Pragma("unroll") for (int n = 0; n < 2; ++n) _Pragma("unroll") for (int k = 0; k < 2; ++k) dst[n][k] = *(const LAS f16x8*)(lds + PG8_SB(b, h) + boff + n * 2048 + k * 1024); } while (0)
; #define PG8_BAR __builtin_amdgcn_s_barrier()
;     ...
;         for (int t = 0; t < nt; t += 2) {
;             const bool last = (t == nt - 2);
;             const char* a1 = cA + (size_t)(t + 1) * kstep;
;             const char* a2 = last ? nA : cA + (size_t)(t + 2) * kstep; const char* b2 = last ? nB : cB + (size_t)(t + 2) * kstep;
;             const char* a3 = a2 + kstep; const char* b3 = b2 + kstep;
;             if (last && has_next) S.a_ready(nxt);
;             if constexpr (SP2) {
;             PG8_LDB(B0, 0, 0); PG8_LDB(B1, 0, 1); PG8_SCHED; PG8_LDA(At, 0, 0); PG8_STAGE(PG8_SA(1, 1), a1 + hstep, voffA);
;             PG8_WAIT_V(8); PG8_WAIT_L(0); PG8_BAR; PG8_MMAF(0, 0, At, B0); PG8_MMAF(0, 1, At, B1); PG8_BAR; PG8_SCHED;
;             const bool fin = last && !has_next;
;             PG8_LDA(At, 0, 1); if (!fin) { PG8_STAGE(PG8_SB(0, 0), b2, voffB); PG8_STAGE(PG8_SB(0, 1), b2 + hstep, voffB); PG8_STAGE(PG8_SA(0, 0), a2, voffA); }
;             if (!fin) PG8_WAIT_V(8); else PG8_WAIT_V(2); PG8_WAIT_L(0); PG8_BAR; PG8_MMAF(1, 0, At, B0); PG8_MMAF(1, 1, At, B1); PG8_BAR; PG8_SCHED;
;             PG8_LDB(B0, 1, 0); PG8_LDB(B1, 1, 1); PG8_SCHED; PG8_LDA(At, 1, 0); if (!fin) PG8_STAGE(PG8_SA(0, 1), a2 + hstep, voffA);
;             if (!fin) PG8_WAIT_V(8); else PG8_WAIT_V(0); PG8_WAIT_L(0); PG8_BAR; PG8_MMA(0, 0, At, B0); PG8_MMA(0, 1, At, B1); PG8_BAR; PG8_SCHED;
;             PG8_LDA(At, 1, 1); if (!fin) { PG8_STAGE(PG8_SB(1, 0), b3, voffB); PG8_STAGE(PG8_SB(1, 1), b3 + hstep, voffB); PG8_STAGE(PG8_SA(1, 0), a3, voffA); }
;             if (!fin) PG8_WAIT_V(8); PG8_WAIT_L(0); PG8_BAR; PG8_MMA(1, 0, At, B0); PG8_MMA(1, 1, At, B1); PG8_BAR; PG8_SCHED;
	v_mfma_f32_16x16x32_f16 v[2:5], v[26:29], v[190:193], v[2:5]
	s_setprio 1
	v_mfma_f32_16x16x32_f16 v[98:101], v[30:33], v[246:249], v[2:5]
	v_mfma_f32_16x16x32_f16 v[34:37], v[26:29], v[42:45], v[130:133]
	v_mfma_f32_16x16x32_f16 v[34:37], v[30:33], v[46:49], v[34:37]
	v_mfma_f32_16x16x32_f16 v[38:41], v[102:105], v[42:45], v[134:137]
	v_mfma_f32_16x16x32_f16 v[38:41], v[106:109], v[46:49], v[38:41]
	v_mfma_f32_16x16x32_f16 v[82:85], v[26:29], v[50:53], v[138:141]
	v_mfma_f32_16x16x32_f16 v[82:85], v[30:33], v[54:57], v[82:85]
	v_mfma_f32_16x16x32_f16 v[86:89], v[102:105], v[50:53], v[142:145]
	v_mfma_f32_16x16x32_f16 v[86:89], v[106:109], v[54:57], v[86:89]
	v_mfma_f32_16x16x32_f16 v[90:93], v[26:29], v[58:61], v[146:149]
	v_mfma_f32_16x16x32_f16 v[90:93], v[30:33], v[126:129], v[90:93]
	v_mfma_f32_16x16x32_f16 v[94:97], v[102:105], v[58:61], v[150:153]
	v_mfma_f32_16x16x32_f16 v[94:97], v[106:109], v[126:129], v[94:97]
	v_mfma_f32_16x16x32_f16 v[2:5], v[102:105], v[190:193], v[6:9]
	v_mfma_f32_16x16x32_f16 v[102:105], v[106:109], v[246:249], v[2:5]
	v_mfma_f32_16x16x32_f16 v[2:5], v[166:169], v[42:45], v[10:13]
	v_mfma_f32_16x16x32_f16 v[106:109], v[170:173], v[46:49], v[2:5]
	v_mfma_f32_16x16x32_f16 v[2:5], v[174:177], v[42:45], v[14:17]
	v_mfma_f32_16x16x32_f16 v[110:113], v[178:181], v[46:49], v[2:5]
	v_mfma_f32_16x16x32_f16 v[2:5], v[166:169], v[50:53], v[62:65]
	v_mfma_f32_16x16x32_f16 v[114:117], v[170:173], v[54:57], v[2:5]
	v_mfma_f32_16x16x32_f16 v[2:5], v[174:177], v[50:53], v[154:157]
	v_mfma_f32_16x16x32_f16 v[118:121], v[178:181], v[54:57], v[2:5]
	v_mfma_f32_16x16x32_f16 v[2:5], v[166:169], v[58:61], v[158:161]
	v_mfma_f32_16x16x32_f16 v[122:125], v[170:173], v[126:129], v[2:5]
	v_mfma_f32_16x16x32_f16 v[2:5], v[174:177], v[58:61], v[162:165]
	v_mfma_f32_16x16x32_f16 v[126:129], v[178:181], v[126:129], v[2:5]
	v_mfma_f32_16x16x32_f16 v[2:5], v[166:169], v[190:193], v[18:21]
	v_mfma_f32_16x16x32_f16 v[130:133], v[170:173], v[246:249], v[2:5]
	v_mfma_f32_16x16x32_f16 v[2:5], v[174:177], v[190:193], v[22:25]
	v_mfma_f32_16x16x32_f16 v[134:137], v[178:181], v[246:249], v[2:5]
	s_barrier
	s_setprio 0
	ds_read_b128 v[154:157], v1
	ds_read_b128 v[158:161], v1 offset:1024
	ds_read_b128 v[162:165], v1 offset:2048
	ds_read_b128 v[166:169], v1 offset:3072
	ds_read_b128 v[138:141], v234
	ds_read_b128 v[142:145], v234 offset:1024
	ds_read_b128 v[146:149], v234 offset:2048
	ds_read_b128 v[150:153], v234 offset:3072
	ds_read_b128 v[46:49], v235
	ds_read_b128 v[50:53], v235 offset:1024
	ds_read_b128 v[54:57], v235 offset:2048
	ds_read_b128 v[58:61], v235 offset:3072
	ds_read_b128 v[62:65], v235 offset:4096
	ds_read_b128 v[170:173], v235 offset:5120
	ds_read_b128 v[174:177], v235 offset:6144
	ds_read_b128 v[178:181], v235 offset:7168
	s_add_u32 s8, s52, 0x10180
	s_addc_u32 s9, s53, 0
	s_add_u32 m0, s14, 0xc000
	s_nop 0
	global_load_lds_dwordx4 v230, s[8:9]
	s_nop 0
	s_add_u32 m0, s14, 0xe000
	s_nop 0
	global_load_lds_dwordx4 v232, s[8:9]
	s_waitcnt vmcnt(8)
	s_waitcnt lgkmcnt(0)
	s_barrier
	v_mfma_f32_16x16x32_f16 v[2:5], v[154:157], v[46:49], v[66:69]
	s_setprio 1
	v_mfma_f32_16x16x32_f16 v[2:5], v[158:161], v[50:53], v[2:5]
	v_mfma_f32_16x16x32_f16 v[10:13], v[158:161], v[58:61], v[74:77]
	v_mfma_f32_16x16x32_f16 v[10:13], v[154:157], v[54:57], v[10:13]
	v_mfma_f32_16x16x32_f16 v[18:21], v[154:157], v[62:65], v[194:197]
	v_mfma_f32_16x16x32_f16 v[18:21], v[158:161], v[170:173], v[18:21]
	v_mfma_f32_16x16x32_f16 v[26:29], v[158:161], v[178:181], v[202:205]
	v_mfma_f32_16x16x32_f16 v[26:29], v[154:157], v[174:177], v[26:29]
	v_mfma_f32_16x16x32_f16 v[30:33], v[162:165], v[174:177], v[206:209]
	v_mfma_f32_16x16x32_f16 v[30:33], v[166:169], v[178:181], v[30:33]
	v_mfma_f32_16x16x32_f16 v[6:9], v[166:169], v[50:53], v[70:73]
	v_mfma_f32_16x16x32_f16 v[6:9], v[162:165], v[46:49], v[6:9]
	v_mfma_f32_16x16x32_f16 v[14:17], v[162:165], v[54:57], v[78:81]
	v_mfma_f32_16x16x32_f16 v[14:17], v[166:169], v[58:61], v[14:17]
	v_mfma_f32_16x16x32_f16 v[22:25], v[166:169], v[170:173], v[198:201]
	v_mfma_f32_16x16x32_f16 v[22:25], v[162:165], v[62:65], v[22:25]
	v_mfma_f32_16x16x32_f16 v[42:45], v[138:141], v[46:49], v[210:213]
	v_mfma_f32_16x16x32_f16 v[42:45], v[142:145], v[50:53], v[42:45]
	v_mfma_f32_16x16x32_f16 v[66:69], v[142:145], v[178:181], v[242:245]
	v_mfma_f32_16x16x32_f16 v[66:69], v[138:141], v[174:177], v[66:69]
	v_mfma_f32_16x16x32_f16 v[70:73], v[146:149], v[174:177], v[186:189]
	v_mfma_f32_16x16x32_f16 v[70:73], v[150:153], v[178:181], v[70:73]
	v_mfma_f32_16x16x32_f16 v[46:49], v[146:149], v[46:49], v[214:217]
	v_mfma_f32_16x16x32_f16 v[46:49], v[150:153], v[50:53], v[46:49]
	v_mfma_f32_16x16x32_f16 v[50:53], v[138:141], v[54:57], v[218:221]
	v_mfma_f32_16x16x32_f16 v[50:53], v[142:145], v[58:61], v[50:53]
	v_mfma_f32_16x16x32_f16 v[54:57], v[146:149], v[54:57], v[222:225]
	v_mfma_f32_16x16x32_f16 v[54:57], v[150:153], v[58:61], v[54:57]
	v_mfma_f32_16x16x32_f16 v[58:61], v[138:141], v[62:65], v[238:241]
	v_mfma_f32_16x16x32_f16 v[58:61], v[142:145], v[170:173], v[58:61]
	v_mfma_f32_16x16x32_f16 v[62:65], v[146:149], v[62:65], v[182:185]
	v_mfma_f32_16x16x32_f16 v[62:65], v[150:153], v[170:173], v[62:65]
	s_barrier
	s_setprio 0
	ds_read_b128 v[194:197], v235 offset:16384
	ds_read_b128 v[198:201], v235 offset:17408
	ds_read_b128 v[186:189], v235 offset:18432
	ds_read_b128 v[190:193], v235 offset:19456
	ds_read_b128 v[178:181], v235 offset:20480
	ds_read_b128 v[182:185], v235 offset:21504
	ds_read_b128 v[170:173], v235 offset:22528
	ds_read_b128 v[174:177], v235 offset:23552
	s_mov_b64 s[8:9], -1
	s_and_b64 vcc, exec, s[4:5]
	s_cbranch_vccz .LBB0_880
	s_waitcnt vmcnt(2)
	s_mov_b64 s[8:9], 0

; #define PG8_STAGE(bufoff, gbase, voff) do { if constexpr (ABL & 1) break; glds16s<(bufoff)>((voff)[0], (const void*)(gbase), ldsbw); glds16s<(bufoff) + 8192>((voff)[1], (const void*)(gbase), ldsbw); } while (0)
; #define PG8_LDA(dst, b, h) do { if constexpr (ABL & 4) break; _Pragma("unroll") for (int m = 0; m < 4; ++m) _Pragma("unroll") for (int k = 0; k < 2; ++k) dst[m][k] = *(const LAS f16x8*)(lds + PG8_SA(b, h) + aoff + m * 2048 + k * 1024); } while (0)
; #define PG8_LDB(dst, b, h) do { if constexpr (ABL & 4) break; _Pragma("unroll") for (int n = 0; n < 2; ++n) _Pragma("unroll") for (int k = 0; k < 2; ++k) dst[n][k] = *(const LAS f16x8*)(lds + PG8_SB(b, h) + boff + n * 2048 + k * 1024); } while (0)
; #define PG8_MMAF(ai, bj, At, Bt) do { if (t == 0) PG8_MMA0(ai, bj, At, Bt); else PG8_MMA(ai, bj, At, Bt); } while (0)
; #define PG8_WAIT_V(n) asm volatile("s_waitcnt vmcnt(" #n ")" ::: "memory")
; #define PG8_WAIT_L(n) asm volatile("s_waitcnt lgkmcnt(" #n ")" ::: "memory")
; #define PG8_BAR __builtin_amdgcn_s_barrier()
; #define PG8_SCHED __builtin_amdgcn_sched_barrier(0)
;     ...
;         for (int t = 0; t < nt; t += 2) {
;             const bool last = (t == nt - 2);
;             const char* a1 = cA + (size_t)(t + 1) * kstep;
;             const char* a2 = last ? nA : cA + (size_t)(t + 2) * kstep; const char* b2 = last ? nB : cB + (size_t)(t + 2) * kstep;
;             const char* a3 = a2 + kstep; const char* b3 = b2 + kstep;
;             if (last && has_next) S.a_ready(nxt);
;             if constexpr (SP2) {
;             PG8_LDB(B0, 0, 0); PG8_LDB(B1, 0, 1); PG8_SCHED; PG8_LDA(At, 0, 0); PG8_STAGE(PG8_SA(1, 1), a1 + hstep, voffA);
;             PG8_WAIT_V(8); PG8_WAIT_L(0); PG8_BAR; PG8_MMAF(0, 0, At, B0); PG8_MMAF(0, 1, At, B1); PG8_BAR; PG8_SCHED;
;             const bool fin = last && !has_next;
;             PG8_LDA(At, 0, 1); if (!fin) { PG8_STAGE(PG8_SB(0, 0), b2, voffB); PG8_STAGE(PG8_SB(0, 1), b2 + hstep, voffB); PG8_STAGE(PG8_SA(0, 0), a2, voffA); }
;             if (!fin) PG8_WAIT_V(8); else PG8_WAIT_V(2); PG8_WAIT_L(0); PG8_BAR; PG8_MMAF(1, 0, At, B0); PG8_MMAF(1, 1, At, B1); PG8_BAR; PG8_SCHED;
.LBB0_987:
	s_waitcnt lgkmcnt(0)
	ds_read_b128 v[2:5], v213
	ds_read_b128 v[6:9], v213 offset:1024
	ds_read_b128 v[10:13], v213 offset:2048
	ds_read_b128 v[14:17], v213 offset:3072
	ds_read_b128 v[18:21], v214
	ds_read_b128 v[22:25], v214 offset:1024
	ds_read_b128 v[26:29], v214 offset:2048
	ds_read_b128 v[30:33], v214 offset:3072
	s_add_u32 s50, s54, 0x100
	s_addc_u32 s51, s55, 0
	s_add_u32 s24, s52, 0x100
	s_addc_u32 s25, s53, 0
	s_add_u32 s6, s54, 0x180
	s_addc_u32 s7, s55, 0
	ds_read_b128 v[34:37], v215
	ds_read_b128 v[38:41], v215 offset:1024
	ds_read_b128 v[42:45], v215 offset:2048
	ds_read_b128 v[46:49], v215 offset:3072
	ds_read_b128 v[50:53], v215 offset:4096
	ds_read_b128 v[54:57], v215 offset:5120
	ds_read_b128 v[58:61], v215 offset:6144
	ds_read_b128 v[62:65], v215 offset:7168
	s_add_u32 s8, s52, 0x180
	s_addc_u32 s9, s53, 0
	s_add_u32 s26, s54, 0xb0080
	s_addc_u32 s27, s55, 0
	s_add_u32 m0, s28, 0xc000
	s_nop 0
	global_load_lds_dwordx4 v1, s[26:27]
	s_nop 0
	s_add_u32 m0, s28, 0xe000
	s_nop 0
	global_load_lds_dwordx4 v211, s[26:27]
	s_waitcnt vmcnt(8)
	s_waitcnt lgkmcnt(0)
	s_barrier
	v_mfma_f32_16x16x32_f16 v[70:73], v[10:13], v[34:37], 0
	s_setprio 1
	v_mfma_f32_16x16x32_f16 v[70:73], v[14:17], v[38:41], v[70:73]
	v_mfma_f32_16x16x32_f16 v[74:77], v[2:5], v[42:45], 0
	v_mfma_f32_16x16x32_f16 v[74:77], v[6:9], v[46:49], v[74:77]
	v_mfma_f32_16x16x32_f16 v[82:85], v[2:5], v[50:53], 0
	v_mfma_f32_16x16x32_f16 v[82:85], v[6:9], v[54:57], v[82:85]
	v_mfma_f32_16x16x32_f16 v[86:89], v[10:13], v[50:53], 0
	v_mfma_f32_16x16x32_f16 v[86:89], v[14:17], v[54:57], v[86:89]
	v_mfma_f32_16x16x32_f16 v[94:97], v[10:13], v[58:61], 0
	v_mfma_f32_16x16x32_f16 v[94:97], v[14:17], v[62:65], v[94:97]
	v_mfma_f32_16x16x32_f16 v[66:69], v[2:5], v[34:37], 0
	v_mfma_f32_16x16x32_f16 v[66:69], v[6:9], v[38:41], v[66:69]
	v_mfma_f32_16x16x32_f16 v[78:81], v[10:13], v[42:45], 0
	v_mfma_f32_16x16x32_f16 v[78:81], v[14:17], v[46:49], v[78:81]
	v_mfma_f32_16x16x32_f16 v[90:93], v[2:5], v[58:61], 0
	v_mfma_f32_16x16x32_f16 v[90:93], v[6:9], v[62:65], v[90:93]
	v_mfma_f32_16x16x32_f16 v[98:101], v[18:21], v[34:37], 0
	v_mfma_f32_16x16x32_f16 v[98:101], v[22:25], v[38:41], v[98:101]
	v_mfma_f32_16x16x32_f16 v[34:37], v[26:29], v[34:37], 0
	v_mfma_f32_16x16x32_f16 v[34:37], v[30:33], v[38:41], v[34:37]
	v_mfma_f32_16x16x32_f16 v[38:41], v[18:21], v[42:45], 0
	v_mfma_f32_16x16x32_f16 v[38:41], v[22:25], v[46:49], v[38:41]
	v_mfma_f32_16x16x32_f16 v[42:45], v[26:29], v[42:45], 0
	v_mfma_f32_16x16x32_f16 v[42:45], v[30:33], v[46:49], v[42:45]
	v_mfma_f32_16x16x32_f16 v[46:49], v[18:21], v[50:53], 0
	v_mfma_f32_16x16x32_f16 v[46:49], v[22:25], v[54:57], v[46:49]
	v_mfma_f32_16x16x32_f16 v[50:53], v[26:29], v[50:53], 0
	v_mfma_f32_16x16x32_f16 v[50:53], v[30:33], v[54:57], v[50:53]
	v_mfma_f32_16x16x32_f16 v[54:57], v[18:21], v[58:61], 0
	v_mfma_f32_16x16x32_f16 v[54:57], v[22:25], v[62:65], v[54:57]
	v_mfma_f32_16x16x32_f16 v[58:61], v[26:29], v[58:61], 0
	v_mfma_f32_16x16x32_f16 v[58:61], v[30:33], v[62:65], v[58:61]
	s_barrier
	s_setprio 0
	ds_read_b128 v[62:65], v215 offset:16384
	ds_read_b128 v[102:105], v215 offset:17408
	ds_read_b128 v[106:109], v215 offset:18432
	ds_read_b128 v[110:113], v215 offset:19456
	ds_read_b128 v[114:117], v215 offset:20480
	ds_read_b128 v[118:121], v215 offset:21504
	ds_read_b128 v[122:125], v215 offset:22528
	ds_read_b128 v[126:129], v215 offset:23552
	s_add_u32 m0, s28, 0x10000
	s_nop 0
	global_load_lds_dwordx4 v210, s[24:25]
	s_nop 0
	s_add_u32 m0, s28, 0x12000
	s_nop 0
	global_load_lds_dwordx4 v212, s[24:25]
	s_add_u32 s24, s52, 0xb0100
	s_addc_u32 s25, s53, 0
	s_add_u32 m0, s28, 0x14000
	s_nop 0
	global_load_lds_dwordx4 v210, s[24:25]
	s_nop 0
	s_add_u32 m0, s28, 0x16000
	s_nop 0
	global_load_lds_dwordx4 v212, s[24:25]
	s_nop 0
	s_add_u32 m0, s28, 0
	s_nop 0
	global_load_lds_dwordx4 v1, s[50:51]
	s_nop 0
	s_add_u32 m0, s28, 0x2000
	s_nop 0
	global_load_lds_dwordx4 v211, s[50:51]
	s_waitcnt vmcnt(8)
	s_waitcnt lgkmcnt(0)
	s_barrier
	v_mfma_f32_16x16x32_f16 v[130:133], v[2:5], v[62:65], 0
	s_setprio 1
	v_mfma_f32_16x16x32_f16 v[138:141], v[6:9], v[102:105], v[130:133]
	v_mfma_f32_16x16x32_f16 v[130:133], v[10:13], v[62:65], 0
	v_mfma_f32_16x16x32_f16 v[158:161], v[14:17], v[102:105], v[130:133]
	v_mfma_f32_16x16x32_f16 v[130:133], v[2:5], v[106:109], 0
	v_mfma_f32_16x16x32_f16 v[162:165], v[6:9], v[110:113], v[130:133]
	v_mfma_f32_16x16x32_f16 v[130:133], v[10:13], v[106:109], 0
	v_mfma_f32_16x16x32_f16 v[166:169], v[14:17], v[110:113], v[130:133]
	v_mfma_f32_16x16x32_f16 v[130:133], v[2:5], v[114:117], 0
	v_mfma_f32_16x16x32_f16 v[170:173], v[6:9], v[118:121], v[130:133]
	v_mfma_f32_16x16x32_f16 v[2:5], v[2:5], v[122:125], 0
	v_mfma_f32_16x16x32_f16 v[2:5], v[6:9], v[126:129], v[2:5]
	v_mfma_f32_16x16x32_f16 v[6:9], v[10:13], v[122:125], 0
	v_mfma_f32_16x16x32_f16 v[6:9], v[14:17], v[126:129], v[6:9]
	v_mfma_f32_16x16x32_f16 v[130:133], v[10:13], v[114:117], 0
	v_mfma_f32_16x16x32_f16 v[174:177], v[14:17], v[118:121], v[130:133]
	v_mfma_f32_16x16x32_f16 v[10:13], v[18:21], v[62:65], 0
	v_mfma_f32_16x16x32_f16 v[178:181], v[22:25], v[102:105], v[10:13]
	v_mfma_f32_16x16x32_f16 v[10:13], v[26:29], v[62:65], 0
	v_mfma_f32_16x16x32_f16 v[102:105], v[30:33], v[102:105], v[10:13]
	v_mfma_f32_16x16x32_f16 v[10:13], v[18:21], v[106:109], 0
	v_mfma_f32_16x16x32_f16 v[182:185], v[22:25], v[110:113], v[10:13]
	v_mfma_f32_16x16x32_f16 v[10:13], v[26:29], v[106:109], 0
	v_mfma_f32_16x16x32_f16 v[186:189], v[30:33], v[110:113], v[10:13]
	v_mfma_f32_16x16x32_f16 v[10:13], v[18:21], v[114:117], 0
	v_mfma_f32_16x16x32_f16 v[190:193], v[22:25], v[118:121], v[10:13]
	v_mfma_f32_16x16x32_f16 v[10:13], v[26:29], v[114:117], 0
	v_mfma_f32_16x16x32_f16 v[114:117], v[30:33], v[118:121], v[10:13]
	v_mfma_f32_16x16x32_f16 v[10:13], v[18:21], v[122:125], 0
	v_mfma_f32_16x16x32_f16 v[194:197], v[22:25], v[126:129], v[10:13]
	v_mfma_f32_16x16x32_f16 v[10:13], v[26:29], v[122:125], 0
	v_mfma_f32_16x16x32_f16 v[126:129], v[30:33], v[126:129], v[10:13]
	s_barrier
; #define PG8_STAGE(bufoff, gbase, voff) do { if constexpr (ABL & 1) break; glds16s<(bufoff)>((voff)[0], (const void*)(gbase), ldsbw); glds16s<(bufoff) + 8192>((voff)[1], (const void*)(gbase), ldsbw); } while (0)
; #define PG8_LDA(dst, b, h) do { if constexpr (ABL & 4) break; _Pragma("unroll") for (int m = 0; m < 4; ++m) _Pragma("unroll") for (int k = 0; k < 2; ++k) dst[m][k] = *(const LAS f16x8*)(lds + PG8_SA(b, h) + aoff + m * 2048 + k * 1024); } while (0)
; #define PG8_LDB(dst, b, h) do { if constexpr (ABL & 4) break; _Pragma("unroll") for (int n = 0; n < 2; ++n) _Pragma("unroll") for (int k = 0; k < 2; ++k) dst[n][k] = *(const LAS f16x8*)(lds + PG8_SB(b, h) + boff + n * 2048 + k * 1024); } while (0)
; #define PG8_MMA(ai, bj, At, Bt) do { if constexpr (ABL & 2) break; __builtin_amdgcn_s_setprio(1); _Pragma("unroll") for (int m = 0; m < 4; ++m) _Pragma("unroll") for (int n = 0; n < 2; ++n) _Pragma("unroll") for (int k = 0; k < 2; ++k) \
;         acc[ai][bj][m][n] = __builtin_amdgcn_mfma_f32_16x16x32_f16(Bt[n][k], At[m][k], acc[ai][bj][m][n], 0, 0, 0); __builtin_amdgcn_s_setprio(0); } while (0)
; #define PG8_MMAF(ai, bj, At, Bt) do { if (t == 0) PG8_MMA0(ai, bj, At, Bt); else PG8_MMA(ai, bj, At, Bt); } while (0)
; #define PG8_WAIT_V(n) asm volatile("s_waitcnt vmcnt(" #n ")" ::: "memory")
; #define PG8_WAIT_L(n) asm volatile("s_waitcnt lgkmcnt(" #n ")" ::: "memory")
; #define PG8_BAR __builtin_amdgcn_s_barrier()
; #define PG8_SCHED __builtin_amdgcn_sched_barrier(0)
;     ...
;             if (!fin) PG8_WAIT_V(8); else PG8_WAIT_V(2); PG8_WAIT_L(0); PG8_BAR; PG8_MMAF(1, 0, At, B0); PG8_MMAF(1, 1, At, B1); PG8_BAR; PG8_SCHED;
;             PG8_LDB(B0, 1, 0); PG8_LDB(B1, 1, 1); PG8_SCHED; PG8_LDA(At, 1, 0); if (!fin) PG8_STAGE(PG8_SA(0, 1), a2 + hstep, voffA);
;             if (!fin) PG8_WAIT_V(8); else PG8_WAIT_V(0); PG8_WAIT_L(0); PG8_BAR; PG8_MMA(0, 0, At, B0); PG8_MMA(0, 1, At, B1); PG8_BAR; PG8_SCHED;
;             PG8_LDA(At, 1, 1); if (!fin) { PG8_STAGE(PG8_SB(1, 0), b3, voffB); PG8_STAGE(PG8_SB(1, 1), b3 + hstep, voffB); PG8_STAGE(PG8_SA(1, 0), a3, voffA); }
;             if (!fin) PG8_WAIT_V(8); PG8_WAIT_L(0); PG8_BAR; PG8_MMA(1, 0, At, B0); PG8_MMA(1, 1, At, B1); PG8_BAR; PG8_SCHED;
	s_setprio 0
	s_nop 4
	ds_read_b128 v[10:13], v216
	ds_read_b128 v[14:17], v216 offset:1024
	ds_read_b128 v[18:21], v216 offset:2048
	ds_read_b128 v[22:25], v216 offset:3072
	ds_read_b128 v[198:201], v217
	ds_read_b128 v[202:205], v217 offset:1024
	ds_read_b128 v[220:223], v217 offset:2048
	ds_read_b128 v[224:227], v217 offset:3072
	ds_read_b128 v[26:29], v215 offset:32768
	ds_read_b128 v[30:33], v215 offset:33792
	ds_read_b128 v[62:65], v215 offset:34816
	ds_read_b128 v[118:121], v215 offset:35840
	ds_read_b128 v[228:231], v215 offset:36864
	ds_read_b128 v[232:235], v215 offset:37888
	ds_read_b128 v[236:239], v215 offset:38912
	ds_read_b128 v[240:243], v215 offset:39936
	s_add_u32 s24, s54, 0xb0100
	s_addc_u32 s25, s55, 0
	s_add_u32 m0, s28, 0x4000
	s_nop 0
	global_load_lds_dwordx4 v1, s[24:25]
	s_nop 0
	s_add_u32 m0, s28, 0x6000
	s_nop 0
	global_load_lds_dwordx4 v211, s[24:25]
	s_waitcnt vmcnt(8)
	s_waitcnt lgkmcnt(0)
	s_barrier
	v_mfma_f32_16x16x32_f16 v[66:69], v[10:13], v[26:29], v[66:69]
	s_setprio 1
	v_mfma_f32_16x16x32_f16 v[154:157], v[14:17], v[30:33], v[66:69]
	v_mfma_f32_16x16x32_f16 v[66:69], v[18:21], v[26:29], v[70:73]
	v_mfma_f32_16x16x32_f16 v[150:153], v[22:25], v[30:33], v[66:69]
	v_mfma_f32_16x16x32_f16 v[66:69], v[10:13], v[62:65], v[74:77]
	v_mfma_f32_16x16x32_f16 v[134:137], v[14:17], v[118:121], v[66:69]
	v_mfma_f32_16x16x32_f16 v[66:69], v[18:21], v[62:65], v[78:81]
	v_mfma_f32_16x16x32_f16 v[130:133], v[22:25], v[118:121], v[66:69]
	v_mfma_f32_16x16x32_f16 v[66:69], v[10:13], v[228:231], v[82:85]
	v_mfma_f32_16x16x32_f16 v[110:113], v[14:17], v[232:235], v[66:69]
	v_mfma_f32_16x16x32_f16 v[66:69], v[18:21], v[228:231], v[86:89]
	v_mfma_f32_16x16x32_f16 v[106:109], v[22:25], v[232:235], v[66:69]
	v_mfma_f32_16x16x32_f16 v[66:69], v[10:13], v[236:239], v[90:93]
	v_mfma_f32_16x16x32_f16 v[86:89], v[14:17], v[240:243], v[66:69]
	v_mfma_f32_16x16x32_f16 v[66:69], v[18:21], v[236:239], v[94:97]
	v_mfma_f32_16x16x32_f16 v[82:85], v[22:25], v[240:243], v[66:69]
	v_mfma_f32_16x16x32_f16 v[66:69], v[198:201], v[26:29], v[98:101]
	v_mfma_f32_16x16x32_f16 v[146:149], v[202:205], v[30:33], v[66:69]
	v_mfma_f32_16x16x32_f16 v[26:29], v[220:223], v[26:29], v[34:37]
	v_mfma_f32_16x16x32_f16 v[142:145], v[224:227], v[30:33], v[26:29]
	v_mfma_f32_16x16x32_f16 v[26:29], v[198:201], v[62:65], v[38:41]
	v_mfma_f32_16x16x32_f16 v[122:125], v[202:205], v[118:121], v[26:29]
	v_mfma_f32_16x16x32_f16 v[26:29], v[220:223], v[62:65], v[42:45]
	v_mfma_f32_16x16x32_f16 v[118:121], v[224:227], v[118:121], v[26:29]
	v_mfma_f32_16x16x32_f16 v[26:29], v[198:201], v[228:231], v[46:49]
	v_mfma_f32_16x16x32_f16 v[98:101], v[202:205], v[232:235], v[26:29]
	v_mfma_f32_16x16x32_f16 v[26:29], v[220:223], v[228:231], v[50:53]
	v_mfma_f32_16x16x32_f16 v[94:97], v[224:227], v[232:235], v[26:29]
	v_mfma_f32_16x16x32_f16 v[26:29], v[198:201], v[236:239], v[54:57]
	v_mfma_f32_16x16x32_f16 v[74:77], v[202:205], v[240:243], v[26:29]
	v_mfma_f32_16x16x32_f16 v[26:29], v[220:223], v[236:239], v[58:61]
	v_mfma_f32_16x16x32_f16 v[70:73], v[224:227], v[240:243], v[26:29]
	s_barrier
	s_setprio 0
	ds_read_b128 v[34:37], v215 offset:49152
	ds_read_b128 v[38:41], v215 offset:50176
	ds_read_b128 v[66:69], v215 offset:51200
	ds_read_b128 v[78:81], v215 offset:52224
	ds_read_b128 v[90:93], v215 offset:53248
	ds_read_b128 v[228:231], v215 offset:54272
	ds_read_b128 v[232:235], v215 offset:55296
	ds_read_b128 v[236:239], v215 offset:56320
	s_add_u32 m0, s28, 0x18000
	s_nop 0
	global_load_lds_dwordx4 v210, s[8:9]
	s_nop 0
	s_add_u32 m0, s28, 0x1a000
	s_nop 0
	global_load_lds_dwordx4 v212, s[8:9]
	s_add_u32 s8, s52, 0xb0180
	s_addc_u32 s9, s53, 0
	s_add_u32 m0, s28, 0x1c000
	s_nop 0
	global_load_lds_dwordx4 v210, s[8:9]
	s_nop 0
	s_add_u32 m0, s28, 0x1e000
	s_nop 0
	global_load_lds_dwordx4 v212, s[8:9]
	s_nop 0
	s_add_u32 m0, s28, 0x8000
	s_nop 0
	global_load_lds_dwordx4 v1, s[6:7]
	s_nop 0
	s_add_u32 m0, s28, 0xa000
	s_nop 0
	global_load_lds_dwordx4 v211, s[6:7]
	s_waitcnt vmcnt(8)
	s_waitcnt lgkmcnt(0)
	s_barrier
	v_mfma_f32_16x16x32_f16 v[26:29], v[10:13], v[34:37], v[138:141]
	s_setprio 1
	v_mfma_f32_16x16x32_f16 v[62:65], v[14:17], v[38:41], v[26:29]
	v_mfma_f32_16x16x32_f16 v[26:29], v[22:25], v[38:41], v[158:161]
	v_mfma_f32_16x16x32_f16 v[58:61], v[18:21], v[34:37], v[26:29]
	v_mfma_f32_16x16x32_f16 v[26:29], v[10:13], v[66:69], v[162:165]
	v_mfma_f32_16x16x32_f16 v[46:49], v[14:17], v[78:81], v[26:29]
	v_mfma_f32_16x16x32_f16 v[26:29], v[22:25], v[78:81], v[166:169]
	v_mfma_f32_16x16x32_f16 v[42:45], v[18:21], v[66:69], v[26:29]
	v_mfma_f32_16x16x32_f16 v[26:29], v[10:13], v[90:93], v[170:173]
	v_mfma_f32_16x16x32_f16 v[30:33], v[14:17], v[228:231], v[26:29]
	v_mfma_f32_16x16x32_f16 v[26:29], v[22:25], v[228:231], v[174:177]
	v_mfma_f32_16x16x32_f16 v[26:29], v[18:21], v[90:93], v[26:29]
	v_mfma_f32_16x16x32_f16 v[2:5], v[10:13], v[232:235], v[2:5]
	v_mfma_f32_16x16x32_f16 v[14:17], v[14:17], v[236:239], v[2:5]
	v_mfma_f32_16x16x32_f16 v[2:5], v[22:25], v[236:239], v[6:9]
	v_mfma_f32_16x16x32_f16 v[10:13], v[18:21], v[232:235], v[2:5]
	v_mfma_f32_16x16x32_f16 v[2:5], v[198:201], v[34:37], v[178:181]
	v_mfma_f32_16x16x32_f16 v[54:57], v[202:205], v[38:41], v[2:5]
	v_mfma_f32_16x16x32_f16 v[2:5], v[224:227], v[38:41], v[102:105]
	v_mfma_f32_16x16x32_f16 v[50:53], v[220:223], v[34:37], v[2:5]
	v_mfma_f32_16x16x32_f16 v[2:5], v[198:201], v[66:69], v[182:185]
	v_mfma_f32_16x16x32_f16 v[38:41], v[202:205], v[78:81], v[2:5]
	v_mfma_f32_16x16x32_f16 v[2:5], v[224:227], v[78:81], v[186:189]
	v_mfma_f32_16x16x32_f16 v[34:37], v[220:223], v[66:69], v[2:5]
	v_mfma_f32_16x16x32_f16 v[2:5], v[198:201], v[90:93], v[190:193]
	v_mfma_f32_16x16x32_f16 v[22:25], v[202:205], v[228:231], v[2:5]
	v_mfma_f32_16x16x32_f16 v[2:5], v[224:227], v[228:231], v[114:117]
	v_mfma_f32_16x16x32_f16 v[18:21], v[220:223], v[90:93], v[2:5]
	v_mfma_f32_16x16x32_f16 v[2:5], v[198:201], v[232:235], v[194:197]
	v_mfma_f32_16x16x32_f16 v[6:9], v[202:205], v[236:239], v[2:5]
	v_mfma_f32_16x16x32_f16 v[2:5], v[224:227], v[236:239], v[126:129]
	v_mfma_f32_16x16x32_f16 v[2:5], v[220:223], v[232:235], v[2:5]
	s_barrier
	s_setprio 0
	s_add_u32 s52, s52, 0x200
	s_addc_u32 s53, s53, 0
	s_mov_b32 s54, 0
	s_branch .LBB0_989
; #define PG8_STAGE(bufoff, gbase, voff) do { if constexpr (ABL & 1) break; glds16s<(bufoff)>((voff)[0], (const void*)(gbase), ldsbw); glds16s<(bufoff) + 8192>((voff)[1], (const void*)(gbase), ldsbw); } while (0)
; #define PG8_LDA(dst, b, h) do { if constexpr (ABL & 4) break; _Pragma("unroll") for (int m = 0; m < 4; ++m) _Pragma("unroll") for (int k = 0; k < 2; ++k) dst[m][k] = *(const LAS f16x8*)(lds + PG8_SA(b, h) + aoff + m * 2048 + k * 1024); } while (0)
; #define PG8_LDB(dst, b, h) do { if constexpr (ABL & 4) break; _Pragma("unroll") for (int n = 0; n < 2; ++n) _Pragma("unroll") for (int k = 0; k < 2; ++k) dst[n][k] = *(const LAS f16x8*)(lds + PG8_SB(b, h) + boff + n * 2048 + k * 1024); } while (0)
; #define PG8_BAR __builtin_amdgcn_s_barrier()
;     ...
;         for (int t = 0; t < nt; t += 2) {
;             const bool last = (t == nt - 2);
;             const char* a1 = cA + (size_t)(t + 1) * kstep;
;             const char* a2 = last ? nA : cA + (size_t)(t + 2) * kstep; const char* b2 = last ? nB : cB + (size_t)(t + 2) * kstep;
;             const char* a3 = a2 + kstep; const char* b3 = b2 + kstep;
;             if (last && has_next) S.a_ready(nxt);
;             if constexpr (SP2) {
;             PG8_LDB(B0, 0, 0); PG8_LDB(B1, 0, 1); PG8_SCHED; PG8_LDA(At, 0, 0); PG8_STAGE(PG8_SA(1, 1), a1 + hstep, voffA);
;             PG8_WAIT_V(8); PG8_WAIT_L(0); PG8_BAR; PG8_MMAF(0, 0, At, B0); PG8_MMAF(0, 1, At, B1); PG8_BAR; PG8_SCHED;
;             const bool fin = last && !has_next;
;             PG8_LDA(At, 0, 1); if (!fin) { PG8_STAGE(PG8_SB(0, 0), b2, voffB); PG8_STAGE(PG8_SB(0, 1), b2 + hstep, voffB); PG8_STAGE(PG8_SA(0, 0), a2, voffA); }
;             if (!fin) PG8_WAIT_V(8); else PG8_WAIT_V(2); PG8_WAIT_L(0); PG8_BAR; PG8_MMAF(1, 0, At, B0); PG8_MMAF(1, 1, At, B1); PG8_BAR; PG8_SCHED;
;             PG8_LDB(B0, 1, 0); PG8_LDB(B1, 1, 1); PG8_SCHED; PG8_LDA(At, 1, 0); if (!fin) PG8_STAGE(PG8_SA(0, 1), a2 + hstep, voffA);
;             if (!fin) PG8_WAIT_V(8); else PG8_WAIT_V(0); PG8_WAIT_L(0); PG8_BAR; PG8_MMA(0, 0, At, B0); PG8_MMA(0, 1, At, B1); PG8_BAR; PG8_SCHED;
;             PG8_LDA(At, 1, 1); if (!fin) { PG8_STAGE(PG8_SB(1, 0), b3, voffB); PG8_STAGE(PG8_SB(1, 1), b3 + hstep, voffB); PG8_STAGE(PG8_SA(1, 0), a3, voffA); }
;             if (!fin) PG8_WAIT_V(8); PG8_WAIT_L(0); PG8_BAR; PG8_MMA(1, 0, At, B0); PG8_MMA(1, 1, At, B1); PG8_BAR; PG8_SCHED;
.LBB0_988:
	s_waitcnt lgkmcnt(0)
	s_barrier
	v_mfma_f32_16x16x32_f16 v[62:65], v[166:169], v[186:189], v[62:65]
	s_setprio 1
	v_mfma_f32_16x16x32_f16 v[62:65], v[170:173], v[190:193], v[62:65]
	v_mfma_f32_16x16x32_f16 v[46:49], v[170:173], v[182:185], v[46:49]
	v_mfma_f32_16x16x32_f16 v[46:49], v[166:169], v[178:181], v[46:49]
	v_mfma_f32_16x16x32_f16 v[30:33], v[166:169], v[138:141], v[30:33]
	v_mfma_f32_16x16x32_f16 v[30:33], v[170:173], v[174:177], v[30:33]
	v_mfma_f32_16x16x32_f16 v[14:17], v[170:173], v[126:129], v[14:17]
	v_mfma_f32_16x16x32_f16 v[14:17], v[166:169], v[114:117], v[14:17]
	v_mfma_f32_16x16x32_f16 v[10:13], v[158:161], v[114:117], v[10:13]
	v_mfma_f32_16x16x32_f16 v[10:13], v[162:165], v[126:129], v[10:13]
	v_mfma_f32_16x16x32_f16 v[58:61], v[162:165], v[190:193], v[58:61]
	v_mfma_f32_16x16x32_f16 v[58:61], v[158:161], v[186:189], v[58:61]
	v_mfma_f32_16x16x32_f16 v[42:45], v[158:161], v[178:181], v[42:45]
	v_mfma_f32_16x16x32_f16 v[42:45], v[162:165], v[182:185], v[42:45]
	v_mfma_f32_16x16x32_f16 v[26:29], v[162:165], v[174:177], v[26:29]
	v_mfma_f32_16x16x32_f16 v[26:29], v[158:161], v[138:141], v[26:29]
	v_mfma_f32_16x16x32_f16 v[22:25], v[90:93], v[138:141], v[22:25]
	v_mfma_f32_16x16x32_f16 v[22:25], v[102:105], v[174:177], v[22:25]
	v_mfma_f32_16x16x32_f16 v[54:57], v[102:105], v[190:193], v[54:57]
	v_mfma_f32_16x16x32_f16 v[54:57], v[90:93], v[186:189], v[54:57]
	v_mfma_f32_16x16x32_f16 v[38:41], v[90:93], v[178:181], v[38:41]
	v_mfma_f32_16x16x32_f16 v[38:41], v[102:105], v[182:185], v[38:41]
	v_mfma_f32_16x16x32_f16 v[6:9], v[102:105], v[126:129], v[6:9]
	v_mfma_f32_16x16x32_f16 v[6:9], v[90:93], v[114:117], v[6:9]
	v_mfma_f32_16x16x32_f16 v[2:5], v[66:69], v[114:117], v[2:5]
	v_mfma_f32_16x16x32_f16 v[2:5], v[78:81], v[126:129], v[2:5]
	v_mfma_f32_16x16x32_f16 v[50:53], v[78:81], v[190:193], v[50:53]
	v_mfma_f32_16x16x32_f16 v[50:53], v[66:69], v[186:189], v[50:53]
	v_mfma_f32_16x16x32_f16 v[34:37], v[66:69], v[178:181], v[34:37]
	v_mfma_f32_16x16x32_f16 v[34:37], v[78:81], v[182:185], v[34:37]
	v_mfma_f32_16x16x32_f16 v[18:21], v[78:81], v[174:177], v[18:21]
	v_mfma_f32_16x16x32_f16 v[18:21], v[66:69], v[138:141], v[18:21]
	s_barrier
	s_setprio 0
	s_add_i32 s54, s54, 2
	s_add_u32 s52, s52, 0x100
	s_addc_u32 s53, s53, 0
	s_cmp_gt_u32 s54, 41
	s_cbranch_scc1 .LBB0_999
.LBB0_989:
	ds_read_b128 v[158:161], v213
	ds_read_b128 v[162:165], v213 offset:1024
	ds_read_b128 v[166:169], v213 offset:2048
	ds_read_b128 v[170:173], v213 offset:3072
	ds_read_b128 v[66:69], v214
	ds_read_b128 v[78:81], v214 offset:1024
	ds_read_b128 v[90:93], v214 offset:2048
	ds_read_b128 v[102:105], v214 offset:3072
	s_mov_b64 s[6:7], s[50:51]
	s_add_u32 s50, s6, 0x100
	s_addc_u32 s51, s7, 0
	s_cmp_eq_u32 s54, 40
	s_cselect_b64 s[26:27], -1, 0
	s_and_b64 s[8:9], s[26:27], exec
	s_cselect_b32 s25, s47, s51
	s_cselect_b32 s24, s46, s50
	s_cselect_b32 s9, s49, s53
	s_cselect_b32 s8, s48, s52
	ds_read_b128 v[174:177], v215
	ds_read_b128 v[178:181], v215 offset:1024
	ds_read_b128 v[182:185], v215 offset:2048
	ds_read_b128 v[186:189], v215 offset:3072
	ds_read_b128 v[190:193], v215 offset:4096
	ds_read_b128 v[194:197], v215 offset:5120
	ds_read_b128 v[198:201], v215 offset:6144
	ds_read_b128 v[202:205], v215 offset:7168
	s_add_u32 s6, s6, 0xb0080
	s_addc_u32 s7, s7, 0
	s_add_u32 m0, s28, 0xc000
	s_nop 0
	global_load_lds_dwordx4 v1, s[6:7]
	s_nop 0
	s_add_u32 m0, s28, 0xe000
	s_nop 0
	global_load_lds_dwordx4 v211, s[6:7]
	s_waitcnt vmcnt(8)
	s_waitcnt lgkmcnt(0)
	s_barrier
	v_mfma_f32_16x16x32_f16 v[114:117], v[158:161], v[174:177], v[154:157]
	s_setprio 1
	v_mfma_f32_16x16x32_f16 v[114:117], v[162:165], v[178:181], v[114:117]
	v_mfma_f32_16x16x32_f16 v[134:137], v[162:165], v[186:189], v[134:137]
	v_mfma_f32_16x16x32_f16 v[134:137], v[158:161], v[182:185], v[134:137]
	v_mfma_f32_16x16x32_f16 v[110:113], v[158:161], v[190:193], v[110:113]
	v_mfma_f32_16x16x32_f16 v[110:113], v[162:165], v[194:197], v[110:113]
	v_mfma_f32_16x16x32_f16 v[86:89], v[162:165], v[202:205], v[86:89]
	v_mfma_f32_16x16x32_f16 v[86:89], v[158:161], v[198:201], v[86:89]
	v_mfma_f32_16x16x32_f16 v[82:85], v[166:169], v[198:201], v[82:85]
	v_mfma_f32_16x16x32_f16 v[82:85], v[170:173], v[202:205], v[82:85]
	v_mfma_f32_16x16x32_f16 v[126:129], v[170:173], v[178:181], v[150:153]
	v_mfma_f32_16x16x32_f16 v[126:129], v[166:169], v[174:177], v[126:129]
	v_mfma_f32_16x16x32_f16 v[130:133], v[166:169], v[182:185], v[130:133]
	v_mfma_f32_16x16x32_f16 v[130:133], v[170:173], v[186:189], v[130:133]
	v_mfma_f32_16x16x32_f16 v[106:109], v[170:173], v[194:197], v[106:109]
	v_mfma_f32_16x16x32_f16 v[106:109], v[166:169], v[190:193], v[106:109]
	v_mfma_f32_16x16x32_f16 v[98:101], v[66:69], v[190:193], v[98:101]
	v_mfma_f32_16x16x32_f16 v[98:101], v[78:81], v[194:197], v[98:101]
	v_mfma_f32_16x16x32_f16 v[138:141], v[78:81], v[178:181], v[146:149]
	v_mfma_f32_16x16x32_f16 v[138:141], v[66:69], v[174:177], v[138:141]
	v_mfma_f32_16x16x32_f16 v[122:125], v[66:69], v[182:185], v[122:125]
	v_mfma_f32_16x16x32_f16 v[122:125], v[78:81], v[186:189], v[122:125]
	v_mfma_f32_16x16x32_f16 v[74:77], v[78:81], v[202:205], v[74:77]
	v_mfma_f32_16x16x32_f16 v[74:77], v[66:69], v[198:201], v[74:77]
	v_mfma_f32_16x16x32_f16 v[70:73], v[90:93], v[198:201], v[70:73]
	v_mfma_f32_16x16x32_f16 v[70:73], v[102:105], v[202:205], v[70:73]
	v_mfma_f32_16x16x32_f16 v[142:145], v[102:105], v[178:181], v[142:145]
	v_mfma_f32_16x16x32_f16 v[142:145], v[90:93], v[174:177], v[142:145]
	v_mfma_f32_16x16x32_f16 v[118:121], v[90:93], v[182:185], v[118:121]
	v_mfma_f32_16x16x32_f16 v[118:121], v[102:105], v[186:189], v[118:121]
	v_mfma_f32_16x16x32_f16 v[94:97], v[102:105], v[194:197], v[94:97]
	v_mfma_f32_16x16x32_f16 v[94:97], v[90:93], v[190:193], v[94:97]
	s_barrier
	s_setprio 0
	ds_read_b128 v[186:189], v215 offset:16384
	ds_read_b128 v[190:193], v215 offset:17408
	ds_read_b128 v[178:181], v215 offset:18432
	ds_read_b128 v[182:185], v215 offset:19456
	ds_read_b128 v[154:157], v215 offset:20480
	ds_read_b128 v[174:177], v215 offset:21504
	ds_read_b128 v[146:149], v215 offset:22528
	ds_read_b128 v[150:153], v215 offset:23552
	s_and_b64 s[6:7], s[4:5], s[26:27]
	s_mov_b64 s[26:27], -1
	s_and_b64 vcc, exec, s[6:7]
	s_cbranch_vccnz .LBB0_991
	s_add_u32 m0, s28, 0x10000
	s_nop 0
	global_load_lds_dwordx4 v210, s[8:9]
	s_nop 0
	s_add_u32 m0, s28, 0x12000
	s_nop 0
	global_load_lds_dwordx4 v212, s[8:9]
	s_add_u32 s26, s8, 0xb0000
	s_addc_u32 s27, s9, 0
	s_add_u32 m0, s28, 0x14000
	s_nop 0
	global_load_lds_dwordx4 v210, s[26:27]
	s_nop 0
	s_add_u32 m0, s28, 0x16000
	s_nop 0
	global_load_lds_dwordx4 v212, s[26:27]
	s_mov_b64 s[26:27], 0
	s_add_u32 m0, s28, 0
	s_nop 0
	global_load_lds_dwordx4 v1, s[24:25]
	s_nop 0
	s_add_u32 m0, s28, 0x2000
	s_nop 0
	global_load_lds_dwordx4 v211, s[24:25]
	s_waitcnt vmcnt(8)

; #define PG8_STAGE(bufoff, gbase, voff) do { if constexpr (ABL & 1) break; glds16s<(bufoff)>((voff)[0], (const void*)(gbase), ldsbw); glds16s<(bufoff) + 8192>((voff)[1], (const void*)(gbase), ldsbw); } while (0)
; #define PG8_LDA(dst, b, h) do { if constexpr (ABL & 4) break; _Pragma("unroll") for (int m = 0; m < 4; ++m) _Pragma("unroll") for (int k = 0; k < 2; ++k) dst[m][k] = *(const LAS f16x8*)(lds + PG8_SA(b, h) + aoff + m * 2048 + k * 1024); } while (0)
; #define PG8_LDB(dst, b, h) do { if constexpr (ABL & 4) break; _Pragma("unroll") for (int n = 0; n < 2; ++n) _Pragma("unroll") for (int k = 0; k < 2; ++k) dst[n][k] = *(const LAS f16x8*)(lds + PG8_SB(b, h) + boff + n * 2048 + k * 1024); } while (0)
; #define PG8_MMA(ai, bj, At, Bt) do { if constexpr (ABL & 2) break; __builtin_amdgcn_s_setprio(1); _Pragma("unroll") for (int m = 0; m < 4; ++m) _Pragma("unroll") for (int n = 0; n < 2; ++n) _Pragma("unroll") for (int k = 0; k < 2; ++k) \
;         acc[ai][bj][m][n] = __builtin_amdgcn_mfma_f32_16x16x32_f16(Bt[n][k], At[m][k], acc[ai][bj][m][n], 0, 0, 0); __builtin_amdgcn_s_setprio(0); } while (0)
; #define PG8_MMAF(ai, bj, At, Bt) do { if (t == 0) PG8_MMA0(ai, bj, At, Bt); else PG8_MMA(ai, bj, At, Bt); } while (0)
; #define PG8_WAIT_V(n) asm volatile("s_waitcnt vmcnt(" #n ")" ::: "memory")
; #define PG8_WAIT_L(n) asm volatile("s_waitcnt lgkmcnt(" #n ")" ::: "memory")
; #define PG8_BAR __builtin_amdgcn_s_barrier()
; #define PG8_SCHED __builtin_amdgcn_sched_barrier(0)
;     ...
;             if (!fin) PG8_WAIT_V(8); else PG8_WAIT_V(2); PG8_WAIT_L(0); PG8_BAR; PG8_MMAF(1, 0, At, B0); PG8_MMAF(1, 1, At, B1); PG8_BAR; PG8_SCHED;
;             PG8_LDB(B0, 1, 0); PG8_LDB(B1, 1, 1); PG8_SCHED; PG8_LDA(At, 1, 0); if (!fin) PG8_STAGE(PG8_SA(0, 1), a2 + hstep, voffA);
;             if (!fin) PG8_WAIT_V(8); else PG8_WAIT_V(0); PG8_WAIT_L(0); PG8_BAR; PG8_MMA(0, 0, At, B0); PG8_MMA(0, 1, At, B1); PG8_BAR; PG8_SCHED;
.LBB0_993:
	s_waitcnt lgkmcnt(0)
	s_xor_b64 s[26:27], s[6:7], -1
	s_barrier
	v_mfma_f32_16x16x32_f16 v[62:65], v[158:161], v[186:189], v[62:65]
	s_setprio 1
	v_mfma_f32_16x16x32_f16 v[62:65], v[162:165], v[190:193], v[62:65]
	v_mfma_f32_16x16x32_f16 v[46:49], v[162:165], v[182:185], v[46:49]
	v_mfma_f32_16x16x32_f16 v[46:49], v[158:161], v[178:181], v[46:49]
	v_mfma_f32_16x16x32_f16 v[30:33], v[158:161], v[154:157], v[30:33]
	v_mfma_f32_16x16x32_f16 v[30:33], v[162:165], v[174:177], v[30:33]
	v_mfma_f32_16x16x32_f16 v[14:17], v[162:165], v[150:153], v[14:17]
	v_mfma_f32_16x16x32_f16 v[14:17], v[158:161], v[146:149], v[14:17]
	v_mfma_f32_16x16x32_f16 v[10:13], v[166:169], v[146:149], v[10:13]
	v_mfma_f32_16x16x32_f16 v[10:13], v[170:173], v[150:153], v[10:13]
	v_mfma_f32_16x16x32_f16 v[58:61], v[170:173], v[190:193], v[58:61]
	v_mfma_f32_16x16x32_f16 v[58:61], v[166:169], v[186:189], v[58:61]
	v_mfma_f32_16x16x32_f16 v[42:45], v[166:169], v[178:181], v[42:45]
	v_mfma_f32_16x16x32_f16 v[42:45], v[170:173], v[182:185], v[42:45]
	v_mfma_f32_16x16x32_f16 v[26:29], v[170:173], v[174:177], v[26:29]
	v_mfma_f32_16x16x32_f16 v[26:29], v[166:169], v[154:157], v[26:29]
	v_mfma_f32_16x16x32_f16 v[22:25], v[66:69], v[154:157], v[22:25]
	v_mfma_f32_16x16x32_f16 v[22:25], v[78:81], v[174:177], v[22:25]
	v_mfma_f32_16x16x32_f16 v[54:57], v[78:81], v[190:193], v[54:57]
	v_mfma_f32_16x16x32_f16 v[54:57], v[66:69], v[186:189], v[54:57]
	v_mfma_f32_16x16x32_f16 v[38:41], v[66:69], v[178:181], v[38:41]
	v_mfma_f32_16x16x32_f16 v[38:41], v[78:81], v[182:185], v[38:41]
	v_mfma_f32_16x16x32_f16 v[6:9], v[78:81], v[150:153], v[6:9]
	v_mfma_f32_16x16x32_f16 v[6:9], v[66:69], v[146:149], v[6:9]
	v_mfma_f32_16x16x32_f16 v[2:5], v[90:93], v[146:149], v[2:5]
	v_mfma_f32_16x16x32_f16 v[2:5], v[102:105], v[150:153], v[2:5]
	v_mfma_f32_16x16x32_f16 v[50:53], v[102:105], v[190:193], v[50:53]
	v_mfma_f32_16x16x32_f16 v[50:53], v[90:93], v[186:189], v[50:53]
	v_mfma_f32_16x16x32_f16 v[34:37], v[90:93], v[178:181], v[34:37]
	v_mfma_f32_16x16x32_f16 v[34:37], v[102:105], v[182:185], v[34:37]
	v_mfma_f32_16x16x32_f16 v[18:21], v[102:105], v[174:177], v[18:21]
	v_mfma_f32_16x16x32_f16 v[18:21], v[90:93], v[154:157], v[18:21]
	s_barrier
	s_setprio 0
	ds_read_b128 v[166:169], v216
	ds_read_b128 v[170:173], v216 offset:1024
	ds_read_b128 v[158:161], v216 offset:2048
	ds_read_b128 v[162:165], v216 offset:3072
	ds_read_b128 v[90:93], v217
	ds_read_b128 v[102:105], v217 offset:1024
	ds_read_b128 v[66:69], v217 offset:2048
	ds_read_b128 v[78:81], v217 offset:3072
	ds_read_b128 v[198:201], v215 offset:32768
	ds_read_b128 v[202:205], v215 offset:33792
	ds_read_b128 v[190:193], v215 offset:34816
	ds_read_b128 v[194:197], v215 offset:35840
	ds_read_b128 v[182:185], v215 offset:36864
	ds_read_b128 v[186:189], v215 offset:37888
	ds_read_b128 v[174:177], v215 offset:38912
	ds_read_b128 v[178:181], v215 offset:39936
	v_cndmask_b32_e64 v146, 0, 1, s[26:27]
	v_cmp_ne_u32_e64 s[6:7], 1, v146
	s_andn2_b64 vcc, exec, s[26:27]
	s_mov_b64 s[26:27], -1
	s_cbranch_vccnz .LBB0_995
	s_add_u32 s26, s24, 0xb0000
	s_addc_u32 s27, s25, 0
	s_add_u32 m0, s28, 0x4000
	s_nop 0
	global_load_lds_dwordx4 v1, s[26:27]
	s_nop 0
	s_add_u32 m0, s28, 0x6000
	s_nop 0
	global_load_lds_dwordx4 v211, s[26:27]
	s_waitcnt vmcnt(8)
	s_mov_b64 s[26:27], 0

;     __device__ __forceinline__ bool next(int i, Unit& u) const { if (i >= count) return false; const int L = first + i; u.pm = L / nN; u.pn = L % nN; return true; }
; #define PG8_STAGE(bufoff, gbase, voff) do { if constexpr (ABL & 1) break; glds16s<(bufoff)>((voff)[0], (const void*)(gbase), ldsbw); glds16s<(bufoff) + 8192>((voff)[1], (const void*)(gbase), ldsbw); } while (0)
; #define PG8_LDA(dst, b, h) do { if constexpr (ABL & 4) break; _Pragma("unroll") for (int m = 0; m < 4; ++m) _Pragma("unroll") for (int k = 0; k < 2; ++k) dst[m][k] = *(const LAS f16x8*)(lds + PG8_SA(b, h) + aoff + m * 2048 + k * 1024); } while (0)
; #define PG8_LDB(dst, b, h) do { if constexpr (ABL & 4) break; _Pragma("unroll") for (int n = 0; n < 2; ++n) _Pragma("unroll") for (int k = 0; k < 2; ++k) dst[n][k] = *(const LAS f16x8*)(lds + PG8_SB(b, h) + boff + n * 2048 + k * 1024); } while (0)
; #define PG8_MMAF(ai, bj, At, Bt) do { if (t == 0) PG8_MMA0(ai, bj, At, Bt); else PG8_MMA(ai, bj, At, Bt); } while (0)
; #define PG8_WAIT_V(n) asm volatile("s_waitcnt vmcnt(" #n ")" ::: "memory")
; #define PG8_BAR __builtin_amdgcn_s_barrier()
;     ...
;         const bool has_next = S.next(ui + 1, nxt);
;         const char* nA = has_next ? (const char*)g.A + (size_t)nxt.pm * tstep : cA; const char* nB = has_next ? (const char*)g.Bt + (size_t)nxt.pn * tstep : cB;
;         for (int t = 0; t < nt; t += 2) {
;             const bool last = (t == nt - 2);
;             const char* a1 = cA + (size_t)(t + 1) * kstep;
;             const char* a2 = last ? nA : cA + (size_t)(t + 2) * kstep; const char* b2 = last ? nB : cB + (size_t)(t + 2) * kstep;
;             const char* a3 = a2 + kstep; const char* b3 = b2 + kstep;
;             if (last && has_next) S.a_ready(nxt);
;             if constexpr (SP2) {
;             PG8_LDB(B0, 0, 0); PG8_LDB(B1, 0, 1); PG8_SCHED; PG8_LDA(At, 0, 0); PG8_STAGE(PG8_SA(1, 1), a1 + hstep, voffA);
;             PG8_WAIT_V(8); PG8_WAIT_L(0); PG8_BAR; PG8_MMAF(0, 0, At, B0); PG8_MMAF(0, 1, At, B1); PG8_BAR; PG8_SCHED;
;             const bool fin = last && !has_next;
;             PG8_LDA(At, 0, 1); if (!fin) { PG8_STAGE(PG8_SB(0, 0), b2, voffB); PG8_STAGE(PG8_SB(0, 1), b2 + hstep, voffB); PG8_STAGE(PG8_SA(0, 0), a2, voffA); }
;             if (!fin) PG8_WAIT_V(8); else PG8_WAIT_V(2); PG8_WAIT_L(0); PG8_BAR; PG8_MMAF(1, 0, At, B0); PG8_MMAF(1, 1, At, B1); PG8_BAR; PG8_SCHED;
.LBB0_1111:
	s_ashr_i32 s43, s42, 31
	s_lshl_b64 s[8:9], s[42:43], 19
	s_add_u32 s44, s74, s8
	s_addc_u32 s45, s75, s9
	s_and_b64 s[8:9], exec, s[4:5]
	s_waitcnt lgkmcnt(0)
	ds_read_b128 v[2:5], v201
	ds_read_b128 v[6:9], v201 offset:1024
	ds_read_b128 v[10:13], v201 offset:2048
	ds_read_b128 v[14:17], v201 offset:3072
	ds_read_b128 v[18:21], v202
	ds_read_b128 v[22:25], v202 offset:1024
	ds_read_b128 v[26:29], v202 offset:2048
	ds_read_b128 v[30:33], v202 offset:3072
	s_cselect_b32 s43, s55, s45
	s_cselect_b32 s56, s54, s44
	s_ashr_i32 s41, s40, 31
	s_lshl_b64 s[8:9], s[40:41], 19
	s_add_u32 s46, s94, s8
	s_addc_u32 s47, s95, s9
	s_and_b64 s[8:9], exec, s[4:5]
	s_cselect_b32 s41, s7, s47
	s_cselect_b32 s57, s6, s46
	s_add_u32 s52, s54, 0x100
	s_addc_u32 s53, s55, 0
	s_add_u32 s26, s6, 0x100
	s_addc_u32 s27, s7, 0
	s_add_u32 s8, s54, 0x180
	s_addc_u32 s9, s55, 0
	ds_read_b128 v[34:37], v203
	ds_read_b128 v[38:41], v203 offset:1024
	ds_read_b128 v[42:45], v203 offset:2048
	ds_read_b128 v[46:49], v203 offset:3072
	ds_read_b128 v[50:53], v203 offset:4096
	ds_read_b128 v[54:57], v203 offset:5120
	ds_read_b128 v[58:61], v203 offset:6144
	ds_read_b128 v[62:65], v203 offset:7168
	s_add_u32 s24, s6, 0x180
	s_addc_u32 s25, s7, 0
	s_add_u32 s58, s54, 0x40080
	s_addc_u32 s59, s55, 0
	s_add_u32 m0, s28, 0xc000
	s_nop 0
	global_load_lds_dwordx4 v1, s[58:59]
	s_nop 0
	s_add_u32 m0, s28, 0xe000
	s_nop 0
	global_load_lds_dwordx4 v199, s[58:59]
	s_waitcnt vmcnt(8)
	s_waitcnt lgkmcnt(0)
	s_barrier
	v_mfma_f32_16x16x32_f16 v[90:93], v[2:5], v[58:61], 0
	s_setprio 1
	v_mfma_f32_16x16x32_f16 v[98:101], v[6:9], v[62:65], v[90:93]
	v_mfma_f32_16x16x32_f16 v[66:69], v[2:5], v[34:37], 0
	v_mfma_f32_16x16x32_f16 v[66:69], v[6:9], v[38:41], v[66:69]
	v_mfma_f32_16x16x32_f16 v[70:73], v[10:13], v[34:37], 0
	v_mfma_f32_16x16x32_f16 v[70:73], v[14:17], v[38:41], v[70:73]
	v_mfma_f32_16x16x32_f16 v[74:77], v[2:5], v[42:45], 0
	v_mfma_f32_16x16x32_f16 v[74:77], v[6:9], v[46:49], v[74:77]
	v_mfma_f32_16x16x32_f16 v[78:81], v[10:13], v[42:45], 0
	v_mfma_f32_16x16x32_f16 v[78:81], v[14:17], v[46:49], v[78:81]
	v_mfma_f32_16x16x32_f16 v[82:85], v[2:5], v[50:53], 0
	v_mfma_f32_16x16x32_f16 v[82:85], v[6:9], v[54:57], v[82:85]
	v_mfma_f32_16x16x32_f16 v[86:89], v[10:13], v[50:53], 0
	v_mfma_f32_16x16x32_f16 v[86:89], v[14:17], v[54:57], v[86:89]
	v_mfma_f32_16x16x32_f16 v[90:93], v[10:13], v[58:61], 0
	v_mfma_f32_16x16x32_f16 v[102:105], v[14:17], v[62:65], v[90:93]
	v_mfma_f32_16x16x32_f16 v[90:93], v[18:21], v[34:37], 0
	v_mfma_f32_16x16x32_f16 v[114:117], v[22:25], v[38:41], v[90:93]
	v_mfma_f32_16x16x32_f16 v[34:37], v[26:29], v[34:37], 0
	v_mfma_f32_16x16x32_f16 v[34:37], v[30:33], v[38:41], v[34:37]
	v_mfma_f32_16x16x32_f16 v[38:41], v[18:21], v[42:45], 0
	v_mfma_f32_16x16x32_f16 v[38:41], v[22:25], v[46:49], v[38:41]
	v_mfma_f32_16x16x32_f16 v[42:45], v[26:29], v[42:45], 0
	v_mfma_f32_16x16x32_f16 v[42:45], v[30:33], v[46:49], v[42:45]
	v_mfma_f32_16x16x32_f16 v[46:49], v[18:21], v[50:53], 0
	v_mfma_f32_16x16x32_f16 v[46:49], v[22:25], v[54:57], v[46:49]
	v_mfma_f32_16x16x32_f16 v[50:53], v[26:29], v[50:53], 0
	v_mfma_f32_16x16x32_f16 v[50:53], v[30:33], v[54:57], v[50:53]
	v_mfma_f32_16x16x32_f16 v[54:57], v[18:21], v[58:61], 0
	v_mfma_f32_16x16x32_f16 v[54:57], v[22:25], v[62:65], v[54:57]
	v_mfma_f32_16x16x32_f16 v[58:61], v[26:29], v[58:61], 0
	v_mfma_f32_16x16x32_f16 v[58:61], v[30:33], v[62:65], v[58:61]
	s_barrier
	s_setprio 0
	ds_read_b128 v[62:65], v203 offset:16384
	ds_read_b128 v[90:93], v203 offset:17408
	ds_read_b128 v[94:97], v203 offset:18432
	ds_read_b128 v[106:109], v203 offset:19456
	ds_read_b128 v[110:113], v203 offset:20480
	ds_read_b128 v[118:121], v203 offset:21504
	ds_read_b128 v[122:125], v203 offset:22528
	ds_read_b128 v[126:129], v203 offset:23552
	s_add_u32 m0, s28, 0x10000
	s_nop 0
	global_load_lds_dwordx4 v198, s[26:27]
	s_nop 0
	s_add_u32 m0, s28, 0x12000
	s_nop 0
	global_load_lds_dwordx4 v200, s[26:27]
	s_add_u32 s26, s6, 0x40100
	s_addc_u32 s27, s7, 0
	s_add_u32 m0, s28, 0x14000
	s_nop 0
	global_load_lds_dwordx4 v198, s[26:27]
	s_nop 0
	s_add_u32 m0, s28, 0x16000
	s_nop 0
	global_load_lds_dwordx4 v200, s[26:27]
	s_nop 0
	s_add_u32 m0, s28, 0
	s_nop 0
	global_load_lds_dwordx4 v1, s[52:53]
	s_nop 0
	s_add_u32 m0, s28, 0x2000
	s_nop 0
	global_load_lds_dwordx4 v199, s[52:53]
	s_waitcnt vmcnt(8)
	s_waitcnt lgkmcnt(0)
	s_barrier
	v_mfma_f32_16x16x32_f16 v[130:133], v[2:5], v[62:65], 0
	s_setprio 1
	v_mfma_f32_16x16x32_f16 v[130:133], v[6:9], v[90:93], v[130:133]
	v_mfma_f32_16x16x32_f16 v[138:141], v[2:5], v[94:97], 0
	v_mfma_f32_16x16x32_f16 v[138:141], v[6:9], v[106:109], v[138:141]
	v_mfma_f32_16x16x32_f16 v[146:149], v[2:5], v[110:113], 0
	v_mfma_f32_16x16x32_f16 v[146:149], v[6:9], v[118:121], v[146:149]
	v_mfma_f32_16x16x32_f16 v[2:5], v[2:5], v[122:125], 0
	v_mfma_f32_16x16x32_f16 v[2:5], v[6:9], v[126:129], v[2:5]
	v_mfma_f32_16x16x32_f16 v[6:9], v[10:13], v[122:125], 0
	v_mfma_f32_16x16x32_f16 v[6:9], v[14:17], v[126:129], v[6:9]
	v_mfma_f32_16x16x32_f16 v[134:137], v[10:13], v[62:65], 0
	v_mfma_f32_16x16x32_f16 v[134:137], v[14:17], v[90:93], v[134:137]
	v_mfma_f32_16x16x32_f16 v[142:145], v[10:13], v[94:97], 0
	v_mfma_f32_16x16x32_f16 v[142:145], v[14:17], v[106:109], v[142:145]
	v_mfma_f32_16x16x32_f16 v[150:153], v[10:13], v[110:113], 0
	v_mfma_f32_16x16x32_f16 v[150:153], v[14:17], v[118:121], v[150:153]
	v_mfma_f32_16x16x32_f16 v[10:13], v[18:21], v[62:65], 0
	v_mfma_f32_16x16x32_f16 v[154:157], v[22:25], v[90:93], v[10:13]
	v_mfma_f32_16x16x32_f16 v[10:13], v[26:29], v[62:65], 0
	v_mfma_f32_16x16x32_f16 v[158:161], v[30:33], v[90:93], v[10:13]
	v_mfma_f32_16x16x32_f16 v[10:13], v[18:21], v[94:97], 0
	v_mfma_f32_16x16x32_f16 v[162:165], v[22:25], v[106:109], v[10:13]
	v_mfma_f32_16x16x32_f16 v[10:13], v[26:29], v[94:97], 0
	v_mfma_f32_16x16x32_f16 v[166:169], v[30:33], v[106:109], v[10:13]
	v_mfma_f32_16x16x32_f16 v[10:13], v[18:21], v[110:113], 0
	v_mfma_f32_16x16x32_f16 v[170:173], v[22:25], v[118:121], v[10:13]
	v_mfma_f32_16x16x32_f16 v[10:13], v[26:29], v[110:113], 0
	v_mfma_f32_16x16x32_f16 v[174:177], v[30:33], v[118:121], v[10:13]
	v_mfma_f32_16x16x32_f16 v[10:13], v[18:21], v[122:125], 0
	v_mfma_f32_16x16x32_f16 v[178:181], v[22:25], v[126:129], v[10:13]
	v_mfma_f32_16x16x32_f16 v[10:13], v[26:29], v[122:125], 0
	v_mfma_f32_16x16x32_f16 v[182:185], v[30:33], v[126:129], v[10:13]
	s_barrier
; #define PG8_STAGE(bufoff, gbase, voff) do { if constexpr (ABL & 1) break; glds16s<(bufoff)>((voff)[0], (const void*)(gbase), ldsbw); glds16s<(bufoff) + 8192>((voff)[1], (const void*)(gbase), ldsbw); } while (0)
; #define PG8_LDA(dst, b, h) do { if constexpr (ABL & 4) break; _Pragma("unroll") for (int m = 0; m < 4; ++m) _Pragma("unroll") for (int k = 0; k < 2; ++k) dst[m][k] = *(const LAS f16x8*)(lds + PG8_SA(b, h) + aoff + m * 2048 + k * 1024); } while (0)
; #define PG8_LDB(dst, b, h) do { if constexpr (ABL & 4) break; _Pragma("unroll") for (int n = 0; n < 2; ++n) _Pragma("unroll") for (int k = 0; k < 2; ++k) dst[n][k] = *(const LAS f16x8*)(lds + PG8_SB(b, h) + boff + n * 2048 + k * 1024); } while (0)
; #define PG8_MMA(ai, bj, At, Bt) do { if constexpr (ABL & 2) break; __builtin_amdgcn_s_setprio(1); _Pragma("unroll") for (int m = 0; m < 4; ++m) _Pragma("unroll") for (int n = 0; n < 2; ++n) _Pragma("unroll") for (int k = 0; k < 2; ++k) \
;         acc[ai][bj][m][n] = __builtin_amdgcn_mfma_f32_16x16x32_f16(Bt[n][k], At[m][k], acc[ai][bj][m][n], 0, 0, 0); __builtin_amdgcn_s_setprio(0); } while (0)
; #define PG8_MMAF(ai, bj, At, Bt) do { if (t == 0) PG8_MMA0(ai, bj, At, Bt); else PG8_MMA(ai, bj, At, Bt); } while (0)
; #define PG8_WAIT_V(n) asm volatile("s_waitcnt vmcnt(" #n ")" ::: "memory")
; #define PG8_WAIT_L(n) asm volatile("s_waitcnt lgkmcnt(" #n ")" ::: "memory")
; #define PG8_BAR __builtin_amdgcn_s_barrier()
; #define PG8_SCHED __builtin_amdgcn_sched_barrier(0)
;     ...
;             if (!fin) PG8_WAIT_V(8); else PG8_WAIT_V(2); PG8_WAIT_L(0); PG8_BAR; PG8_MMAF(1, 0, At, B0); PG8_MMAF(1, 1, At, B1); PG8_BAR; PG8_SCHED;
;             PG8_LDB(B0, 1, 0); PG8_LDB(B1, 1, 1); PG8_SCHED; PG8_LDA(At, 1, 0); if (!fin) PG8_STAGE(PG8_SA(0, 1), a2 + hstep, voffA);
;             if (!fin) PG8_WAIT_V(8); else PG8_WAIT_V(0); PG8_WAIT_L(0); PG8_BAR; PG8_MMA(0, 0, At, B0); PG8_MMA(0, 1, At, B1); PG8_BAR; PG8_SCHED;
;             PG8_LDA(At, 1, 1); if (!fin) { PG8_STAGE(PG8_SB(1, 0), b3, voffB); PG8_STAGE(PG8_SB(1, 1), b3 + hstep, voffB); PG8_STAGE(PG8_SA(1, 0), a3, voffA); }
;             if (!fin) PG8_WAIT_V(8); PG8_WAIT_L(0); PG8_BAR; PG8_MMA(1, 0, At, B0); PG8_MMA(1, 1, At, B1); PG8_BAR; PG8_SCHED;
	s_setprio 0
	s_nop 4
	ds_read_b128 v[10:13], v204
	ds_read_b128 v[14:17], v204 offset:1024
	ds_read_b128 v[18:21], v204 offset:2048
	ds_read_b128 v[22:25], v204 offset:3072
	ds_read_b128 v[186:189], v205
	ds_read_b128 v[190:193], v205 offset:1024
	ds_read_b128 v[210:213], v205 offset:2048
	ds_read_b128 v[214:217], v205 offset:3072
	ds_read_b128 v[26:29], v203 offset:32768
	ds_read_b128 v[30:33], v203 offset:33792
	ds_read_b128 v[62:65], v203 offset:34816
	ds_read_b128 v[218:221], v203 offset:35840
	ds_read_b128 v[222:225], v203 offset:36864
	ds_read_b128 v[226:229], v203 offset:37888
	ds_read_b128 v[230:233], v203 offset:38912
	ds_read_b128 v[234:237], v203 offset:39936
	s_add_u32 s26, s54, 0x40100
	s_addc_u32 s27, s55, 0
	s_add_u32 m0, s28, 0x4000
	s_nop 0
	global_load_lds_dwordx4 v1, s[26:27]
	s_nop 0
	s_add_u32 m0, s28, 0x6000
	s_nop 0
	global_load_lds_dwordx4 v199, s[26:27]
	s_waitcnt vmcnt(8)
	s_waitcnt lgkmcnt(0)
	s_barrier
	v_mfma_f32_16x16x32_f16 v[66:69], v[10:13], v[26:29], v[66:69]
	s_setprio 1
	v_mfma_f32_16x16x32_f16 v[126:129], v[14:17], v[30:33], v[66:69]
	v_mfma_f32_16x16x32_f16 v[66:69], v[18:21], v[26:29], v[70:73]
	v_mfma_f32_16x16x32_f16 v[122:125], v[22:25], v[30:33], v[66:69]
	v_mfma_f32_16x16x32_f16 v[66:69], v[10:13], v[62:65], v[74:77]
	v_mfma_f32_16x16x32_f16 v[110:113], v[14:17], v[218:221], v[66:69]
	v_mfma_f32_16x16x32_f16 v[66:69], v[18:21], v[62:65], v[78:81]
	v_mfma_f32_16x16x32_f16 v[106:109], v[22:25], v[218:221], v[66:69]
	v_mfma_f32_16x16x32_f16 v[66:69], v[10:13], v[222:225], v[82:85]
	v_mfma_f32_16x16x32_f16 v[94:97], v[14:17], v[226:229], v[66:69]
	v_mfma_f32_16x16x32_f16 v[66:69], v[18:21], v[222:225], v[86:89]
	v_mfma_f32_16x16x32_f16 v[90:93], v[22:25], v[226:229], v[66:69]
	v_mfma_f32_16x16x32_f16 v[66:69], v[10:13], v[230:233], v[98:101]
	v_mfma_f32_16x16x32_f16 v[78:81], v[14:17], v[234:237], v[66:69]
	v_mfma_f32_16x16x32_f16 v[66:69], v[18:21], v[230:233], v[102:105]
	v_mfma_f32_16x16x32_f16 v[74:77], v[22:25], v[234:237], v[66:69]
	v_mfma_f32_16x16x32_f16 v[66:69], v[186:189], v[26:29], v[114:117]
	v_mfma_f32_16x16x32_f16 v[118:121], v[190:193], v[30:33], v[66:69]
	v_mfma_f32_16x16x32_f16 v[26:29], v[210:213], v[26:29], v[34:37]
	v_mfma_f32_16x16x32_f16 v[114:117], v[214:217], v[30:33], v[26:29]
	v_mfma_f32_16x16x32_f16 v[26:29], v[186:189], v[62:65], v[38:41]
	v_mfma_f32_16x16x32_f16 v[102:105], v[190:193], v[218:221], v[26:29]
	v_mfma_f32_16x16x32_f16 v[26:29], v[210:213], v[62:65], v[42:45]
	v_mfma_f32_16x16x32_f16 v[98:101], v[214:217], v[218:221], v[26:29]
	v_mfma_f32_16x16x32_f16 v[26:29], v[186:189], v[222:225], v[46:49]
	v_mfma_f32_16x16x32_f16 v[86:89], v[190:193], v[226:229], v[26:29]
	v_mfma_f32_16x16x32_f16 v[26:29], v[210:213], v[222:225], v[50:53]
	v_mfma_f32_16x16x32_f16 v[82:85], v[214:217], v[226:229], v[26:29]
	v_mfma_f32_16x16x32_f16 v[26:29], v[186:189], v[230:233], v[54:57]
	v_mfma_f32_16x16x32_f16 v[70:73], v[190:193], v[234:237], v[26:29]
	v_mfma_f32_16x16x32_f16 v[26:29], v[210:213], v[230:233], v[58:61]
	v_mfma_f32_16x16x32_f16 v[66:69], v[214:217], v[234:237], v[26:29]
	s_barrier
	s_setprio 0
	ds_read_b128 v[34:37], v203 offset:49152
	ds_read_b128 v[38:41], v203 offset:50176
	ds_read_b128 v[218:221], v203 offset:51200
	ds_read_b128 v[222:225], v203 offset:52224
	ds_read_b128 v[226:229], v203 offset:53248
	ds_read_b128 v[230:233], v203 offset:54272
	ds_read_b128 v[234:237], v203 offset:55296
	ds_read_b128 v[238:241], v203 offset:56320
	s_add_u32 m0, s28, 0x18000
	s_nop 0
	global_load_lds_dwordx4 v198, s[24:25]
	s_nop 0
	s_add_u32 m0, s28, 0x1a000
	s_nop 0
	global_load_lds_dwordx4 v200, s[24:25]
	s_add_u32 s24, s6, 0x40180
	s_addc_u32 s25, s7, 0
	s_add_u32 m0, s28, 0x1c000
	s_nop 0
	global_load_lds_dwordx4 v198, s[24:25]
	s_nop 0
	s_add_u32 m0, s28, 0x1e000
	s_nop 0
	global_load_lds_dwordx4 v200, s[24:25]
	s_nop 0
	s_add_u32 m0, s28, 0x8000
	s_nop 0
	global_load_lds_dwordx4 v1, s[8:9]
	s_nop 0
	s_add_u32 m0, s28, 0xa000
	s_nop 0
	global_load_lds_dwordx4 v199, s[8:9]
	s_waitcnt vmcnt(8)
	s_waitcnt lgkmcnt(0)
	s_barrier
	v_mfma_f32_16x16x32_f16 v[26:29], v[10:13], v[34:37], v[130:133]
	s_setprio 1
	v_mfma_f32_16x16x32_f16 v[62:65], v[14:17], v[38:41], v[26:29]
	v_mfma_f32_16x16x32_f16 v[26:29], v[22:25], v[38:41], v[134:137]
	v_mfma_f32_16x16x32_f16 v[58:61], v[18:21], v[34:37], v[26:29]
	v_mfma_f32_16x16x32_f16 v[26:29], v[10:13], v[218:221], v[138:141]
	v_mfma_f32_16x16x32_f16 v[46:49], v[14:17], v[222:225], v[26:29]
	v_mfma_f32_16x16x32_f16 v[26:29], v[22:25], v[222:225], v[142:145]
	v_mfma_f32_16x16x32_f16 v[42:45], v[18:21], v[218:221], v[26:29]
	v_mfma_f32_16x16x32_f16 v[26:29], v[10:13], v[226:229], v[146:149]
	v_mfma_f32_16x16x32_f16 v[30:33], v[14:17], v[230:233], v[26:29]
	v_mfma_f32_16x16x32_f16 v[26:29], v[22:25], v[230:233], v[150:153]
	v_mfma_f32_16x16x32_f16 v[26:29], v[18:21], v[226:229], v[26:29]
	v_mfma_f32_16x16x32_f16 v[2:5], v[10:13], v[234:237], v[2:5]
	v_mfma_f32_16x16x32_f16 v[14:17], v[14:17], v[238:241], v[2:5]
	v_mfma_f32_16x16x32_f16 v[2:5], v[22:25], v[238:241], v[6:9]
	v_mfma_f32_16x16x32_f16 v[10:13], v[18:21], v[234:237], v[2:5]
	v_mfma_f32_16x16x32_f16 v[2:5], v[186:189], v[34:37], v[154:157]
	v_mfma_f32_16x16x32_f16 v[54:57], v[190:193], v[38:41], v[2:5]
	v_mfma_f32_16x16x32_f16 v[2:5], v[214:217], v[38:41], v[158:161]
	v_mfma_f32_16x16x32_f16 v[50:53], v[210:213], v[34:37], v[2:5]
	v_mfma_f32_16x16x32_f16 v[2:5], v[186:189], v[218:221], v[162:165]
	v_mfma_f32_16x16x32_f16 v[38:41], v[190:193], v[222:225], v[2:5]
	v_mfma_f32_16x16x32_f16 v[2:5], v[214:217], v[222:225], v[166:169]
	v_mfma_f32_16x16x32_f16 v[34:37], v[210:213], v[218:221], v[2:5]
	v_mfma_f32_16x16x32_f16 v[2:5], v[186:189], v[226:229], v[170:173]
	v_mfma_f32_16x16x32_f16 v[22:25], v[190:193], v[230:233], v[2:5]
	v_mfma_f32_16x16x32_f16 v[2:5], v[214:217], v[230:233], v[174:177]
	v_mfma_f32_16x16x32_f16 v[18:21], v[210:213], v[226:229], v[2:5]
	v_mfma_f32_16x16x32_f16 v[2:5], v[186:189], v[234:237], v[178:181]
	v_mfma_f32_16x16x32_f16 v[6:9], v[190:193], v[238:241], v[2:5]
	v_mfma_f32_16x16x32_f16 v[2:5], v[214:217], v[238:241], v[182:185]
	v_mfma_f32_16x16x32_f16 v[2:5], v[210:213], v[234:237], v[2:5]
	s_barrier
	s_setprio 0
	s_add_u32 s54, s6, 0x200
	s_addc_u32 s55, s7, 0
	s_mov_b32 s58, 0
	s_branch .LBB0_1113
; #define PG8_STAGE(bufoff, gbase, voff) do { if constexpr (ABL & 1) break; glds16s<(bufoff)>((voff)[0], (const void*)(gbase), ldsbw); glds16s<(bufoff) + 8192>((voff)[1], (const void*)(gbase), ldsbw); } while (0)
; #define PG8_LDA(dst, b, h) do { if constexpr (ABL & 4) break; _Pragma("unroll") for (int m = 0; m < 4; ++m) _Pragma("unroll") for (int k = 0; k < 2; ++k) dst[m][k] = *(const LAS f16x8*)(lds + PG8_SA(b, h) + aoff + m * 2048 + k * 1024); } while (0)
; #define PG8_LDB(dst, b, h) do { if constexpr (ABL & 4) break; _Pragma("unroll") for (int n = 0; n < 2; ++n) _Pragma("unroll") for (int k = 0; k < 2; ++k) dst[n][k] = *(const LAS f16x8*)(lds + PG8_SB(b, h) + boff + n * 2048 + k * 1024); } while (0)
; #define PG8_BAR __builtin_amdgcn_s_barrier()
;     ...
;         for (int t = 0; t < nt; t += 2) {
;             const bool last = (t == nt - 2);
;             const char* a1 = cA + (size_t)(t + 1) * kstep;
;             const char* a2 = last ? nA : cA + (size_t)(t + 2) * kstep; const char* b2 = last ? nB : cB + (size_t)(t + 2) * kstep;
;             const char* a3 = a2 + kstep; const char* b3 = b2 + kstep;
;             if (last && has_next) S.a_ready(nxt);
;             if constexpr (SP2) {
;             PG8_LDB(B0, 0, 0); PG8_LDB(B1, 0, 1); PG8_SCHED; PG8_LDA(At, 0, 0); PG8_STAGE(PG8_SA(1, 1), a1 + hstep, voffA);
;             PG8_WAIT_V(8); PG8_WAIT_L(0); PG8_BAR; PG8_MMAF(0, 0, At, B0); PG8_MMAF(0, 1, At, B1); PG8_BAR; PG8_SCHED;
;             const bool fin = last && !has_next;
;             PG8_LDA(At, 0, 1); if (!fin) { PG8_STAGE(PG8_SB(0, 0), b2, voffB); PG8_STAGE(PG8_SB(0, 1), b2 + hstep, voffB); PG8_STAGE(PG8_SA(0, 0), a2, voffA); }
;             if (!fin) PG8_WAIT_V(8); else PG8_WAIT_V(2); PG8_WAIT_L(0); PG8_BAR; PG8_MMAF(1, 0, At, B0); PG8_MMAF(1, 1, At, B1); PG8_BAR; PG8_SCHED;
;             PG8_LDB(B0, 1, 0); PG8_LDB(B1, 1, 1); PG8_SCHED; PG8_LDA(At, 1, 0); if (!fin) PG8_STAGE(PG8_SA(0, 1), a2 + hstep, voffA);
;             if (!fin) PG8_WAIT_V(8); else PG8_WAIT_V(0); PG8_WAIT_L(0); PG8_BAR; PG8_MMA(0, 0, At, B0); PG8_MMA(0, 1, At, B1); PG8_BAR; PG8_SCHED;
;             PG8_LDA(At, 1, 1); if (!fin) { PG8_STAGE(PG8_SB(1, 0), b3, voffB); PG8_STAGE(PG8_SB(1, 1), b3 + hstep, voffB); PG8_STAGE(PG8_SA(1, 0), a3, voffA); }
;             if (!fin) PG8_WAIT_V(8); PG8_WAIT_L(0); PG8_BAR; PG8_MMA(1, 0, At, B0); PG8_MMA(1, 1, At, B1); PG8_BAR; PG8_SCHED;
.LBB0_1112:
	s_waitcnt lgkmcnt(0)
	s_barrier
	v_mfma_f32_16x16x32_f16 v[62:65], v[146:149], v[186:189], v[62:65]
	s_setprio 1
	v_mfma_f32_16x16x32_f16 v[62:65], v[150:153], v[190:193], v[62:65]
	v_mfma_f32_16x16x32_f16 v[46:49], v[150:153], v[182:185], v[46:49]
	v_mfma_f32_16x16x32_f16 v[46:49], v[146:149], v[178:181], v[46:49]
	v_mfma_f32_16x16x32_f16 v[30:33], v[146:149], v[170:173], v[30:33]
	v_mfma_f32_16x16x32_f16 v[30:33], v[150:153], v[174:177], v[30:33]
	v_mfma_f32_16x16x32_f16 v[14:17], v[150:153], v[166:169], v[14:17]
	v_mfma_f32_16x16x32_f16 v[14:17], v[146:149], v[162:165], v[14:17]
	v_mfma_f32_16x16x32_f16 v[10:13], v[154:157], v[162:165], v[10:13]
	v_mfma_f32_16x16x32_f16 v[10:13], v[158:161], v[166:169], v[10:13]
	v_mfma_f32_16x16x32_f16 v[58:61], v[158:161], v[190:193], v[58:61]
	v_mfma_f32_16x16x32_f16 v[58:61], v[154:157], v[186:189], v[58:61]
	v_mfma_f32_16x16x32_f16 v[42:45], v[154:157], v[178:181], v[42:45]
	v_mfma_f32_16x16x32_f16 v[42:45], v[158:161], v[182:185], v[42:45]
	v_mfma_f32_16x16x32_f16 v[26:29], v[158:161], v[174:177], v[26:29]
	v_mfma_f32_16x16x32_f16 v[26:29], v[154:157], v[170:173], v[26:29]
	v_mfma_f32_16x16x32_f16 v[22:25], v[130:133], v[170:173], v[22:25]
	v_mfma_f32_16x16x32_f16 v[22:25], v[134:137], v[174:177], v[22:25]
	v_mfma_f32_16x16x32_f16 v[54:57], v[134:137], v[190:193], v[54:57]
	v_mfma_f32_16x16x32_f16 v[54:57], v[130:133], v[186:189], v[54:57]
	v_mfma_f32_16x16x32_f16 v[38:41], v[130:133], v[178:181], v[38:41]
	v_mfma_f32_16x16x32_f16 v[38:41], v[134:137], v[182:185], v[38:41]
	v_mfma_f32_16x16x32_f16 v[6:9], v[134:137], v[166:169], v[6:9]
	v_mfma_f32_16x16x32_f16 v[6:9], v[130:133], v[162:165], v[6:9]
	v_mfma_f32_16x16x32_f16 v[2:5], v[138:141], v[162:165], v[2:5]
	v_mfma_f32_16x16x32_f16 v[2:5], v[142:145], v[166:169], v[2:5]
	v_mfma_f32_16x16x32_f16 v[50:53], v[142:145], v[190:193], v[50:53]
	v_mfma_f32_16x16x32_f16 v[50:53], v[138:141], v[186:189], v[50:53]
	v_mfma_f32_16x16x32_f16 v[34:37], v[138:141], v[178:181], v[34:37]
	v_mfma_f32_16x16x32_f16 v[34:37], v[142:145], v[182:185], v[34:37]
	v_mfma_f32_16x16x32_f16 v[18:21], v[142:145], v[174:177], v[18:21]
	v_mfma_f32_16x16x32_f16 v[18:21], v[138:141], v[170:173], v[18:21]
	s_barrier
	s_setprio 0
	s_add_i32 s58, s58, 2
	s_add_u32 s54, s54, 0x100
	s_addc_u32 s55, s55, 0
	s_cmp_gt_u32 s58, 13
	s_cbranch_scc1 .LBB0_1123
.LBB0_1113:
	ds_read_b128 v[146:149], v201
	ds_read_b128 v[150:153], v201 offset:1024
	ds_read_b128 v[154:157], v201 offset:2048
	ds_read_b128 v[158:161], v201 offset:3072
	ds_read_b128 v[130:133], v202
	ds_read_b128 v[134:137], v202 offset:1024
	ds_read_b128 v[138:141], v202 offset:2048
	ds_read_b128 v[142:145], v202 offset:3072
	s_mov_b64 s[6:7], s[52:53]
	s_add_u32 s52, s6, 0x100
	s_addc_u32 s53, s7, 0
	s_cmp_eq_u32 s58, 12
	s_cselect_b64 s[26:27], -1, 0
	s_and_b64 s[8:9], s[26:27], exec
	s_cselect_b32 s25, s43, s53
	s_cselect_b32 s24, s56, s52
	s_cselect_b32 s9, s41, s55
	s_cselect_b32 s8, s57, s54
	ds_read_b128 v[162:165], v203
	ds_read_b128 v[166:169], v203 offset:1024
	ds_read_b128 v[170:173], v203 offset:2048
	ds_read_b128 v[174:177], v203 offset:3072
	ds_read_b128 v[178:181], v203 offset:4096
	ds_read_b128 v[182:185], v203 offset:5120
	ds_read_b128 v[186:189], v203 offset:6144
	ds_read_b128 v[190:193], v203 offset:7168
	s_add_u32 s6, s6, 0x40080
	s_addc_u32 s7, s7, 0
	s_add_u32 m0, s28, 0xc000
	s_nop 0
	global_load_lds_dwordx4 v1, s[6:7]
	s_nop 0
	s_add_u32 m0, s28, 0xe000
	s_nop 0
	global_load_lds_dwordx4 v199, s[6:7]
	s_waitcnt vmcnt(8)
	s_waitcnt lgkmcnt(0)
	s_barrier
	v_mfma_f32_16x16x32_f16 v[126:129], v[146:149], v[162:165], v[126:129]
	s_setprio 1
	v_mfma_f32_16x16x32_f16 v[126:129], v[150:153], v[166:169], v[126:129]
	v_mfma_f32_16x16x32_f16 v[110:113], v[150:153], v[174:177], v[110:113]
	v_mfma_f32_16x16x32_f16 v[110:113], v[146:149], v[170:173], v[110:113]
	v_mfma_f32_16x16x32_f16 v[94:97], v[146:149], v[178:181], v[94:97]
	v_mfma_f32_16x16x32_f16 v[94:97], v[150:153], v[182:185], v[94:97]
	v_mfma_f32_16x16x32_f16 v[78:81], v[150:153], v[190:193], v[78:81]
	v_mfma_f32_16x16x32_f16 v[78:81], v[146:149], v[186:189], v[78:81]
	v_mfma_f32_16x16x32_f16 v[74:77], v[154:157], v[186:189], v[74:77]
	v_mfma_f32_16x16x32_f16 v[74:77], v[158:161], v[190:193], v[74:77]
	v_mfma_f32_16x16x32_f16 v[122:125], v[158:161], v[166:169], v[122:125]
	v_mfma_f32_16x16x32_f16 v[122:125], v[154:157], v[162:165], v[122:125]
	v_mfma_f32_16x16x32_f16 v[106:109], v[154:157], v[170:173], v[106:109]
	v_mfma_f32_16x16x32_f16 v[106:109], v[158:161], v[174:177], v[106:109]
	v_mfma_f32_16x16x32_f16 v[90:93], v[158:161], v[182:185], v[90:93]
	v_mfma_f32_16x16x32_f16 v[90:93], v[154:157], v[178:181], v[90:93]
	v_mfma_f32_16x16x32_f16 v[86:89], v[130:133], v[178:181], v[86:89]
	v_mfma_f32_16x16x32_f16 v[86:89], v[134:137], v[182:185], v[86:89]
	v_mfma_f32_16x16x32_f16 v[118:121], v[134:137], v[166:169], v[118:121]
	v_mfma_f32_16x16x32_f16 v[118:121], v[130:133], v[162:165], v[118:121]
	v_mfma_f32_16x16x32_f16 v[102:105], v[130:133], v[170:173], v[102:105]
	v_mfma_f32_16x16x32_f16 v[102:105], v[134:137], v[174:177], v[102:105]
	v_mfma_f32_16x16x32_f16 v[70:73], v[134:137], v[190:193], v[70:73]
	v_mfma_f32_16x16x32_f16 v[70:73], v[130:133], v[186:189], v[70:73]
	v_mfma_f32_16x16x32_f16 v[66:69], v[138:141], v[186:189], v[66:69]
	v_mfma_f32_16x16x32_f16 v[66:69], v[142:145], v[190:193], v[66:69]
	v_mfma_f32_16x16x32_f16 v[114:117], v[142:145], v[166:169], v[114:117]
	v_mfma_f32_16x16x32_f16 v[114:117], v[138:141], v[162:165], v[114:117]
	v_mfma_f32_16x16x32_f16 v[98:101], v[138:141], v[170:173], v[98:101]
	v_mfma_f32_16x16x32_f16 v[98:101], v[142:145], v[174:177], v[98:101]
	v_mfma_f32_16x16x32_f16 v[82:85], v[142:145], v[182:185], v[82:85]
	v_mfma_f32_16x16x32_f16 v[82:85], v[138:141], v[178:181], v[82:85]
	s_barrier
	s_setprio 0
	ds_read_b128 v[186:189], v203 offset:16384
	ds_read_b128 v[190:193], v203 offset:17408
	ds_read_b128 v[178:181], v203 offset:18432
	ds_read_b128 v[182:185], v203 offset:19456
	ds_read_b128 v[170:173], v203 offset:20480
	ds_read_b128 v[174:177], v203 offset:21504
	ds_read_b128 v[162:165], v203 offset:22528
	ds_read_b128 v[166:169], v203 offset:23552
	s_and_b64 s[6:7], s[4:5], s[26:27]
	s_mov_b64 s[26:27], -1
	s_and_b64 vcc, exec, s[6:7]
	s_cbranch_vccnz .LBB0_1115
	s_add_u32 m0, s28, 0x10000
	s_nop 0
	global_load_lds_dwordx4 v198, s[8:9]
	s_nop 0
	s_add_u32 m0, s28, 0x12000
	s_nop 0
	global_load_lds_dwordx4 v200, s[8:9]
	s_add_u32 s26, s8, 0x40000
	s_addc_u32 s27, s9, 0
	s_add_u32 m0, s28, 0x14000
	s_nop 0
	global_load_lds_dwordx4 v198, s[26:27]
	s_nop 0
	s_add_u32 m0, s28, 0x16000
	s_nop 0
	global_load_lds_dwordx4 v200, s[26:27]
	s_mov_b64 s[26:27], 0
	s_add_u32 m0, s28, 0
	s_nop 0
	global_load_lds_dwordx4 v1, s[24:25]
	s_nop 0
	s_add_u32 m0, s28, 0x2000
	s_nop 0
	global_load_lds_dwordx4 v199, s[24:25]
	s_waitcnt vmcnt(8)

; #define PG8_STAGE(bufoff, gbase, voff) do { if constexpr (ABL & 1) break; glds16s<(bufoff)>((voff)[0], (const void*)(gbase), ldsbw); glds16s<(bufoff) + 8192>((voff)[1], (const void*)(gbase), ldsbw); } while (0)
; #define PG8_LDA(dst, b, h) do { if constexpr (ABL & 4) break; _Pragma("unroll") for (int m = 0; m < 4; ++m) _Pragma("unroll") for (int k = 0; k < 2; ++k) dst[m][k] = *(const LAS f16x8*)(lds + PG8_SA(b, h) + aoff + m * 2048 + k * 1024); } while (0)
; #define PG8_LDB(dst, b, h) do { if constexpr (ABL & 4) break; _Pragma("unroll") for (int n = 0; n < 2; ++n) _Pragma("unroll") for (int k = 0; k < 2; ++k) dst[n][k] = *(const LAS f16x8*)(lds + PG8_SB(b, h) + boff + n * 2048 + k * 1024); } while (0)
; #define PG8_MMA(ai, bj, At, Bt) do { if constexpr (ABL & 2) break; __builtin_amdgcn_s_setprio(1); _Pragma("unroll") for (int m = 0; m < 4; ++m) _Pragma("unroll") for (int n = 0; n < 2; ++n) _Pragma("unroll") for (int k = 0; k < 2; ++k) \
;         acc[ai][bj][m][n] = __builtin_amdgcn_mfma_f32_16x16x32_f16(Bt[n][k], At[m][k], acc[ai][bj][m][n], 0, 0, 0); __builtin_amdgcn_s_setprio(0); } while (0)
; #define PG8_MMAF(ai, bj, At, Bt) do { if (t == 0) PG8_MMA0(ai, bj, At, Bt); else PG8_MMA(ai, bj, At, Bt); } while (0)
; #define PG8_WAIT_V(n) asm volatile("s_waitcnt vmcnt(" #n ")" ::: "memory")
; #define PG8_WAIT_L(n) asm volatile("s_waitcnt lgkmcnt(" #n ")" ::: "memory")
; #define PG8_BAR __builtin_amdgcn_s_barrier()
; #define PG8_SCHED __builtin_amdgcn_sched_barrier(0)
;     ...
;             if (!fin) PG8_WAIT_V(8); else PG8_WAIT_V(2); PG8_WAIT_L(0); PG8_BAR; PG8_MMAF(1, 0, At, B0); PG8_MMAF(1, 1, At, B1); PG8_BAR; PG8_SCHED;
;             PG8_LDB(B0, 1, 0); PG8_LDB(B1, 1, 1); PG8_SCHED; PG8_LDA(At, 1, 0); if (!fin) PG8_STAGE(PG8_SA(0, 1), a2 + hstep, voffA);
;             if (!fin) PG8_WAIT_V(8); else PG8_WAIT_V(0); PG8_WAIT_L(0); PG8_BAR; PG8_MMA(0, 0, At, B0); PG8_MMA(0, 1, At, B1); PG8_BAR; PG8_SCHED;
.LBB0_1117:
	s_waitcnt lgkmcnt(0)
	s_xor_b64 s[26:27], s[6:7], -1
	s_barrier
	v_mfma_f32_16x16x32_f16 v[62:65], v[146:149], v[186:189], v[62:65]
	s_setprio 1
	v_mfma_f32_16x16x32_f16 v[62:65], v[150:153], v[190:193], v[62:65]
	v_mfma_f32_16x16x32_f16 v[46:49], v[150:153], v[182:185], v[46:49]
	v_mfma_f32_16x16x32_f16 v[46:49], v[146:149], v[178:181], v[46:49]
	v_mfma_f32_16x16x32_f16 v[30:33], v[146:149], v[170:173], v[30:33]
	v_mfma_f32_16x16x32_f16 v[30:33], v[150:153], v[174:177], v[30:33]
	v_mfma_f32_16x16x32_f16 v[14:17], v[150:153], v[166:169], v[14:17]
	v_mfma_f32_16x16x32_f16 v[14:17], v[146:149], v[162:165], v[14:17]
	v_mfma_f32_16x16x32_f16 v[10:13], v[154:157], v[162:165], v[10:13]
	v_mfma_f32_16x16x32_f16 v[10:13], v[158:161], v[166:169], v[10:13]
	v_mfma_f32_16x16x32_f16 v[58:61], v[158:161], v[190:193], v[58:61]
	v_mfma_f32_16x16x32_f16 v[58:61], v[154:157], v[186:189], v[58:61]
	v_mfma_f32_16x16x32_f16 v[42:45], v[154:157], v[178:181], v[42:45]
	v_mfma_f32_16x16x32_f16 v[42:45], v[158:161], v[182:185], v[42:45]
	v_mfma_f32_16x16x32_f16 v[26:29], v[158:161], v[174:177], v[26:29]
	v_mfma_f32_16x16x32_f16 v[26:29], v[154:157], v[170:173], v[26:29]
	v_mfma_f32_16x16x32_f16 v[22:25], v[130:133], v[170:173], v[22:25]
	v_mfma_f32_16x16x32_f16 v[22:25], v[134:137], v[174:177], v[22:25]
	v_mfma_f32_16x16x32_f16 v[54:57], v[134:137], v[190:193], v[54:57]
	v_mfma_f32_16x16x32_f16 v[54:57], v[130:133], v[186:189], v[54:57]
	v_mfma_f32_16x16x32_f16 v[38:41], v[130:133], v[178:181], v[38:41]
	v_mfma_f32_16x16x32_f16 v[38:41], v[134:137], v[182:185], v[38:41]
	v_mfma_f32_16x16x32_f16 v[6:9], v[134:137], v[166:169], v[6:9]
	v_mfma_f32_16x16x32_f16 v[6:9], v[130:133], v[162:165], v[6:9]
	v_mfma_f32_16x16x32_f16 v[2:5], v[138:141], v[162:165], v[2:5]
	v_mfma_f32_16x16x32_f16 v[2:5], v[142:145], v[166:169], v[2:5]
	v_mfma_f32_16x16x32_f16 v[50:53], v[142:145], v[190:193], v[50:53]
	v_mfma_f32_16x16x32_f16 v[50:53], v[138:141], v[186:189], v[50:53]
	v_mfma_f32_16x16x32_f16 v[34:37], v[138:141], v[178:181], v[34:37]
	v_mfma_f32_16x16x32_f16 v[34:37], v[142:145], v[182:185], v[34:37]
	v_mfma_f32_16x16x32_f16 v[18:21], v[142:145], v[174:177], v[18:21]
	v_mfma_f32_16x16x32_f16 v[18:21], v[138:141], v[170:173], v[18:21]
	s_barrier
	s_setprio 0
	ds_read_b128 v[146:149], v204
	ds_read_b128 v[150:153], v204 offset:1024
	ds_read_b128 v[154:157], v204 offset:2048
	ds_read_b128 v[158:161], v204 offset:3072
	ds_read_b128 v[130:133], v205
	ds_read_b128 v[134:137], v205 offset:1024
	ds_read_b128 v[138:141], v205 offset:2048
	ds_read_b128 v[142:145], v205 offset:3072
	ds_read_b128 v[186:189], v203 offset:32768
	ds_read_b128 v[190:193], v203 offset:33792
	ds_read_b128 v[178:181], v203 offset:34816
	ds_read_b128 v[182:185], v203 offset:35840
	ds_read_b128 v[170:173], v203 offset:36864
	ds_read_b128 v[174:177], v203 offset:37888
	ds_read_b128 v[162:165], v203 offset:38912
	ds_read_b128 v[166:169], v203 offset:39936
	v_cndmask_b32_e64 v209, 0, 1, s[26:27]
	v_cmp_ne_u32_e64 s[6:7], 1, v209
	s_andn2_b64 vcc, exec, s[26:27]
	s_mov_b64 s[26:27], -1
	s_cbranch_vccnz .LBB0_1119
	s_add_u32 s26, s24, 0x40000
	s_addc_u32 s27, s25, 0
	s_add_u32 m0, s28, 0x4000
	s_nop 0
	global_load_lds_dwordx4 v1, s[26:27]
	s_nop 0
	s_add_u32 m0, s28, 0x6000
	s_nop 0
	global_load_lds_dwordx4 v199, s[26:27]
	s_waitcnt vmcnt(8)
	s_mov_b64 s[26:27], 0

; #define PG8_STAGE(bufoff, gbase, voff) do { if constexpr (ABL & 1) break; glds16s<(bufoff)>((voff)[0], (const void*)(gbase), ldsbw); glds16s<(bufoff) + 8192>((voff)[1], (const void*)(gbase), ldsbw); } while (0)
; #define PG8_LDA(dst, b, h) do { if constexpr (ABL & 4) break; _Pragma("unroll") for (int m = 0; m < 4; ++m) _Pragma("unroll") for (int k = 0; k < 2; ++k) dst[m][k] = *(const LAS f16x8*)(lds + PG8_SA(b, h) + aoff + m * 2048 + k * 1024); } while (0)
; #define PG8_MMA(ai, bj, At, Bt) do { if constexpr (ABL & 2) break; __builtin_amdgcn_s_setprio(1); _Pragma("unroll") for (int m = 0; m < 4; ++m) _Pragma("unroll") for (int n = 0; n < 2; ++n) _Pragma("unroll") for (int k = 0; k < 2; ++k) \
;         acc[ai][bj][m][n] = __builtin_amdgcn_mfma_f32_16x16x32_f16(Bt[n][k], At[m][k], acc[ai][bj][m][n], 0, 0, 0); __builtin_amdgcn_s_setprio(0); } while (0)
; #define PG8_WAIT_V(n) asm volatile("s_waitcnt vmcnt(" #n ")" ::: "memory")
; #define PG8_WAIT_L(n) asm volatile("s_waitcnt lgkmcnt(" #n ")" ::: "memory")
; #define PG8_BAR __builtin_amdgcn_s_barrier()
; #define PG8_SCHED __builtin_amdgcn_sched_barrier(0)
;     ...
;             if (!fin) PG8_WAIT_V(8); else PG8_WAIT_V(0); PG8_WAIT_L(0); PG8_BAR; PG8_MMA(0, 0, At, B0); PG8_MMA(0, 1, At, B1); PG8_BAR; PG8_SCHED;
;             PG8_LDA(At, 1, 1); if (!fin) { PG8_STAGE(PG8_SB(1, 0), b3, voffB); PG8_STAGE(PG8_SB(1, 1), b3 + hstep, voffB); PG8_STAGE(PG8_SA(1, 0), a3, voffA); }
;             if (!fin) PG8_WAIT_V(8); PG8_WAIT_L(0); PG8_BAR; PG8_MMA(1, 0, At, B0); PG8_MMA(1, 1, At, B1); PG8_BAR; PG8_SCHED;
.LBB0_1121:
	s_waitcnt lgkmcnt(0)
	s_barrier
	v_mfma_f32_16x16x32_f16 v[126:129], v[146:149], v[186:189], v[126:129]
	s_setprio 1
	v_mfma_f32_16x16x32_f16 v[126:129], v[150:153], v[190:193], v[126:129]
	v_mfma_f32_16x16x32_f16 v[110:113], v[150:153], v[182:185], v[110:113]
	v_mfma_f32_16x16x32_f16 v[110:113], v[146:149], v[178:181], v[110:113]
	v_mfma_f32_16x16x32_f16 v[94:97], v[146:149], v[170:173], v[94:97]
	v_mfma_f32_16x16x32_f16 v[94:97], v[150:153], v[174:177], v[94:97]
	v_mfma_f32_16x16x32_f16 v[78:81], v[150:153], v[166:169], v[78:81]
	v_mfma_f32_16x16x32_f16 v[78:81], v[146:149], v[162:165], v[78:81]
	v_mfma_f32_16x16x32_f16 v[74:77], v[154:157], v[162:165], v[74:77]
	v_mfma_f32_16x16x32_f16 v[74:77], v[158:161], v[166:169], v[74:77]
	v_mfma_f32_16x16x32_f16 v[122:125], v[158:161], v[190:193], v[122:125]
	v_mfma_f32_16x16x32_f16 v[122:125], v[154:157], v[186:189], v[122:125]
	v_mfma_f32_16x16x32_f16 v[106:109], v[154:157], v[178:181], v[106:109]
	v_mfma_f32_16x16x32_f16 v[106:109], v[158:161], v[182:185], v[106:109]
	v_mfma_f32_16x16x32_f16 v[90:93], v[158:161], v[174:177], v[90:93]
	v_mfma_f32_16x16x32_f16 v[90:93], v[154:157], v[170:173], v[90:93]
	v_mfma_f32_16x16x32_f16 v[86:89], v[130:133], v[170:173], v[86:89]
	v_mfma_f32_16x16x32_f16 v[86:89], v[134:137], v[174:177], v[86:89]
	v_mfma_f32_16x16x32_f16 v[118:121], v[134:137], v[190:193], v[118:121]
	v_mfma_f32_16x16x32_f16 v[118:121], v[130:133], v[186:189], v[118:121]
	v_mfma_f32_16x16x32_f16 v[102:105], v[130:133], v[178:181], v[102:105]
	v_mfma_f32_16x16x32_f16 v[102:105], v[134:137], v[182:185], v[102:105]
	v_mfma_f32_16x16x32_f16 v[70:73], v[134:137], v[166:169], v[70:73]
	v_mfma_f32_16x16x32_f16 v[70:73], v[130:133], v[162:165], v[70:73]
	v_mfma_f32_16x16x32_f16 v[66:69], v[138:141], v[162:165], v[66:69]
	v_mfma_f32_16x16x32_f16 v[66:69], v[142:145], v[166:169], v[66:69]
	v_mfma_f32_16x16x32_f16 v[114:117], v[142:145], v[190:193], v[114:117]
	v_mfma_f32_16x16x32_f16 v[114:117], v[138:141], v[186:189], v[114:117]
	v_mfma_f32_16x16x32_f16 v[98:101], v[138:141], v[178:181], v[98:101]
	v_mfma_f32_16x16x32_f16 v[98:101], v[142:145], v[182:185], v[98:101]
	v_mfma_f32_16x16x32_f16 v[82:85], v[142:145], v[174:177], v[82:85]
	v_mfma_f32_16x16x32_f16 v[82:85], v[138:141], v[170:173], v[82:85]
	s_barrier
	s_setprio 0
	ds_read_b128 v[186:189], v203 offset:49152
	ds_read_b128 v[190:193], v203 offset:50176
	ds_read_b128 v[178:181], v203 offset:51200
	ds_read_b128 v[182:185], v203 offset:52224
	ds_read_b128 v[170:173], v203 offset:53248
	ds_read_b128 v[174:177], v203 offset:54272
	ds_read_b128 v[162:165], v203 offset:55296
	ds_read_b128 v[166:169], v203 offset:56320
	s_and_b64 vcc, exec, s[6:7]
	s_cbranch_vccnz .LBB0_1112
	s_add_u32 s6, s24, 0x80
	s_addc_u32 s7, s25, 0
	s_add_u32 s24, s8, 0x80
	s_addc_u32 s25, s9, 0
	s_add_u32 m0, s28, 0x18000
	s_nop 0
	global_load_lds_dwordx4 v198, s[24:25]
	s_nop 0
	s_add_u32 m0, s28, 0x1a000
	s_nop 0
	global_load_lds_dwordx4 v200, s[24:25]
	s_add_u32 s8, s8, 0x40080
	s_addc_u32 s9, s9, 0
	s_add_u32 m0, s28, 0x1c000
	s_nop 0
	global_load_lds_dwordx4 v198, s[8:9]
	s_nop 0
	s_add_u32 m0, s28, 0x1e000
	s_nop 0
	global_load_lds_dwordx4 v200, s[8:9]
	s_nop 0
	s_add_u32 m0, s28, 0x8000
	s_nop 0
	global_load_lds_dwordx4 v1, s[6:7]
	s_nop 0
	s_add_u32 m0, s28, 0xa000
	s_nop 0
	global_load_lds_dwordx4 v199, s[6:7]
	s_waitcnt vmcnt(8)
	s_branch .LBB0_1112

;     __device__ __forceinline__ bool next(int i, Unit& u) const { if (i >= count) return false; const int L = first + i; u.pm = L / nN; u.pn = L % nN; return true; }
; #define PG8_STAGE(bufoff, gbase, voff) do { if constexpr (ABL & 1) break; glds16s<(bufoff)>((voff)[0], (const void*)(gbase), ldsbw); glds16s<(bufoff) + 8192>((voff)[1], (const void*)(gbase), ldsbw); } while (0)
; #define PG8_LDA(dst, b, h) do { if constexpr (ABL & 4) break; _Pragma("unroll") for (int m = 0; m < 4; ++m) _Pragma("unroll") for (int k = 0; k < 2; ++k) dst[m][k] = *(const LAS f16x8*)(lds + PG8_SA(b, h) + aoff + m * 2048 + k * 1024); } while (0)
; #define PG8_LDB(dst, b, h) do { if constexpr (ABL & 4) break; _Pragma("unroll") for (int n = 0; n < 2; ++n) _Pragma("unroll") for (int k = 0; k < 2; ++k) dst[n][k] = *(const LAS f16x8*)(lds + PG8_SB(b, h) + boff + n * 2048 + k * 1024); } while (0)
; #define PG8_MMAF(ai, bj, At, Bt) do { if (t == 0) PG8_MMA0(ai, bj, At, Bt); else PG8_MMA(ai, bj, At, Bt); } while (0)
; #define PG8_WAIT_V(n) asm volatile("s_waitcnt vmcnt(" #n ")" ::: "memory")
; #define PG8_BAR __builtin_amdgcn_s_barrier()
;     ...
;         const bool has_next = S.next(ui + 1, nxt);
;         const char* nA = has_next ? (const char*)g.A + (size_t)nxt.pm * tstep : cA; const char* nB = has_next ? (const char*)g.Bt + (size_t)nxt.pn * tstep : cB;
;         for (int t = 0; t < nt; t += 2) {
;             const bool last = (t == nt - 2);
;             const char* a1 = cA + (size_t)(t + 1) * kstep;
;             const char* a2 = last ? nA : cA + (size_t)(t + 2) * kstep; const char* b2 = last ? nB : cB + (size_t)(t + 2) * kstep;
;             const char* a3 = a2 + kstep; const char* b3 = b2 + kstep;
;             if (last && has_next) S.a_ready(nxt);
;             if constexpr (SP2) {
;             PG8_LDB(B0, 0, 0); PG8_LDB(B1, 0, 1); PG8_SCHED; PG8_LDA(At, 0, 0); PG8_STAGE(PG8_SA(1, 1), a1 + hstep, voffA);
;             PG8_WAIT_V(8); PG8_WAIT_L(0); PG8_BAR; PG8_MMAF(0, 0, At, B0); PG8_MMAF(0, 1, At, B1); PG8_BAR; PG8_SCHED;
;             const bool fin = last && !has_next;
;             PG8_LDA(At, 0, 1); if (!fin) { PG8_STAGE(PG8_SB(0, 0), b2, voffB); PG8_STAGE(PG8_SB(0, 1), b2 + hstep, voffB); PG8_STAGE(PG8_SA(0, 0), a2, voffA); }
;             if (!fin) PG8_WAIT_V(8); else PG8_WAIT_V(2); PG8_WAIT_L(0); PG8_BAR; PG8_MMAF(1, 0, At, B0); PG8_MMAF(1, 1, At, B1); PG8_BAR; PG8_SCHED;
.LBB0_1163:
	s_ashr_i32 s49, s48, 31
	s_lshl_b64 s[6:7], s[48:49], 19
	s_add_u32 s50, s74, s6
	s_addc_u32 s51, s75, s7
	s_and_b64 s[6:7], exec, s[2:3]
	ds_read_b128 v[2:5], v213
	ds_read_b128 v[6:9], v213 offset:1024
	ds_read_b128 v[10:13], v213 offset:2048
	ds_read_b128 v[14:17], v213 offset:3072
	ds_read_b128 v[18:21], v214
	ds_read_b128 v[22:25], v214 offset:1024
	ds_read_b128 v[26:29], v214 offset:2048
	ds_read_b128 v[30:33], v214 offset:3072
	s_cselect_b32 s45, s37, s51
	s_cselect_b32 s49, s36, s50
	s_ashr_i32 s47, s46, 31
	s_lshl_b64 s[6:7], s[46:47], 19
	s_add_u32 s52, s94, s6
	s_addc_u32 s53, s95, s7
	s_and_b64 s[6:7], exec, s[2:3]
	s_cselect_b32 s47, s39, s53
	s_cselect_b32 s57, s38, s52
	s_add_u32 s24, s36, 0x100
	s_addc_u32 s25, s37, 0
	s_add_u32 s26, s38, 0x100
	s_addc_u32 s27, s39, 0
	s_add_u32 s6, s36, 0x180
	s_addc_u32 s7, s37, 0
	ds_read_b128 v[34:37], v215
	ds_read_b128 v[38:41], v215 offset:1024
	ds_read_b128 v[42:45], v215 offset:2048
	ds_read_b128 v[46:49], v215 offset:3072
	ds_read_b128 v[50:53], v215 offset:4096
	ds_read_b128 v[54:57], v215 offset:5120
	ds_read_b128 v[58:61], v215 offset:6144
	ds_read_b128 v[62:65], v215 offset:7168
	s_add_u32 s8, s38, 0x180
	s_addc_u32 s9, s39, 0
	s_add_u32 s54, s36, 0x40080
	s_addc_u32 s55, s37, 0
	s_add_u32 m0, s35, 0xc000
	s_nop 0
	global_load_lds_dwordx4 v1, s[54:55]
	s_nop 0
	s_add_u32 m0, s35, 0xe000
	s_nop 0
	global_load_lds_dwordx4 v211, s[54:55]
	s_waitcnt vmcnt(8)
	s_waitcnt lgkmcnt(0)
	s_barrier
	v_mfma_f32_16x16x32_f16 v[90:93], v[2:5], v[58:61], 0
	s_setprio 1
	v_mfma_f32_16x16x32_f16 v[98:101], v[6:9], v[62:65], v[90:93]
	v_mfma_f32_16x16x32_f16 v[66:69], v[2:5], v[34:37], 0
	v_mfma_f32_16x16x32_f16 v[66:69], v[6:9], v[38:41], v[66:69]
	v_mfma_f32_16x16x32_f16 v[70:73], v[10:13], v[34:37], 0
	v_mfma_f32_16x16x32_f16 v[70:73], v[14:17], v[38:41], v[70:73]
	v_mfma_f32_16x16x32_f16 v[74:77], v[2:5], v[42:45], 0
	v_mfma_f32_16x16x32_f16 v[74:77], v[6:9], v[46:49], v[74:77]
	v_mfma_f32_16x16x32_f16 v[78:81], v[10:13], v[42:45], 0
	v_mfma_f32_16x16x32_f16 v[78:81], v[14:17], v[46:49], v[78:81]
	v_mfma_f32_16x16x32_f16 v[82:85], v[2:5], v[50:53], 0
	v_mfma_f32_16x16x32_f16 v[82:85], v[6:9], v[54:57], v[82:85]
	v_mfma_f32_16x16x32_f16 v[86:89], v[10:13], v[50:53], 0
	v_mfma_f32_16x16x32_f16 v[86:89], v[14:17], v[54:57], v[86:89]
	v_mfma_f32_16x16x32_f16 v[90:93], v[10:13], v[58:61], 0
	v_mfma_f32_16x16x32_f16 v[102:105], v[14:17], v[62:65], v[90:93]
	v_mfma_f32_16x16x32_f16 v[90:93], v[18:21], v[34:37], 0
	v_mfma_f32_16x16x32_f16 v[114:117], v[22:25], v[38:41], v[90:93]
	v_mfma_f32_16x16x32_f16 v[34:37], v[26:29], v[34:37], 0
	v_mfma_f32_16x16x32_f16 v[34:37], v[30:33], v[38:41], v[34:37]
	v_mfma_f32_16x16x32_f16 v[38:41], v[18:21], v[42:45], 0
	v_mfma_f32_16x16x32_f16 v[38:41], v[22:25], v[46:49], v[38:41]
	v_mfma_f32_16x16x32_f16 v[42:45], v[26:29], v[42:45], 0
	v_mfma_f32_16x16x32_f16 v[42:45], v[30:33], v[46:49], v[42:45]
	v_mfma_f32_16x16x32_f16 v[46:49], v[18:21], v[50:53], 0
	v_mfma_f32_16x16x32_f16 v[46:49], v[22:25], v[54:57], v[46:49]
	v_mfma_f32_16x16x32_f16 v[50:53], v[26:29], v[50:53], 0
	v_mfma_f32_16x16x32_f16 v[50:53], v[30:33], v[54:57], v[50:53]
	v_mfma_f32_16x16x32_f16 v[54:57], v[18:21], v[58:61], 0
	v_mfma_f32_16x16x32_f16 v[54:57], v[22:25], v[62:65], v[54:57]
	v_mfma_f32_16x16x32_f16 v[58:61], v[26:29], v[58:61], 0
	v_mfma_f32_16x16x32_f16 v[58:61], v[30:33], v[62:65], v[58:61]
	s_barrier
	s_setprio 0
	ds_read_b128 v[62:65], v215 offset:16384
	ds_read_b128 v[90:93], v215 offset:17408
	ds_read_b128 v[94:97], v215 offset:18432
	ds_read_b128 v[106:109], v215 offset:19456
	ds_read_b128 v[110:113], v215 offset:20480
	ds_read_b128 v[118:121], v215 offset:21504
	ds_read_b128 v[122:125], v215 offset:22528
	ds_read_b128 v[126:129], v215 offset:23552
	s_add_u32 m0, s35, 0x10000
	s_nop 0
	global_load_lds_dwordx4 v210, s[26:27]
	s_nop 0
	s_add_u32 m0, s35, 0x12000
	s_nop 0
	global_load_lds_dwordx4 v212, s[26:27]
	s_add_u32 s26, s38, 0x40100
	s_addc_u32 s27, s39, 0
	s_add_u32 m0, s35, 0x14000
	s_nop 0
	global_load_lds_dwordx4 v210, s[26:27]
	s_nop 0
	s_add_u32 m0, s35, 0x16000
	s_nop 0
	global_load_lds_dwordx4 v212, s[26:27]
	s_nop 0
	s_add_u32 m0, s35, 0
	s_nop 0
	global_load_lds_dwordx4 v1, s[24:25]
	s_nop 0
	s_add_u32 m0, s35, 0x2000
	s_nop 0
	global_load_lds_dwordx4 v211, s[24:25]
	s_waitcnt vmcnt(8)
	s_waitcnt lgkmcnt(0)
	s_barrier
	v_mfma_f32_16x16x32_f16 v[134:137], v[10:13], v[62:65], 0
	s_setprio 1
	v_mfma_f32_16x16x32_f16 v[146:149], v[14:17], v[90:93], v[134:137]
	v_mfma_f32_16x16x32_f16 v[134:137], v[2:5], v[94:97], 0
	v_mfma_f32_16x16x32_f16 v[150:153], v[6:9], v[106:109], v[134:137]
	v_mfma_f32_16x16x32_f16 v[134:137], v[10:13], v[94:97], 0
	v_mfma_f32_16x16x32_f16 v[154:157], v[14:17], v[106:109], v[134:137]
	v_mfma_f32_16x16x32_f16 v[130:133], v[2:5], v[62:65], 0
	v_mfma_f32_16x16x32_f16 v[130:133], v[6:9], v[90:93], v[130:133]
	v_mfma_f32_16x16x32_f16 v[134:137], v[2:5], v[110:113], 0
	v_mfma_f32_16x16x32_f16 v[158:161], v[6:9], v[118:121], v[134:137]
	v_mfma_f32_16x16x32_f16 v[2:5], v[2:5], v[122:125], 0
	v_mfma_f32_16x16x32_f16 v[2:5], v[6:9], v[126:129], v[2:5]
	v_mfma_f32_16x16x32_f16 v[6:9], v[10:13], v[122:125], 0
	v_mfma_f32_16x16x32_f16 v[6:9], v[14:17], v[126:129], v[6:9]
	v_mfma_f32_16x16x32_f16 v[134:137], v[10:13], v[110:113], 0
	v_mfma_f32_16x16x32_f16 v[162:165], v[14:17], v[118:121], v[134:137]
	v_mfma_f32_16x16x32_f16 v[10:13], v[18:21], v[62:65], 0
	v_mfma_f32_16x16x32_f16 v[166:169], v[22:25], v[90:93], v[10:13]
	v_mfma_f32_16x16x32_f16 v[10:13], v[26:29], v[62:65], 0
	v_mfma_f32_16x16x32_f16 v[170:173], v[30:33], v[90:93], v[10:13]
	v_mfma_f32_16x16x32_f16 v[10:13], v[18:21], v[94:97], 0
	v_mfma_f32_16x16x32_f16 v[174:177], v[22:25], v[106:109], v[10:13]
	v_mfma_f32_16x16x32_f16 v[10:13], v[26:29], v[94:97], 0
	v_mfma_f32_16x16x32_f16 v[178:181], v[30:33], v[106:109], v[10:13]
	v_mfma_f32_16x16x32_f16 v[10:13], v[18:21], v[110:113], 0
	v_mfma_f32_16x16x32_f16 v[182:185], v[22:25], v[118:121], v[10:13]
	v_mfma_f32_16x16x32_f16 v[10:13], v[26:29], v[110:113], 0
	v_mfma_f32_16x16x32_f16 v[118:121], v[30:33], v[118:121], v[10:13]
	v_mfma_f32_16x16x32_f16 v[10:13], v[18:21], v[122:125], 0
	v_mfma_f32_16x16x32_f16 v[186:189], v[22:25], v[126:129], v[10:13]
	v_mfma_f32_16x16x32_f16 v[10:13], v[26:29], v[122:125], 0
	v_mfma_f32_16x16x32_f16 v[122:125], v[30:33], v[126:129], v[10:13]
	s_barrier
; #define PG8_STAGE(bufoff, gbase, voff) do { if constexpr (ABL & 1) break; glds16s<(bufoff)>((voff)[0], (const void*)(gbase), ldsbw); glds16s<(bufoff) + 8192>((voff)[1], (const void*)(gbase), ldsbw); } while (0)
; #define PG8_LDA(dst, b, h) do { if constexpr (ABL & 4) break; _Pragma("unroll") for (int m = 0; m < 4; ++m) _Pragma("unroll") for (int k = 0; k < 2; ++k) dst[m][k] = *(const LAS f16x8*)(lds + PG8_SA(b, h) + aoff + m * 2048 + k * 1024); } while (0)
; #define PG8_LDB(dst, b, h) do { if constexpr (ABL & 4) break; _Pragma("unroll") for (int n = 0; n < 2; ++n) _Pragma("unroll") for (int k = 0; k < 2; ++k) dst[n][k] = *(const LAS f16x8*)(lds + PG8_SB(b, h) + boff + n * 2048 + k * 1024); } while (0)
; #define PG8_MMA(ai, bj, At, Bt) do { if constexpr (ABL & 2) break; __builtin_amdgcn_s_setprio(1); _Pragma("unroll") for (int m = 0; m < 4; ++m) _Pragma("unroll") for (int n = 0; n < 2; ++n) _Pragma("unroll") for (int k = 0; k < 2; ++k) \
;         acc[ai][bj][m][n] = __builtin_amdgcn_mfma_f32_16x16x32_f16(Bt[n][k], At[m][k], acc[ai][bj][m][n], 0, 0, 0); __builtin_amdgcn_s_setprio(0); } while (0)
; #define PG8_MMAF(ai, bj, At, Bt) do { if (t == 0) PG8_MMA0(ai, bj, At, Bt); else PG8_MMA(ai, bj, At, Bt); } while (0)
; #define PG8_WAIT_V(n) asm volatile("s_waitcnt vmcnt(" #n ")" ::: "memory")
; #define PG8_WAIT_L(n) asm volatile("s_waitcnt lgkmcnt(" #n ")" ::: "memory")
; #define PG8_BAR __builtin_amdgcn_s_barrier()
; #define PG8_SCHED __builtin_amdgcn_sched_barrier(0)
;     ...
;             if (!fin) PG8_WAIT_V(8); else PG8_WAIT_V(2); PG8_WAIT_L(0); PG8_BAR; PG8_MMAF(1, 0, At, B0); PG8_MMAF(1, 1, At, B1); PG8_BAR; PG8_SCHED;
;             PG8_LDB(B0, 1, 0); PG8_LDB(B1, 1, 1); PG8_SCHED; PG8_LDA(At, 1, 0); if (!fin) PG8_STAGE(PG8_SA(0, 1), a2 + hstep, voffA);
;             if (!fin) PG8_WAIT_V(8); else PG8_WAIT_V(0); PG8_WAIT_L(0); PG8_BAR; PG8_MMA(0, 0, At, B0); PG8_MMA(0, 1, At, B1); PG8_BAR; PG8_SCHED;
;             PG8_LDA(At, 1, 1); if (!fin) { PG8_STAGE(PG8_SB(1, 0), b3, voffB); PG8_STAGE(PG8_SB(1, 1), b3 + hstep, voffB); PG8_STAGE(PG8_SA(1, 0), a3, voffA); }
;             if (!fin) PG8_WAIT_V(8); PG8_WAIT_L(0); PG8_BAR; PG8_MMA(1, 0, At, B0); PG8_MMA(1, 1, At, B1); PG8_BAR; PG8_SCHED;
	s_setprio 0
	s_nop 4
	ds_read_b128 v[10:13], v216
	ds_read_b128 v[14:17], v216 offset:1024
	ds_read_b128 v[18:21], v216 offset:2048
	ds_read_b128 v[22:25], v216 offset:3072
	ds_read_b128 v[190:193], v217
	ds_read_b128 v[194:197], v217 offset:1024
	ds_read_b128 v[198:201], v217 offset:2048
	ds_read_b128 v[202:205], v217 offset:3072
	ds_read_b128 v[26:29], v215 offset:32768
	ds_read_b128 v[30:33], v215 offset:33792
	ds_read_b128 v[62:65], v215 offset:34816
	ds_read_b128 v[218:221], v215 offset:35840
	ds_read_b128 v[222:225], v215 offset:36864
	ds_read_b128 v[226:229], v215 offset:37888
	ds_read_b128 v[230:233], v215 offset:38912
	ds_read_b128 v[234:237], v215 offset:39936
	s_add_u32 s24, s36, 0x40100
	s_addc_u32 s25, s37, 0
	s_add_u32 m0, s35, 0x4000
	s_nop 0
	global_load_lds_dwordx4 v1, s[24:25]
	s_nop 0
	s_add_u32 m0, s35, 0x6000
	s_nop 0
	global_load_lds_dwordx4 v211, s[24:25]
	s_waitcnt vmcnt(8)
	s_waitcnt lgkmcnt(0)
	s_barrier
	v_mfma_f32_16x16x32_f16 v[66:69], v[10:13], v[26:29], v[66:69]
	s_setprio 1
	v_mfma_f32_16x16x32_f16 v[142:145], v[14:17], v[30:33], v[66:69]
	v_mfma_f32_16x16x32_f16 v[66:69], v[18:21], v[26:29], v[70:73]
	v_mfma_f32_16x16x32_f16 v[138:141], v[22:25], v[30:33], v[66:69]
	v_mfma_f32_16x16x32_f16 v[66:69], v[10:13], v[62:65], v[74:77]
	v_mfma_f32_16x16x32_f16 v[110:113], v[14:17], v[218:221], v[66:69]
	v_mfma_f32_16x16x32_f16 v[66:69], v[18:21], v[62:65], v[78:81]
	v_mfma_f32_16x16x32_f16 v[106:109], v[22:25], v[218:221], v[66:69]
	v_mfma_f32_16x16x32_f16 v[66:69], v[10:13], v[222:225], v[82:85]
	v_mfma_f32_16x16x32_f16 v[94:97], v[14:17], v[226:229], v[66:69]
	v_mfma_f32_16x16x32_f16 v[66:69], v[18:21], v[222:225], v[86:89]
	v_mfma_f32_16x16x32_f16 v[90:93], v[22:25], v[226:229], v[66:69]
	v_mfma_f32_16x16x32_f16 v[66:69], v[10:13], v[230:233], v[98:101]
	v_mfma_f32_16x16x32_f16 v[78:81], v[14:17], v[234:237], v[66:69]
	v_mfma_f32_16x16x32_f16 v[66:69], v[18:21], v[230:233], v[102:105]
	v_mfma_f32_16x16x32_f16 v[74:77], v[22:25], v[234:237], v[66:69]
	v_mfma_f32_16x16x32_f16 v[66:69], v[190:193], v[26:29], v[114:117]
	v_mfma_f32_16x16x32_f16 v[134:137], v[194:197], v[30:33], v[66:69]
	v_mfma_f32_16x16x32_f16 v[26:29], v[198:201], v[26:29], v[34:37]
	v_mfma_f32_16x16x32_f16 v[126:129], v[202:205], v[30:33], v[26:29]
	v_mfma_f32_16x16x32_f16 v[26:29], v[190:193], v[62:65], v[38:41]
	v_mfma_f32_16x16x32_f16 v[102:105], v[194:197], v[218:221], v[26:29]
	v_mfma_f32_16x16x32_f16 v[26:29], v[198:201], v[62:65], v[42:45]
	v_mfma_f32_16x16x32_f16 v[98:101], v[202:205], v[218:221], v[26:29]
	v_mfma_f32_16x16x32_f16 v[26:29], v[190:193], v[222:225], v[46:49]
	v_mfma_f32_16x16x32_f16 v[86:89], v[194:197], v[226:229], v[26:29]
	v_mfma_f32_16x16x32_f16 v[26:29], v[198:201], v[222:225], v[50:53]
	v_mfma_f32_16x16x32_f16 v[82:85], v[202:205], v[226:229], v[26:29]
	v_mfma_f32_16x16x32_f16 v[26:29], v[190:193], v[230:233], v[54:57]
	v_mfma_f32_16x16x32_f16 v[70:73], v[194:197], v[234:237], v[26:29]
	v_mfma_f32_16x16x32_f16 v[26:29], v[198:201], v[230:233], v[58:61]
	v_mfma_f32_16x16x32_f16 v[66:69], v[202:205], v[234:237], v[26:29]
	s_barrier
	s_setprio 0
	ds_read_b128 v[34:37], v215 offset:49152
	ds_read_b128 v[38:41], v215 offset:50176
	ds_read_b128 v[114:117], v215 offset:51200
	ds_read_b128 v[218:221], v215 offset:52224
	ds_read_b128 v[222:225], v215 offset:53248
	ds_read_b128 v[226:229], v215 offset:54272
	ds_read_b128 v[230:233], v215 offset:55296
	ds_read_b128 v[234:237], v215 offset:56320
	s_add_u32 m0, s35, 0x18000
	s_nop 0
	global_load_lds_dwordx4 v210, s[8:9]
	s_nop 0
	s_add_u32 m0, s35, 0x1a000
	s_nop 0
	global_load_lds_dwordx4 v212, s[8:9]
	s_add_u32 s8, s38, 0x40180
	s_addc_u32 s9, s39, 0
	s_add_u32 m0, s35, 0x1c000
	s_nop 0
	global_load_lds_dwordx4 v210, s[8:9]
	s_nop 0
	s_add_u32 m0, s35, 0x1e000
	s_nop 0
	global_load_lds_dwordx4 v212, s[8:9]
	s_nop 0
	s_add_u32 m0, s35, 0x8000
	s_nop 0
	global_load_lds_dwordx4 v1, s[6:7]
	s_nop 0
	s_add_u32 m0, s35, 0xa000
	s_nop 0
	global_load_lds_dwordx4 v211, s[6:7]
	s_waitcnt vmcnt(8)
	s_waitcnt lgkmcnt(0)
	s_barrier
	v_mfma_f32_16x16x32_f16 v[26:29], v[10:13], v[34:37], v[130:133]
	s_setprio 1
	v_mfma_f32_16x16x32_f16 v[62:65], v[14:17], v[38:41], v[26:29]
	v_mfma_f32_16x16x32_f16 v[26:29], v[22:25], v[38:41], v[146:149]
	v_mfma_f32_16x16x32_f16 v[58:61], v[18:21], v[34:37], v[26:29]
	v_mfma_f32_16x16x32_f16 v[26:29], v[10:13], v[114:117], v[150:153]
	v_mfma_f32_16x16x32_f16 v[46:49], v[14:17], v[218:221], v[26:29]
	v_mfma_f32_16x16x32_f16 v[26:29], v[22:25], v[218:221], v[154:157]
	v_mfma_f32_16x16x32_f16 v[42:45], v[18:21], v[114:117], v[26:29]
	v_mfma_f32_16x16x32_f16 v[26:29], v[10:13], v[222:225], v[158:161]
	v_mfma_f32_16x16x32_f16 v[30:33], v[14:17], v[226:229], v[26:29]
	v_mfma_f32_16x16x32_f16 v[26:29], v[22:25], v[226:229], v[162:165]
	v_mfma_f32_16x16x32_f16 v[26:29], v[18:21], v[222:225], v[26:29]
	v_mfma_f32_16x16x32_f16 v[2:5], v[10:13], v[230:233], v[2:5]
	v_mfma_f32_16x16x32_f16 v[14:17], v[14:17], v[234:237], v[2:5]
	v_mfma_f32_16x16x32_f16 v[2:5], v[22:25], v[234:237], v[6:9]
	v_mfma_f32_16x16x32_f16 v[10:13], v[18:21], v[230:233], v[2:5]
	v_mfma_f32_16x16x32_f16 v[2:5], v[190:193], v[34:37], v[166:169]
	v_mfma_f32_16x16x32_f16 v[54:57], v[194:197], v[38:41], v[2:5]
	v_mfma_f32_16x16x32_f16 v[2:5], v[202:205], v[38:41], v[170:173]
	v_mfma_f32_16x16x32_f16 v[50:53], v[198:201], v[34:37], v[2:5]
	v_mfma_f32_16x16x32_f16 v[2:5], v[190:193], v[114:117], v[174:177]
	v_mfma_f32_16x16x32_f16 v[38:41], v[194:197], v[218:221], v[2:5]
	v_mfma_f32_16x16x32_f16 v[2:5], v[202:205], v[218:221], v[178:181]
	v_mfma_f32_16x16x32_f16 v[34:37], v[198:201], v[114:117], v[2:5]
	v_mfma_f32_16x16x32_f16 v[2:5], v[190:193], v[222:225], v[182:185]
	v_mfma_f32_16x16x32_f16 v[22:25], v[194:197], v[226:229], v[2:5]
	v_mfma_f32_16x16x32_f16 v[2:5], v[202:205], v[226:229], v[118:121]
	v_mfma_f32_16x16x32_f16 v[18:21], v[198:201], v[222:225], v[2:5]
	v_mfma_f32_16x16x32_f16 v[2:5], v[190:193], v[230:233], v[186:189]
	v_mfma_f32_16x16x32_f16 v[6:9], v[194:197], v[234:237], v[2:5]
	v_mfma_f32_16x16x32_f16 v[2:5], v[202:205], v[234:237], v[122:125]
	v_mfma_f32_16x16x32_f16 v[2:5], v[198:201], v[230:233], v[2:5]
	s_barrier
	s_setprio 0
	s_mov_b32 s58, 0
	s_mov_b64 s[54:55], 0
	s_branch .LBB0_1165
; #define PG8_STAGE(bufoff, gbase, voff) do { if constexpr (ABL & 1) break; glds16s<(bufoff)>((voff)[0], (const void*)(gbase), ldsbw); glds16s<(bufoff) + 8192>((voff)[1], (const void*)(gbase), ldsbw); } while (0)
; #define PG8_LDA(dst, b, h) do { if constexpr (ABL & 4) break; _Pragma("unroll") for (int m = 0; m < 4; ++m) _Pragma("unroll") for (int k = 0; k < 2; ++k) dst[m][k] = *(const LAS f16x8*)(lds + PG8_SA(b, h) + aoff + m * 2048 + k * 1024); } while (0)
; #define PG8_LDB(dst, b, h) do { if constexpr (ABL & 4) break; _Pragma("unroll") for (int n = 0; n < 2; ++n) _Pragma("unroll") for (int k = 0; k < 2; ++k) dst[n][k] = *(const LAS f16x8*)(lds + PG8_SB(b, h) + boff + n * 2048 + k * 1024); } while (0)
; #define PG8_BAR __builtin_amdgcn_s_barrier()
;     ...
;         for (int t = 0; t < nt; t += 2) {
;             const bool last = (t == nt - 2);
;             const char* a1 = cA + (size_t)(t + 1) * kstep;
;             const char* a2 = last ? nA : cA + (size_t)(t + 2) * kstep; const char* b2 = last ? nB : cB + (size_t)(t + 2) * kstep;
;             const char* a3 = a2 + kstep; const char* b3 = b2 + kstep;
;             if (last && has_next) S.a_ready(nxt);
;             if constexpr (SP2) {
;             PG8_LDB(B0, 0, 0); PG8_LDB(B1, 0, 1); PG8_SCHED; PG8_LDA(At, 0, 0); PG8_STAGE(PG8_SA(1, 1), a1 + hstep, voffA);
;             PG8_WAIT_V(8); PG8_WAIT_L(0); PG8_BAR; PG8_MMAF(0, 0, At, B0); PG8_MMAF(0, 1, At, B1); PG8_BAR; PG8_SCHED;
;             const bool fin = last && !has_next;
;             PG8_LDA(At, 0, 1); if (!fin) { PG8_STAGE(PG8_SB(0, 0), b2, voffB); PG8_STAGE(PG8_SB(0, 1), b2 + hstep, voffB); PG8_STAGE(PG8_SA(0, 0), a2, voffA); }
;             if (!fin) PG8_WAIT_V(8); else PG8_WAIT_V(2); PG8_WAIT_L(0); PG8_BAR; PG8_MMAF(1, 0, At, B0); PG8_MMAF(1, 1, At, B1); PG8_BAR; PG8_SCHED;
;             PG8_LDB(B0, 1, 0); PG8_LDB(B1, 1, 1); PG8_SCHED; PG8_LDA(At, 1, 0); if (!fin) PG8_STAGE(PG8_SA(0, 1), a2 + hstep, voffA);
;             if (!fin) PG8_WAIT_V(8); else PG8_WAIT_V(0); PG8_WAIT_L(0); PG8_BAR; PG8_MMA(0, 0, At, B0); PG8_MMA(0, 1, At, B1); PG8_BAR; PG8_SCHED;
;             PG8_LDA(At, 1, 1); if (!fin) { PG8_STAGE(PG8_SB(1, 0), b3, voffB); PG8_STAGE(PG8_SB(1, 1), b3 + hstep, voffB); PG8_STAGE(PG8_SA(1, 0), a3, voffA); }
;             if (!fin) PG8_WAIT_V(8); PG8_WAIT_L(0); PG8_BAR; PG8_MMA(1, 0, At, B0); PG8_MMA(1, 1, At, B1); PG8_BAR; PG8_SCHED;
.LBB0_1164:
	s_waitcnt lgkmcnt(0)
	s_barrier
	v_mfma_f32_16x16x32_f16 v[62:65], v[158:161], v[186:189], v[62:65]
	s_setprio 1
	v_mfma_f32_16x16x32_f16 v[62:65], v[162:165], v[190:193], v[62:65]
	v_mfma_f32_16x16x32_f16 v[46:49], v[162:165], v[182:185], v[46:49]
	v_mfma_f32_16x16x32_f16 v[46:49], v[158:161], v[178:181], v[46:49]
	v_mfma_f32_16x16x32_f16 v[30:33], v[158:161], v[122:125], v[30:33]
	v_mfma_f32_16x16x32_f16 v[30:33], v[162:165], v[174:177], v[30:33]
	v_mfma_f32_16x16x32_f16 v[14:17], v[162:165], v[118:121], v[14:17]
	v_mfma_f32_16x16x32_f16 v[14:17], v[158:161], v[114:117], v[14:17]
	v_mfma_f32_16x16x32_f16 v[10:13], v[166:169], v[114:117], v[10:13]
	v_mfma_f32_16x16x32_f16 v[10:13], v[170:173], v[118:121], v[10:13]
	v_mfma_f32_16x16x32_f16 v[58:61], v[170:173], v[190:193], v[58:61]
	v_mfma_f32_16x16x32_f16 v[58:61], v[166:169], v[186:189], v[58:61]
	v_mfma_f32_16x16x32_f16 v[42:45], v[166:169], v[178:181], v[42:45]
	v_mfma_f32_16x16x32_f16 v[42:45], v[170:173], v[182:185], v[42:45]
	v_mfma_f32_16x16x32_f16 v[26:29], v[170:173], v[174:177], v[26:29]
	v_mfma_f32_16x16x32_f16 v[26:29], v[166:169], v[122:125], v[26:29]
	v_mfma_f32_16x16x32_f16 v[22:25], v[130:133], v[122:125], v[22:25]
	v_mfma_f32_16x16x32_f16 v[22:25], v[146:149], v[174:177], v[22:25]
	v_mfma_f32_16x16x32_f16 v[54:57], v[146:149], v[190:193], v[54:57]
	v_mfma_f32_16x16x32_f16 v[54:57], v[130:133], v[186:189], v[54:57]
	v_mfma_f32_16x16x32_f16 v[38:41], v[130:133], v[178:181], v[38:41]
	v_mfma_f32_16x16x32_f16 v[38:41], v[146:149], v[182:185], v[38:41]
	v_mfma_f32_16x16x32_f16 v[6:9], v[146:149], v[118:121], v[6:9]
	v_mfma_f32_16x16x32_f16 v[6:9], v[130:133], v[114:117], v[6:9]
	v_mfma_f32_16x16x32_f16 v[2:5], v[150:153], v[114:117], v[2:5]
	v_mfma_f32_16x16x32_f16 v[2:5], v[154:157], v[118:121], v[2:5]
	v_mfma_f32_16x16x32_f16 v[50:53], v[154:157], v[190:193], v[50:53]
	v_mfma_f32_16x16x32_f16 v[50:53], v[150:153], v[186:189], v[50:53]
	v_mfma_f32_16x16x32_f16 v[34:37], v[150:153], v[178:181], v[34:37]
	v_mfma_f32_16x16x32_f16 v[34:37], v[154:157], v[182:185], v[34:37]
	v_mfma_f32_16x16x32_f16 v[18:21], v[154:157], v[174:177], v[18:21]
	v_mfma_f32_16x16x32_f16 v[18:21], v[150:153], v[122:125], v[18:21]
	s_barrier
	s_setprio 0
	s_add_i32 s58, s58, 2
	s_add_u32 s54, s54, 0x100
	s_addc_u32 s55, s55, 0
	s_cmp_gt_u32 s58, 13
	s_cbranch_scc1 .LBB0_1175
.LBB0_1165:
	s_add_u32 s26, s36, s54
	s_addc_u32 s27, s37, s55
	ds_read_b128 v[158:161], v213
	ds_read_b128 v[162:165], v213 offset:1024
	ds_read_b128 v[166:169], v213 offset:2048
	ds_read_b128 v[170:173], v213 offset:3072
	ds_read_b128 v[130:133], v214
	ds_read_b128 v[146:149], v214 offset:1024
	ds_read_b128 v[150:153], v214 offset:2048
	ds_read_b128 v[154:157], v214 offset:3072
	s_add_u32 s24, s26, 0x200
	s_addc_u32 s25, s27, 0
	s_add_u32 s6, s38, s54
	s_addc_u32 s7, s39, s55
	s_add_u32 s59, s6, 0x200
	s_addc_u32 s60, s7, 0
	s_cmp_eq_u32 s58, 12
	s_cselect_b64 s[6:7], -1, 0
	s_and_b64 s[8:9], s[6:7], exec
	s_cselect_b32 s25, s45, s25
	s_cselect_b32 s24, s49, s24
	s_cselect_b32 s9, s47, s60
	s_cselect_b32 s8, s57, s59
	ds_read_b128 v[174:177], v215
	ds_read_b128 v[178:181], v215 offset:1024
	ds_read_b128 v[182:185], v215 offset:2048
	ds_read_b128 v[186:189], v215 offset:3072
	ds_read_b128 v[190:193], v215 offset:4096
	ds_read_b128 v[194:197], v215 offset:5120
	ds_read_b128 v[198:201], v215 offset:6144
	ds_read_b128 v[202:205], v215 offset:7168
	s_add_u32 s26, s26, 0x40180
	s_addc_u32 s27, s27, 0
	s_add_u32 m0, s35, 0xc000
	s_nop 0
	global_load_lds_dwordx4 v1, s[26:27]
	s_nop 0
	s_add_u32 m0, s35, 0xe000
	s_nop 0
	global_load_lds_dwordx4 v211, s[26:27]
	s_waitcnt vmcnt(8)
	s_waitcnt lgkmcnt(0)
	s_barrier
	v_mfma_f32_16x16x32_f16 v[114:117], v[158:161], v[174:177], v[142:145]
	s_setprio 1
	v_mfma_f32_16x16x32_f16 v[114:117], v[162:165], v[178:181], v[114:117]
	v_mfma_f32_16x16x32_f16 v[110:113], v[162:165], v[186:189], v[110:113]
	v_mfma_f32_16x16x32_f16 v[110:113], v[158:161], v[182:185], v[110:113]
	v_mfma_f32_16x16x32_f16 v[94:97], v[158:161], v[190:193], v[94:97]
	v_mfma_f32_16x16x32_f16 v[94:97], v[162:165], v[194:197], v[94:97]
	v_mfma_f32_16x16x32_f16 v[78:81], v[162:165], v[202:205], v[78:81]
	v_mfma_f32_16x16x32_f16 v[78:81], v[158:161], v[198:201], v[78:81]
	v_mfma_f32_16x16x32_f16 v[74:77], v[166:169], v[198:201], v[74:77]
	v_mfma_f32_16x16x32_f16 v[74:77], v[170:173], v[202:205], v[74:77]
	v_mfma_f32_16x16x32_f16 v[118:121], v[170:173], v[178:181], v[138:141]
	v_mfma_f32_16x16x32_f16 v[118:121], v[166:169], v[174:177], v[118:121]
	v_mfma_f32_16x16x32_f16 v[106:109], v[166:169], v[182:185], v[106:109]
	v_mfma_f32_16x16x32_f16 v[106:109], v[170:173], v[186:189], v[106:109]
	v_mfma_f32_16x16x32_f16 v[90:93], v[170:173], v[194:197], v[90:93]
	v_mfma_f32_16x16x32_f16 v[90:93], v[166:169], v[190:193], v[90:93]
	v_mfma_f32_16x16x32_f16 v[86:89], v[130:133], v[190:193], v[86:89]
	v_mfma_f32_16x16x32_f16 v[86:89], v[146:149], v[194:197], v[86:89]
	v_mfma_f32_16x16x32_f16 v[122:125], v[146:149], v[178:181], v[134:137]
	v_mfma_f32_16x16x32_f16 v[122:125], v[130:133], v[174:177], v[122:125]
	v_mfma_f32_16x16x32_f16 v[102:105], v[130:133], v[182:185], v[102:105]
	v_mfma_f32_16x16x32_f16 v[102:105], v[146:149], v[186:189], v[102:105]
	v_mfma_f32_16x16x32_f16 v[70:73], v[146:149], v[202:205], v[70:73]
	v_mfma_f32_16x16x32_f16 v[70:73], v[130:133], v[198:201], v[70:73]
	v_mfma_f32_16x16x32_f16 v[66:69], v[150:153], v[198:201], v[66:69]
	v_mfma_f32_16x16x32_f16 v[66:69], v[154:157], v[202:205], v[66:69]
	v_mfma_f32_16x16x32_f16 v[126:129], v[154:157], v[178:181], v[126:129]
	v_mfma_f32_16x16x32_f16 v[126:129], v[150:153], v[174:177], v[126:129]
	v_mfma_f32_16x16x32_f16 v[98:101], v[150:153], v[182:185], v[98:101]
	v_mfma_f32_16x16x32_f16 v[98:101], v[154:157], v[186:189], v[98:101]
	v_mfma_f32_16x16x32_f16 v[82:85], v[154:157], v[194:197], v[82:85]
	v_mfma_f32_16x16x32_f16 v[82:85], v[150:153], v[190:193], v[82:85]
	s_barrier
	s_setprio 0
	ds_read_b128 v[186:189], v215 offset:16384
	ds_read_b128 v[190:193], v215 offset:17408
	ds_read_b128 v[178:181], v215 offset:18432
	ds_read_b128 v[182:185], v215 offset:19456
	ds_read_b128 v[142:145], v215 offset:20480
	ds_read_b128 v[174:177], v215 offset:21504
	ds_read_b128 v[134:137], v215 offset:22528
	ds_read_b128 v[138:141], v215 offset:23552
	s_and_b64 s[6:7], s[2:3], s[6:7]
	s_mov_b64 s[26:27], -1
	s_and_b64 vcc, exec, s[6:7]
	s_cbranch_vccnz .LBB0_1167
	s_add_u32 m0, s35, 0x10000
	s_nop 0
	global_load_lds_dwordx4 v210, s[8:9]
	s_nop 0
	s_add_u32 m0, s35, 0x12000
	s_nop 0
	global_load_lds_dwordx4 v212, s[8:9]
	s_add_u32 s26, s8, 0x40000
	s_addc_u32 s27, s9, 0
	s_add_u32 m0, s35, 0x14000
	s_nop 0
	global_load_lds_dwordx4 v210, s[26:27]
	s_nop 0
	s_add_u32 m0, s35, 0x16000
	s_nop 0
	global_load_lds_dwordx4 v212, s[26:27]
	s_mov_b64 s[26:27], 0
	s_add_u32 m0, s35, 0
	s_nop 0
	global_load_lds_dwordx4 v1, s[24:25]
	s_nop 0
	s_add_u32 m0, s35, 0x2000
	s_nop 0
	global_load_lds_dwordx4 v211, s[24:25]
	s_waitcnt vmcnt(8)

; #define PG8_STAGE(bufoff, gbase, voff) do { if constexpr (ABL & 1) break; glds16s<(bufoff)>((voff)[0], (const void*)(gbase), ldsbw); glds16s<(bufoff) + 8192>((voff)[1], (const void*)(gbase), ldsbw); } while (0)
; #define PG8_LDA(dst, b, h) do { if constexpr (ABL & 4) break; _Pragma("unroll") for (int m = 0; m < 4; ++m) _Pragma("unroll") for (int k = 0; k < 2; ++k) dst[m][k] = *(const LAS f16x8*)(lds + PG8_SA(b, h) + aoff + m * 2048 + k * 1024); } while (0)
; #define PG8_LDB(dst, b, h) do { if constexpr (ABL & 4) break; _Pragma("unroll") for (int n = 0; n < 2; ++n) _Pragma("unroll") for (int k = 0; k < 2; ++k) dst[n][k] = *(const LAS f16x8*)(lds + PG8_SB(b, h) + boff + n * 2048 + k * 1024); } while (0)
; #define PG8_MMA(ai, bj, At, Bt) do { if constexpr (ABL & 2) break; __builtin_amdgcn_s_setprio(1); _Pragma("unroll") for (int m = 0; m < 4; ++m) _Pragma("unroll") for (int n = 0; n < 2; ++n) _Pragma("unroll") for (int k = 0; k < 2; ++k) \
;         acc[ai][bj][m][n] = __builtin_amdgcn_mfma_f32_16x16x32_f16(Bt[n][k], At[m][k], acc[ai][bj][m][n], 0, 0, 0); __builtin_amdgcn_s_setprio(0); } while (0)
; #define PG8_MMAF(ai, bj, At, Bt) do { if (t == 0) PG8_MMA0(ai, bj, At, Bt); else PG8_MMA(ai, bj, At, Bt); } while (0)
; #define PG8_WAIT_V(n) asm volatile("s_waitcnt vmcnt(" #n ")" ::: "memory")
; #define PG8_WAIT_L(n) asm volatile("s_waitcnt lgkmcnt(" #n ")" ::: "memory")
; #define PG8_BAR __builtin_amdgcn_s_barrier()
; #define PG8_SCHED __builtin_amdgcn_sched_barrier(0)
;     ...
;             if (!fin) PG8_WAIT_V(8); else PG8_WAIT_V(2); PG8_WAIT_L(0); PG8_BAR; PG8_MMAF(1, 0, At, B0); PG8_MMAF(1, 1, At, B1); PG8_BAR; PG8_SCHED;
;             PG8_LDB(B0, 1, 0); PG8_LDB(B1, 1, 1); PG8_SCHED; PG8_LDA(At, 1, 0); if (!fin) PG8_STAGE(PG8_SA(0, 1), a2 + hstep, voffA);
;             if (!fin) PG8_WAIT_V(8); else PG8_WAIT_V(0); PG8_WAIT_L(0); PG8_BAR; PG8_MMA(0, 0, At, B0); PG8_MMA(0, 1, At, B1); PG8_BAR; PG8_SCHED;
.LBB0_1169:
	s_waitcnt lgkmcnt(0)
	s_xor_b64 s[26:27], s[6:7], -1
	s_barrier
	v_mfma_f32_16x16x32_f16 v[62:65], v[158:161], v[186:189], v[62:65]
	s_setprio 1
	v_mfma_f32_16x16x32_f16 v[62:65], v[162:165], v[190:193], v[62:65]
	v_mfma_f32_16x16x32_f16 v[46:49], v[162:165], v[182:185], v[46:49]
	v_mfma_f32_16x16x32_f16 v[46:49], v[158:161], v[178:181], v[46:49]
	v_mfma_f32_16x16x32_f16 v[30:33], v[158:161], v[142:145], v[30:33]
	v_mfma_f32_16x16x32_f16 v[30:33], v[162:165], v[174:177], v[30:33]
	v_mfma_f32_16x16x32_f16 v[14:17], v[162:165], v[138:141], v[14:17]
	v_mfma_f32_16x16x32_f16 v[14:17], v[158:161], v[134:137], v[14:17]
	v_mfma_f32_16x16x32_f16 v[10:13], v[166:169], v[134:137], v[10:13]
	v_mfma_f32_16x16x32_f16 v[10:13], v[170:173], v[138:141], v[10:13]
	v_mfma_f32_16x16x32_f16 v[58:61], v[170:173], v[190:193], v[58:61]
	v_mfma_f32_16x16x32_f16 v[58:61], v[166:169], v[186:189], v[58:61]
	v_mfma_f32_16x16x32_f16 v[42:45], v[166:169], v[178:181], v[42:45]
	v_mfma_f32_16x16x32_f16 v[42:45], v[170:173], v[182:185], v[42:45]
	v_mfma_f32_16x16x32_f16 v[26:29], v[170:173], v[174:177], v[26:29]
	v_mfma_f32_16x16x32_f16 v[26:29], v[166:169], v[142:145], v[26:29]
	v_mfma_f32_16x16x32_f16 v[22:25], v[130:133], v[142:145], v[22:25]
	v_mfma_f32_16x16x32_f16 v[22:25], v[146:149], v[174:177], v[22:25]
	v_mfma_f32_16x16x32_f16 v[54:57], v[146:149], v[190:193], v[54:57]
	v_mfma_f32_16x16x32_f16 v[54:57], v[130:133], v[186:189], v[54:57]
	v_mfma_f32_16x16x32_f16 v[38:41], v[130:133], v[178:181], v[38:41]
	v_mfma_f32_16x16x32_f16 v[38:41], v[146:149], v[182:185], v[38:41]
	v_mfma_f32_16x16x32_f16 v[6:9], v[146:149], v[138:141], v[6:9]
	v_mfma_f32_16x16x32_f16 v[6:9], v[130:133], v[134:137], v[6:9]
	v_mfma_f32_16x16x32_f16 v[2:5], v[150:153], v[134:137], v[2:5]
	v_mfma_f32_16x16x32_f16 v[2:5], v[154:157], v[138:141], v[2:5]
	v_mfma_f32_16x16x32_f16 v[50:53], v[154:157], v[190:193], v[50:53]
	v_mfma_f32_16x16x32_f16 v[50:53], v[150:153], v[186:189], v[50:53]
	v_mfma_f32_16x16x32_f16 v[34:37], v[150:153], v[178:181], v[34:37]
	v_mfma_f32_16x16x32_f16 v[34:37], v[154:157], v[182:185], v[34:37]
	v_mfma_f32_16x16x32_f16 v[18:21], v[154:157], v[174:177], v[18:21]
	v_mfma_f32_16x16x32_f16 v[18:21], v[150:153], v[142:145], v[18:21]
	s_barrier
	s_setprio 0
	ds_read_b128 v[158:161], v216
	ds_read_b128 v[162:165], v216 offset:1024
	ds_read_b128 v[166:169], v216 offset:2048
	ds_read_b128 v[170:173], v216 offset:3072
	ds_read_b128 v[130:133], v217
	ds_read_b128 v[146:149], v217 offset:1024
	ds_read_b128 v[150:153], v217 offset:2048
	ds_read_b128 v[154:157], v217 offset:3072
	ds_read_b128 v[198:201], v215 offset:32768
	ds_read_b128 v[202:205], v215 offset:33792
	ds_read_b128 v[190:193], v215 offset:34816
	ds_read_b128 v[194:197], v215 offset:35840
	ds_read_b128 v[182:185], v215 offset:36864
	ds_read_b128 v[186:189], v215 offset:37888
	ds_read_b128 v[174:177], v215 offset:38912
	ds_read_b128 v[178:181], v215 offset:39936
	v_cndmask_b32_e64 v134, 0, 1, s[26:27]
	v_cmp_ne_u32_e64 s[6:7], 1, v134
	s_andn2_b64 vcc, exec, s[26:27]
	s_mov_b64 s[26:27], -1
	s_cbranch_vccnz .LBB0_1171
	s_add_u32 s26, s24, 0x40000
	s_addc_u32 s27, s25, 0
	s_add_u32 m0, s35, 0x4000
	s_nop 0
	global_load_lds_dwordx4 v1, s[26:27]
	s_nop 0
	s_add_u32 m0, s35, 0x6000
	s_nop 0
	global_load_lds_dwordx4 v211, s[26:27]
	s_waitcnt vmcnt(8)
	s_mov_b64 s[26:27], 0
